# snake variant B: same accumulate chains, snake walks the accumulator grid B-operand-major (12 srcB shares + 3 srcA shares per block instead of 12 srcA + 3 srcB)
# baseline (speedup 1.0000x reference)
; #define PG8_STAGE(bufoff, gbase, voff) do { _Pragma("unroll") for (int _i = 0; _i < 2; ++_i) \
;         __builtin_amdgcn_global_load_lds((const unsigned*)((const char*)(gbase) + (voff)[_i]), (PG8_LAS unsigned*)(lds + (bufoff) + ldsw + _i * 8192), 16, 0, 0); } while (0)
; #define PG8_LDA(dst, b, h) do { _Pragma("unroll") for (int m = 0; m < 4; ++m) _Pragma("unroll") for (int k = 0; k < 2; ++k) dst[m][k] = *(const PG8_LAS bf16x8*)(lds + PG8_SA(b, h) + aoff + m * 2048 + k * 1024); } while (0)
; #define PG8_LDB(dst, b, h) do { _Pragma("unroll") for (int n = 0; n < 2; ++n) _Pragma("unroll") for (int k = 0; k < 2; ++k) dst[n][k] = *(const PG8_LAS bf16x8*)(lds + PG8_SB(b, h) + boff + n * 2048 + k * 1024); } while (0)
; #define PG8_MMA(ai, bj, At, Bt) do { __builtin_amdgcn_s_setprio(1); _Pragma("unroll") for (int m = 0; m < 4; ++m) _Pragma("unroll") for (int n = 0; n < 2; ++n) _Pragma("unroll") for (int k = 0; k < 2; ++k) \
;         acc[ai][bj][m][n] = __builtin_amdgcn_mfma_f32_16x16x32_bf16(Bt[n][k], At[m][k], acc[ai][bj][m][n], 0, 0, 0); __builtin_amdgcn_s_setprio(0); } while (0)
; #define PG8_WAIT_V(n) asm volatile("s_waitcnt vmcnt(" #n ")" ::: "memory")
; #define PG8_BAR __builtin_amdgcn_s_barrier()
; template <class Epi, class Sched, bool ALIGN_EPI = false, bool SP2 = false>
; __device__ __forceinline__ void gemm_phase(PG8_LAS unsigned char* lds, const Gemm g, const Sched& S, const Epi& E) {
;     ...
;         for (int t = 0; t < nt; t += 2) {
;             const bool last = (t == nt - 2);
;             const char* a1 = cA + (size_t)(t + 1) * kstep;
;             const char* a2 = last ? nA : cA + (size_t)(t + 2) * kstep; const char* b2 = last ? nB : cB + (size_t)(t + 2) * kstep;
;             const char* a3 = a2 + kstep; const char* b3 = b2 + kstep;
;             if (last && has_next) S.a_ready(nxt);
;             if constexpr (SP2) {
;             PG8_LDB(B0, 0, 0); PG8_LDB(B1, 0, 1); PG8_SCHED; PG8_LDA(At, 0, 0); PG8_STAGE(PG8_SA(1, 1), a1 + hstep, voffA);
;             PG8_WAIT_V(8); PG8_WAIT_L(0); PG8_BAR; PG8_MMA(0, 0, At, B0); PG8_MMA(0, 1, At, B1); PG8_BAR; PG8_SCHED;
;             PG8_LDA(At, 0, 1); PG8_STAGE(PG8_SB(0, 0), b2, voffB); PG8_STAGE(PG8_SB(0, 1), b2 + hstep, voffB); PG8_STAGE(PG8_SA(0, 0), a2, voffA);
;             PG8_WAIT_V(8); PG8_WAIT_L(0); PG8_BAR; PG8_MMA(1, 0, At, B0); PG8_MMA(1, 1, At, B1); PG8_BAR; PG8_SCHED;
.LBB0_673:
	ds_read_b128 v[148:151], v241 offset:0
	ds_read_b128 v[156:159], v241 offset:1024
	ds_read_b128 v[166:169], v241 offset:2048
	ds_read_b128 v[170:173], v241 offset:3072
	ds_read_b128 v[174:177], v241 offset:16384
	ds_read_b128 v[178:181], v241 offset:17408
	ds_read_b128 v[182:185], v241 offset:18432
	ds_read_b128 v[186:189], v241 offset:19456
	s_add_u32 s20, s22, 0xfff00080
	s_addc_u32 s21, s23, -1
	s_cmp_eq_u32 s35, 60
	s_cselect_b32 s25, s11, s21
	s_cselect_b32 s24, s52, s20
	s_cselect_b32 s21, s13, s34
	s_cselect_b32 s20, s53, s62
	s_add_i32 m0, s19, 0xc000
	ds_read_b128 v[190:193], v161
	ds_read_b128 v[194:197], v161 offset:1024
	ds_read_b128 v[198:201], v161 offset:2048
	ds_read_b128 v[202:205], v161 offset:3072
	ds_read_b128 v[206:209], v161 offset:4096
	ds_read_b128 v[210:213], v161 offset:5120
	ds_read_b128 v[214:217], v161 offset:6144
	ds_read_b128 v[218:221], v161 offset:7168
	global_load_lds_dwordx4 v138, s[22:23]
	s_add_i32 m0, s19, 0xe000
	s_nop 0
	global_load_lds_dwordx4 v140, s[22:23]
	s_waitcnt vmcnt(8)
	s_waitcnt lgkmcnt(0)
	s_barrier
	s_waitcnt lgkmcnt(0)
	v_mfma_f32_16x16x32_bf16 v[118:121], v[148:151], v[190:193], v[118:121]
	v_mfma_f32_16x16x32_bf16 v[118:121], v[156:159], v[194:197], v[118:121]
	v_mfma_f32_16x16x32_bf16 v[114:117], v[170:173], v[194:197], v[114:117]
	v_mfma_f32_16x16x32_bf16 v[114:117], v[166:169], v[190:193], v[114:117]
	v_mfma_f32_16x16x32_bf16 v[126:129], v[174:177], v[190:193], v[126:129]
	v_mfma_f32_16x16x32_bf16 v[126:129], v[178:181], v[194:197], v[126:129]
	v_mfma_f32_16x16x32_bf16 v[122:125], v[186:189], v[194:197], v[122:125]
	v_mfma_f32_16x16x32_bf16 v[122:125], v[182:185], v[190:193], v[122:125]
	v_mfma_f32_16x16x32_bf16 v[106:109], v[182:185], v[198:201], v[106:109]
	v_mfma_f32_16x16x32_bf16 v[106:109], v[186:189], v[202:205], v[106:109]
	v_mfma_f32_16x16x32_bf16 v[110:113], v[178:181], v[202:205], v[110:113]
	v_mfma_f32_16x16x32_bf16 v[110:113], v[174:177], v[198:201], v[110:113]
	v_mfma_f32_16x16x32_bf16 v[98:101], v[166:169], v[198:201], v[98:101]
	v_mfma_f32_16x16x32_bf16 v[98:101], v[170:173], v[202:205], v[98:101]
	v_mfma_f32_16x16x32_bf16 v[102:105], v[156:159], v[202:205], v[102:105]
	v_mfma_f32_16x16x32_bf16 v[102:105], v[148:151], v[198:201], v[102:105]
	v_mfma_f32_16x16x32_bf16 v[86:89], v[148:151], v[206:209], v[86:89]
	v_mfma_f32_16x16x32_bf16 v[86:89], v[156:159], v[210:213], v[86:89]
	v_mfma_f32_16x16x32_bf16 v[82:85], v[170:173], v[210:213], v[82:85]
	v_mfma_f32_16x16x32_bf16 v[82:85], v[166:169], v[206:209], v[82:85]
	v_mfma_f32_16x16x32_bf16 v[94:97], v[174:177], v[206:209], v[94:97]
	v_mfma_f32_16x16x32_bf16 v[94:97], v[178:181], v[210:213], v[94:97]
	v_mfma_f32_16x16x32_bf16 v[90:93], v[186:189], v[210:213], v[90:93]
	v_mfma_f32_16x16x32_bf16 v[90:93], v[182:185], v[206:209], v[90:93]
	v_mfma_f32_16x16x32_bf16 v[74:77], v[182:185], v[214:217], v[74:77]
	v_mfma_f32_16x16x32_bf16 v[74:77], v[186:189], v[218:221], v[74:77]
	v_mfma_f32_16x16x32_bf16 v[78:81], v[178:181], v[218:221], v[78:81]
	v_mfma_f32_16x16x32_bf16 v[78:81], v[174:177], v[214:217], v[78:81]
	v_mfma_f32_16x16x32_bf16 v[66:69], v[166:169], v[214:217], v[66:69]
	v_mfma_f32_16x16x32_bf16 v[66:69], v[170:173], v[218:221], v[66:69]
	v_mfma_f32_16x16x32_bf16 v[70:73], v[156:159], v[218:221], v[70:73]
	v_mfma_f32_16x16x32_bf16 v[70:73], v[148:151], v[214:217], v[70:73]
	s_barrier
	s_add_i32 s63, s43, s26
	s_mov_b32 m0, s63
	ds_read_b128 v[190:193], v161 offset:16384
	ds_read_b128 v[194:197], v161 offset:17408
	ds_read_b128 v[198:201], v161 offset:18432
	ds_read_b128 v[202:205], v161 offset:19456
	ds_read_b128 v[206:209], v161 offset:20480
	ds_read_b128 v[210:213], v161 offset:21504
	ds_read_b128 v[214:217], v161 offset:22528
	ds_read_b128 v[218:221], v161 offset:23552
	global_load_lds_dwordx4 v132, s[20:21]
	s_add_i32 m0, s63, 0x2000
	s_add_u32 s64, s20, 0x100000
	s_addc_u32 s65, s21, 0
	s_add_i32 s63, s46, s26
	global_load_lds_dwordx4 v136, s[20:21]
	s_mov_b32 m0, s63
	s_add_u32 s100, s24, 0x80
	s_addc_u32 s101, s25, 0
	global_load_lds_dwordx4 v132, s[64:65]
	s_add_i32 m0, s63, 0x2000
	s_nop 0
	global_load_lds_dwordx4 v136, s[64:65]
	s_mov_b32 m0, s19
	s_nop 0
	global_load_lds_dwordx4 v130, s[24:25]
	s_mov_b32 m0, s29
	s_nop 0
	global_load_lds_dwordx4 v134, s[24:25]
	s_waitcnt vmcnt(8)
	s_waitcnt lgkmcnt(0)
	s_barrier
	s_waitcnt lgkmcnt(0)
	v_mfma_f32_16x16x32_bf16 v[54:57], v[148:151], v[190:193], v[54:57]
	v_mfma_f32_16x16x32_bf16 v[54:57], v[156:159], v[194:197], v[54:57]
	v_mfma_f32_16x16x32_bf16 v[50:53], v[170:173], v[194:197], v[50:53]
	v_mfma_f32_16x16x32_bf16 v[50:53], v[166:169], v[190:193], v[50:53]
	v_mfma_f32_16x16x32_bf16 v[62:65], v[174:177], v[190:193], v[62:65]
	v_mfma_f32_16x16x32_bf16 v[62:65], v[178:181], v[194:197], v[62:65]
	v_mfma_f32_16x16x32_bf16 v[58:61], v[186:189], v[194:197], v[58:61]
	v_mfma_f32_16x16x32_bf16 v[58:61], v[182:185], v[190:193], v[58:61]
	v_mfma_f32_16x16x32_bf16 v[42:45], v[182:185], v[198:201], v[42:45]
	v_mfma_f32_16x16x32_bf16 v[42:45], v[186:189], v[202:205], v[42:45]
	v_mfma_f32_16x16x32_bf16 v[46:49], v[178:181], v[202:205], v[46:49]
	v_mfma_f32_16x16x32_bf16 v[46:49], v[174:177], v[198:201], v[46:49]
	v_mfma_f32_16x16x32_bf16 v[34:37], v[166:169], v[198:201], v[34:37]
	v_mfma_f32_16x16x32_bf16 v[34:37], v[170:173], v[202:205], v[34:37]
	v_mfma_f32_16x16x32_bf16 v[38:41], v[156:159], v[202:205], v[38:41]
	v_mfma_f32_16x16x32_bf16 v[38:41], v[148:151], v[198:201], v[38:41]
	v_mfma_f32_16x16x32_bf16 v[22:25], v[148:151], v[206:209], v[22:25]
	v_mfma_f32_16x16x32_bf16 v[22:25], v[156:159], v[210:213], v[22:25]
	v_mfma_f32_16x16x32_bf16 v[18:21], v[170:173], v[210:213], v[18:21]
	v_mfma_f32_16x16x32_bf16 v[18:21], v[166:169], v[206:209], v[18:21]
	v_mfma_f32_16x16x32_bf16 v[30:33], v[174:177], v[206:209], v[30:33]
	v_mfma_f32_16x16x32_bf16 v[30:33], v[178:181], v[210:213], v[30:33]
	v_mfma_f32_16x16x32_bf16 v[26:29], v[186:189], v[210:213], v[26:29]
	v_mfma_f32_16x16x32_bf16 v[26:29], v[182:185], v[206:209], v[26:29]
	v_mfma_f32_16x16x32_bf16 v[14:17], v[182:185], v[214:217], v[14:17]
	v_mfma_f32_16x16x32_bf16 v[14:17], v[186:189], v[218:221], v[14:17]
	v_mfma_f32_16x16x32_bf16 v[10:13], v[178:181], v[218:221], v[10:13]
	v_mfma_f32_16x16x32_bf16 v[10:13], v[174:177], v[214:217], v[10:13]
	v_mfma_f32_16x16x32_bf16 v[2:5], v[166:169], v[214:217], v[2:5]
	v_mfma_f32_16x16x32_bf16 v[2:5], v[170:173], v[218:221], v[2:5]
	v_mfma_f32_16x16x32_bf16 v[6:9], v[156:159], v[218:221], v[6:9]
	v_mfma_f32_16x16x32_bf16 v[6:9], v[148:151], v[214:217], v[6:9]
	s_barrier
; #define PG8_STAGE(bufoff, gbase, voff) do { _Pragma("unroll") for (int _i = 0; _i < 2; ++_i) \
;         __builtin_amdgcn_global_load_lds((const unsigned*)((const char*)(gbase) + (voff)[_i]), (PG8_LAS unsigned*)(lds + (bufoff) + ldsw + _i * 8192), 16, 0, 0); } while (0)
; #define PG8_LDA(dst, b, h) do { _Pragma("unroll") for (int m = 0; m < 4; ++m) _Pragma("unroll") for (int k = 0; k < 2; ++k) dst[m][k] = *(const PG8_LAS bf16x8*)(lds + PG8_SA(b, h) + aoff + m * 2048 + k * 1024); } while (0)
; #define PG8_LDB(dst, b, h) do { _Pragma("unroll") for (int n = 0; n < 2; ++n) _Pragma("unroll") for (int k = 0; k < 2; ++k) dst[n][k] = *(const PG8_LAS bf16x8*)(lds + PG8_SB(b, h) + boff + n * 2048 + k * 1024); } while (0)
; #define PG8_MMA(ai, bj, At, Bt) do { __builtin_amdgcn_s_setprio(1); _Pragma("unroll") for (int m = 0; m < 4; ++m) _Pragma("unroll") for (int n = 0; n < 2; ++n) _Pragma("unroll") for (int k = 0; k < 2; ++k) \
;         acc[ai][bj][m][n] = __builtin_amdgcn_mfma_f32_16x16x32_bf16(Bt[n][k], At[m][k], acc[ai][bj][m][n], 0, 0, 0); __builtin_amdgcn_s_setprio(0); } while (0)
; #define PG8_WAIT_V(n) asm volatile("s_waitcnt vmcnt(" #n ")" ::: "memory")
; #define PG8_WAIT_L(n) asm volatile("s_waitcnt lgkmcnt(" #n ")" ::: "memory")
; #define PG8_BAR __builtin_amdgcn_s_barrier()
; #define PG8_SCHED __builtin_amdgcn_sched_barrier(0)
; template <class Epi, class Sched, bool ALIGN_EPI = false, bool SP2 = false>
; __device__ __forceinline__ void gemm_phase(PG8_LAS unsigned char* lds, const Gemm g, const Sched& S, const Epi& E) {
;     ...
;         for (int t = 0; t < nt; t += 2) {
;             const bool last = (t == nt - 2);
;             const char* a1 = cA + (size_t)(t + 1) * kstep;
;             const char* a2 = last ? nA : cA + (size_t)(t + 2) * kstep; const char* b2 = last ? nB : cB + (size_t)(t + 2) * kstep;
;     ...
;             PG8_LDB(B0, 1, 0); PG8_LDB(B1, 1, 1); PG8_SCHED; PG8_LDA(At, 1, 0); PG8_STAGE(PG8_SA(0, 1), a2 + hstep, voffA);
;             PG8_WAIT_V(8); PG8_WAIT_L(0); PG8_BAR; PG8_MMA(0, 0, At, B0); PG8_MMA(0, 1, At, B1); PG8_BAR; PG8_SCHED;
;             PG8_LDA(At, 1, 1); PG8_STAGE(PG8_SB(1, 0), b3, voffB); PG8_STAGE(PG8_SB(1, 1), b3 + hstep, voffB); PG8_STAGE(PG8_SA(1, 0), a3, voffA);
;             PG8_WAIT_V(8); PG8_WAIT_L(0); PG8_BAR; PG8_MMA(1, 0, At, B0); PG8_MMA(1, 1, At, B1); PG8_BAR; PG8_SCHED;
	s_add_i32 s63, 0, 0x18000
	s_add_i32 s64, 0, 0x1c000
	ds_read_b128 v[148:151], v241 offset:32768
	ds_read_b128 v[156:159], v241 offset:33792
	ds_read_b128 v[166:169], v241 offset:34816
	ds_read_b128 v[170:173], v241 offset:35840
	ds_read_b128 v[174:177], v241 offset:49152
	ds_read_b128 v[178:181], v241 offset:50176
	ds_read_b128 v[182:185], v241 offset:51200
	ds_read_b128 v[186:189], v241 offset:52224
	s_add_u32 s24, s24, 0x100000
	s_addc_u32 s25, s25, 0
	s_mov_b32 m0, s30
	ds_read_b128 v[190:193], v161 offset:32768
	ds_read_b128 v[194:197], v161 offset:33792
	ds_read_b128 v[198:201], v161 offset:34816
	ds_read_b128 v[202:205], v161 offset:35840
	ds_read_b128 v[206:209], v161 offset:36864
	ds_read_b128 v[210:213], v161 offset:37888
	ds_read_b128 v[214:217], v161 offset:38912
	ds_read_b128 v[218:221], v161 offset:39936
	global_load_lds_dwordx4 v130, s[24:25]
	s_mov_b32 m0, s31
	s_nop 0
	global_load_lds_dwordx4 v134, s[24:25]
	s_waitcnt vmcnt(8)
	s_waitcnt lgkmcnt(0)
	s_barrier
	s_waitcnt lgkmcnt(0)
	v_mfma_f32_16x16x32_bf16 v[118:121], v[148:151], v[190:193], v[118:121]
	v_mfma_f32_16x16x32_bf16 v[118:121], v[156:159], v[194:197], v[118:121]
	v_mfma_f32_16x16x32_bf16 v[114:117], v[170:173], v[194:197], v[114:117]
	v_mfma_f32_16x16x32_bf16 v[114:117], v[166:169], v[190:193], v[114:117]
	v_mfma_f32_16x16x32_bf16 v[126:129], v[174:177], v[190:193], v[126:129]
	v_mfma_f32_16x16x32_bf16 v[126:129], v[178:181], v[194:197], v[126:129]
	v_mfma_f32_16x16x32_bf16 v[122:125], v[186:189], v[194:197], v[122:125]
	v_mfma_f32_16x16x32_bf16 v[122:125], v[182:185], v[190:193], v[122:125]
	v_mfma_f32_16x16x32_bf16 v[106:109], v[182:185], v[198:201], v[106:109]
	v_mfma_f32_16x16x32_bf16 v[106:109], v[186:189], v[202:205], v[106:109]
	v_mfma_f32_16x16x32_bf16 v[110:113], v[178:181], v[202:205], v[110:113]
	v_mfma_f32_16x16x32_bf16 v[110:113], v[174:177], v[198:201], v[110:113]
	v_mfma_f32_16x16x32_bf16 v[98:101], v[166:169], v[198:201], v[98:101]
	v_mfma_f32_16x16x32_bf16 v[98:101], v[170:173], v[202:205], v[98:101]
	v_mfma_f32_16x16x32_bf16 v[102:105], v[156:159], v[202:205], v[102:105]
	v_mfma_f32_16x16x32_bf16 v[102:105], v[148:151], v[198:201], v[102:105]
	v_mfma_f32_16x16x32_bf16 v[86:89], v[148:151], v[206:209], v[86:89]
	v_mfma_f32_16x16x32_bf16 v[86:89], v[156:159], v[210:213], v[86:89]
	v_mfma_f32_16x16x32_bf16 v[82:85], v[170:173], v[210:213], v[82:85]
	v_mfma_f32_16x16x32_bf16 v[82:85], v[166:169], v[206:209], v[82:85]
	v_mfma_f32_16x16x32_bf16 v[94:97], v[174:177], v[206:209], v[94:97]
	v_mfma_f32_16x16x32_bf16 v[94:97], v[178:181], v[210:213], v[94:97]
	v_mfma_f32_16x16x32_bf16 v[90:93], v[186:189], v[210:213], v[90:93]
	v_mfma_f32_16x16x32_bf16 v[90:93], v[182:185], v[206:209], v[90:93]
	v_mfma_f32_16x16x32_bf16 v[74:77], v[182:185], v[214:217], v[74:77]
	v_mfma_f32_16x16x32_bf16 v[74:77], v[186:189], v[218:221], v[74:77]
	v_mfma_f32_16x16x32_bf16 v[78:81], v[178:181], v[218:221], v[78:81]
	v_mfma_f32_16x16x32_bf16 v[78:81], v[174:177], v[214:217], v[78:81]
	v_mfma_f32_16x16x32_bf16 v[66:69], v[166:169], v[214:217], v[66:69]
	v_mfma_f32_16x16x32_bf16 v[66:69], v[170:173], v[218:221], v[66:69]
	v_mfma_f32_16x16x32_bf16 v[70:73], v[156:159], v[218:221], v[70:73]
	v_mfma_f32_16x16x32_bf16 v[70:73], v[148:151], v[214:217], v[70:73]
	s_barrier
	s_add_i32 s24, s63, s26
	s_add_i32 m0, s24, 0xffffff80
	ds_read_b128 v[190:193], v161 offset:49152
	ds_read_b128 v[194:197], v161 offset:50176
	ds_read_b128 v[198:201], v161 offset:51200
	ds_read_b128 v[202:205], v161 offset:52224
	ds_read_b128 v[206:209], v161 offset:53248
	ds_read_b128 v[210:213], v161 offset:54272
	ds_read_b128 v[214:217], v161 offset:55296
	ds_read_b128 v[218:221], v161 offset:56320
	global_load_lds_dwordx4 v132, s[20:21] offset:128
	s_add_i32 m0, s24, 0x1f80
	s_add_i32 s24, s64, s26
	global_load_lds_dwordx4 v136, s[20:21] offset:128
	s_add_u32 s20, s20, 0x100080
	s_addc_u32 s21, s21, 0
	s_mov_b32 m0, s24
	s_nop 0
	global_load_lds_dwordx4 v132, s[20:21]
	s_add_i32 m0, s24, 0x2000
	s_nop 0
	global_load_lds_dwordx4 v136, s[20:21]
	s_mov_b32 m0, s40
	s_nop 0
	global_load_lds_dwordx4 v130, s[100:101]
	s_mov_b32 m0, s41
	s_nop 0
	global_load_lds_dwordx4 v134, s[100:101]
	s_waitcnt vmcnt(8)
	s_waitcnt lgkmcnt(0)
	s_barrier
	s_waitcnt lgkmcnt(0)
	v_mfma_f32_16x16x32_bf16 v[54:57], v[148:151], v[190:193], v[54:57]
	v_mfma_f32_16x16x32_bf16 v[54:57], v[156:159], v[194:197], v[54:57]
	v_mfma_f32_16x16x32_bf16 v[50:53], v[170:173], v[194:197], v[50:53]
	v_mfma_f32_16x16x32_bf16 v[50:53], v[166:169], v[190:193], v[50:53]
	v_mfma_f32_16x16x32_bf16 v[62:65], v[174:177], v[190:193], v[62:65]
	v_mfma_f32_16x16x32_bf16 v[62:65], v[178:181], v[194:197], v[62:65]
	v_mfma_f32_16x16x32_bf16 v[58:61], v[186:189], v[194:197], v[58:61]
	v_mfma_f32_16x16x32_bf16 v[58:61], v[182:185], v[190:193], v[58:61]
	v_mfma_f32_16x16x32_bf16 v[42:45], v[182:185], v[198:201], v[42:45]
	v_mfma_f32_16x16x32_bf16 v[42:45], v[186:189], v[202:205], v[42:45]
	v_mfma_f32_16x16x32_bf16 v[46:49], v[178:181], v[202:205], v[46:49]
	v_mfma_f32_16x16x32_bf16 v[46:49], v[174:177], v[198:201], v[46:49]
	v_mfma_f32_16x16x32_bf16 v[34:37], v[166:169], v[198:201], v[34:37]
	v_mfma_f32_16x16x32_bf16 v[34:37], v[170:173], v[202:205], v[34:37]
	v_mfma_f32_16x16x32_bf16 v[38:41], v[156:159], v[202:205], v[38:41]
	v_mfma_f32_16x16x32_bf16 v[38:41], v[148:151], v[198:201], v[38:41]
	v_mfma_f32_16x16x32_bf16 v[22:25], v[148:151], v[206:209], v[22:25]
	v_mfma_f32_16x16x32_bf16 v[22:25], v[156:159], v[210:213], v[22:25]
	v_mfma_f32_16x16x32_bf16 v[18:21], v[170:173], v[210:213], v[18:21]
	v_mfma_f32_16x16x32_bf16 v[18:21], v[166:169], v[206:209], v[18:21]
	v_mfma_f32_16x16x32_bf16 v[30:33], v[174:177], v[206:209], v[30:33]
	v_mfma_f32_16x16x32_bf16 v[30:33], v[178:181], v[210:213], v[30:33]
	v_mfma_f32_16x16x32_bf16 v[26:29], v[186:189], v[210:213], v[26:29]
	v_mfma_f32_16x16x32_bf16 v[26:29], v[182:185], v[206:209], v[26:29]
	v_mfma_f32_16x16x32_bf16 v[14:17], v[182:185], v[214:217], v[14:17]
	v_mfma_f32_16x16x32_bf16 v[14:17], v[186:189], v[218:221], v[14:17]
	v_mfma_f32_16x16x32_bf16 v[10:13], v[178:181], v[218:221], v[10:13]
	v_mfma_f32_16x16x32_bf16 v[10:13], v[174:177], v[214:217], v[10:13]
	v_mfma_f32_16x16x32_bf16 v[2:5], v[166:169], v[214:217], v[2:5]
	v_mfma_f32_16x16x32_bf16 v[2:5], v[170:173], v[218:221], v[2:5]
	v_mfma_f32_16x16x32_bf16 v[6:9], v[156:159], v[218:221], v[6:9]
	v_mfma_f32_16x16x32_bf16 v[6:9], v[148:151], v[214:217], v[6:9]
	s_barrier
	s_add_i32 s35, s35, 2
	s_add_u32 s22, s22, 0x100
	s_addc_u32 s23, s23, 0
	s_add_u32 s62, s62, 0x100
	s_addc_u32 s34, s34, 0
	s_cmp_gt_u32 s35, 61
	s_cbranch_scc0 .LBB0_673
	s_and_b64 vcc, exec, s[8:9]
	s_cbranch_vccz .LBB0_676
	s_barrier

; #define PG8_STAGE(bufoff, gbase, voff) do { _Pragma("unroll") for (int _i = 0; _i < 2; ++_i) \
;         __builtin_amdgcn_global_load_lds((const unsigned*)((const char*)(gbase) + (voff)[_i]), (PG8_LAS unsigned*)(lds + (bufoff) + ldsw + _i * 8192), 16, 0, 0); } while (0)
; #define PG8_LDA(dst, b, h) do { _Pragma("unroll") for (int m = 0; m < 4; ++m) _Pragma("unroll") for (int k = 0; k < 2; ++k) dst[m][k] = *(const PG8_LAS bf16x8*)(lds + PG8_SA(b, h) + aoff + m * 2048 + k * 1024); } while (0)
; #define PG8_LDB(dst, b, h) do { _Pragma("unroll") for (int n = 0; n < 2; ++n) _Pragma("unroll") for (int k = 0; k < 2; ++k) dst[n][k] = *(const PG8_LAS bf16x8*)(lds + PG8_SB(b, h) + boff + n * 2048 + k * 1024); } while (0)
; #define PG8_MMA(ai, bj, At, Bt) do { __builtin_amdgcn_s_setprio(1); _Pragma("unroll") for (int m = 0; m < 4; ++m) _Pragma("unroll") for (int n = 0; n < 2; ++n) _Pragma("unroll") for (int k = 0; k < 2; ++k) \
;         acc[ai][bj][m][n] = __builtin_amdgcn_mfma_f32_16x16x32_bf16(Bt[n][k], At[m][k], acc[ai][bj][m][n], 0, 0, 0); __builtin_amdgcn_s_setprio(0); } while (0)
; #define PG8_WAIT_V(n) asm volatile("s_waitcnt vmcnt(" #n ")" ::: "memory")
; #define PG8_BAR __builtin_amdgcn_s_barrier()
; template <class Epi, class Sched, bool ALIGN_EPI = false, bool SP2 = false>
; __device__ __forceinline__ void gemm_phase(PG8_LAS unsigned char* lds, const Gemm g, const Sched& S, const Epi& E) {
;     ...
;         for (int t = 0; t < nt; t += 2) {
;             const bool last = (t == nt - 2);
;             const char* a1 = cA + (size_t)(t + 1) * kstep;
;             const char* a2 = last ? nA : cA + (size_t)(t + 2) * kstep; const char* b2 = last ? nB : cB + (size_t)(t + 2) * kstep;
;             const char* a3 = a2 + kstep; const char* b3 = b2 + kstep;
;             if (last && has_next) S.a_ready(nxt);
;             if constexpr (SP2) {
;             PG8_LDB(B0, 0, 0); PG8_LDB(B1, 0, 1); PG8_SCHED; PG8_LDA(At, 0, 0); PG8_STAGE(PG8_SA(1, 1), a1 + hstep, voffA);
;             PG8_WAIT_V(8); PG8_WAIT_L(0); PG8_BAR; PG8_MMA(0, 0, At, B0); PG8_MMA(0, 1, At, B1); PG8_BAR; PG8_SCHED;
;             PG8_LDA(At, 0, 1); PG8_STAGE(PG8_SB(0, 0), b2, voffB); PG8_STAGE(PG8_SB(0, 1), b2 + hstep, voffB); PG8_STAGE(PG8_SA(0, 0), a2, voffA);
;             PG8_WAIT_V(8); PG8_WAIT_L(0); PG8_BAR; PG8_MMA(1, 0, At, B0); PG8_MMA(1, 1, At, B1); PG8_BAR; PG8_SCHED;
.LBB0_1039:
	ds_read_b128 v[130:133], v241 offset:0
	ds_read_b128 v[134:137], v241 offset:1024
	ds_read_b128 v[138:141], v241 offset:2048
	ds_read_b128 v[142:145], v241 offset:3072
	ds_read_b128 v[146:149], v241 offset:16384
	ds_read_b128 v[150:153], v241 offset:17408
	ds_read_b128 v[172:175], v241 offset:18432
	ds_read_b128 v[176:179], v241 offset:19456
	s_add_u32 s24, s26, 0xfff00080
	s_addc_u32 s25, s27, -1
	s_cmp_eq_u32 s68, 60
	s_cselect_b32 s29, s15, s25
	s_cselect_b32 s28, s21, s24
	s_cselect_b32 s25, s13, s67
	s_cselect_b32 s24, s65, s66
	s_add_i32 m0, s23, 0xc000
	ds_read_b128 v[180:183], v185
	ds_read_b128 v[188:191], v185 offset:1024
	ds_read_b128 v[192:195], v185 offset:2048
	ds_read_b128 v[196:199], v185 offset:3072
	ds_read_b128 v[200:203], v185 offset:4096
	ds_read_b128 v[204:207], v185 offset:5120
	ds_read_b128 v[208:211], v185 offset:6144
	ds_read_b128 v[212:215], v185 offset:7168
	global_load_lds_dwordx4 v162, s[26:27]
	s_add_i32 m0, s23, 0xe000
	s_nop 0
	global_load_lds_dwordx4 v166, s[26:27]
	s_waitcnt vmcnt(8)
	s_waitcnt lgkmcnt(0)
	s_barrier
	s_waitcnt lgkmcnt(0)
	v_mfma_f32_16x16x32_bf16 v[114:117], v[130:133], v[180:183], v[114:117]
	v_mfma_f32_16x16x32_bf16 v[114:117], v[134:137], v[188:191], v[114:117]
	v_mfma_f32_16x16x32_bf16 v[118:121], v[142:145], v[188:191], v[118:121]
	v_mfma_f32_16x16x32_bf16 v[118:121], v[138:141], v[180:183], v[118:121]
	v_mfma_f32_16x16x32_bf16 v[122:125], v[146:149], v[180:183], v[122:125]
	v_mfma_f32_16x16x32_bf16 v[122:125], v[150:153], v[188:191], v[122:125]
	v_mfma_f32_16x16x32_bf16 v[126:129], v[176:179], v[188:191], v[126:129]
	v_mfma_f32_16x16x32_bf16 v[126:129], v[172:175], v[180:183], v[126:129]
	v_mfma_f32_16x16x32_bf16 v[102:105], v[172:175], v[192:195], v[102:105]
	v_mfma_f32_16x16x32_bf16 v[102:105], v[176:179], v[196:199], v[102:105]
	v_mfma_f32_16x16x32_bf16 v[110:113], v[150:153], v[196:199], v[110:113]
	v_mfma_f32_16x16x32_bf16 v[110:113], v[146:149], v[192:195], v[110:113]
	v_mfma_f32_16x16x32_bf16 v[98:101], v[138:141], v[192:195], v[98:101]
	v_mfma_f32_16x16x32_bf16 v[98:101], v[142:145], v[196:199], v[98:101]
	v_mfma_f32_16x16x32_bf16 v[106:109], v[134:137], v[196:199], v[106:109]
	v_mfma_f32_16x16x32_bf16 v[106:109], v[130:133], v[192:195], v[106:109]
	v_mfma_f32_16x16x32_bf16 v[90:93], v[130:133], v[200:203], v[90:93]
	v_mfma_f32_16x16x32_bf16 v[90:93], v[134:137], v[204:207], v[90:93]
	v_mfma_f32_16x16x32_bf16 v[82:85], v[142:145], v[204:207], v[82:85]
	v_mfma_f32_16x16x32_bf16 v[82:85], v[138:141], v[200:203], v[82:85]
	v_mfma_f32_16x16x32_bf16 v[94:97], v[146:149], v[200:203], v[94:97]
	v_mfma_f32_16x16x32_bf16 v[94:97], v[150:153], v[204:207], v[94:97]
	v_mfma_f32_16x16x32_bf16 v[86:89], v[176:179], v[204:207], v[86:89]
	v_mfma_f32_16x16x32_bf16 v[86:89], v[172:175], v[200:203], v[86:89]
	v_mfma_f32_16x16x32_bf16 v[70:73], v[172:175], v[208:211], v[70:73]
	v_mfma_f32_16x16x32_bf16 v[70:73], v[176:179], v[212:215], v[70:73]
	v_mfma_f32_16x16x32_bf16 v[78:81], v[150:153], v[212:215], v[78:81]
	v_mfma_f32_16x16x32_bf16 v[78:81], v[146:149], v[208:211], v[78:81]
	v_mfma_f32_16x16x32_bf16 v[66:69], v[138:141], v[208:211], v[66:69]
	v_mfma_f32_16x16x32_bf16 v[66:69], v[142:145], v[212:215], v[66:69]
	v_mfma_f32_16x16x32_bf16 v[74:77], v[134:137], v[212:215], v[74:77]
	v_mfma_f32_16x16x32_bf16 v[74:77], v[130:133], v[208:211], v[74:77]
	s_barrier
	s_add_i32 s33, s62, s36
	s_mov_b32 m0, s33
	ds_read_b128 v[180:183], v185 offset:16384
	ds_read_b128 v[188:191], v185 offset:17408
	ds_read_b128 v[192:195], v185 offset:18432
	ds_read_b128 v[196:199], v185 offset:19456
	ds_read_b128 v[200:203], v185 offset:20480
	ds_read_b128 v[204:207], v185 offset:21504
	ds_read_b128 v[208:211], v185 offset:22528
	ds_read_b128 v[212:215], v185 offset:23552
	global_load_lds_dwordx4 v156, s[24:25]
	s_add_i32 m0, s33, 0x2000
	s_add_u32 s72, s24, 0x100000
	s_addc_u32 s73, s25, 0
	s_add_i32 s33, s63, s36
	global_load_lds_dwordx4 v160, s[24:25]
	s_mov_b32 m0, s33
	s_add_u32 s100, s28, 0x80
	s_addc_u32 s101, s29, 0
	global_load_lds_dwordx4 v156, s[72:73]
	s_add_i32 m0, s33, 0x2000
	s_nop 0
	global_load_lds_dwordx4 v160, s[72:73]
	s_mov_b32 m0, s23
	s_nop 0
	global_load_lds_dwordx4 v154, s[28:29]
	s_mov_b32 m0, s37
	s_nop 0
	global_load_lds_dwordx4 v158, s[28:29]
	s_waitcnt vmcnt(8)
	s_waitcnt lgkmcnt(0)
	s_barrier
	s_waitcnt lgkmcnt(0)
	v_mfma_f32_16x16x32_bf16 v[58:61], v[130:133], v[180:183], v[58:61]
	v_mfma_f32_16x16x32_bf16 v[58:61], v[134:137], v[188:191], v[58:61]
	v_mfma_f32_16x16x32_bf16 v[54:57], v[142:145], v[188:191], v[54:57]
	v_mfma_f32_16x16x32_bf16 v[54:57], v[138:141], v[180:183], v[54:57]
	v_mfma_f32_16x16x32_bf16 v[62:65], v[146:149], v[180:183], v[62:65]
	v_mfma_f32_16x16x32_bf16 v[62:65], v[150:153], v[188:191], v[62:65]
	v_mfma_f32_16x16x32_bf16 v[50:53], v[176:179], v[188:191], v[50:53]
	v_mfma_f32_16x16x32_bf16 v[50:53], v[172:175], v[180:183], v[50:53]
	v_mfma_f32_16x16x32_bf16 v[38:41], v[172:175], v[192:195], v[38:41]
	v_mfma_f32_16x16x32_bf16 v[38:41], v[176:179], v[196:199], v[38:41]
	v_mfma_f32_16x16x32_bf16 v[46:49], v[150:153], v[196:199], v[46:49]
	v_mfma_f32_16x16x32_bf16 v[46:49], v[146:149], v[192:195], v[46:49]
	v_mfma_f32_16x16x32_bf16 v[34:37], v[138:141], v[192:195], v[34:37]
	v_mfma_f32_16x16x32_bf16 v[34:37], v[142:145], v[196:199], v[34:37]
	v_mfma_f32_16x16x32_bf16 v[42:45], v[134:137], v[196:199], v[42:45]
	v_mfma_f32_16x16x32_bf16 v[42:45], v[130:133], v[192:195], v[42:45]
	v_mfma_f32_16x16x32_bf16 v[26:29], v[130:133], v[200:203], v[26:29]
	v_mfma_f32_16x16x32_bf16 v[26:29], v[134:137], v[204:207], v[26:29]
	v_mfma_f32_16x16x32_bf16 v[18:21], v[142:145], v[204:207], v[18:21]
	v_mfma_f32_16x16x32_bf16 v[18:21], v[138:141], v[200:203], v[18:21]
	v_mfma_f32_16x16x32_bf16 v[30:33], v[146:149], v[200:203], v[30:33]
	v_mfma_f32_16x16x32_bf16 v[30:33], v[150:153], v[204:207], v[30:33]
	v_mfma_f32_16x16x32_bf16 v[22:25], v[176:179], v[204:207], v[22:25]
	v_mfma_f32_16x16x32_bf16 v[22:25], v[172:175], v[200:203], v[22:25]
	v_mfma_f32_16x16x32_bf16 v[14:17], v[172:175], v[208:211], v[14:17]
	v_mfma_f32_16x16x32_bf16 v[14:17], v[176:179], v[212:215], v[14:17]
	v_mfma_f32_16x16x32_bf16 v[10:13], v[150:153], v[212:215], v[10:13]
	v_mfma_f32_16x16x32_bf16 v[10:13], v[146:149], v[208:211], v[10:13]
	v_mfma_f32_16x16x32_bf16 v[2:5], v[138:141], v[208:211], v[2:5]
	v_mfma_f32_16x16x32_bf16 v[2:5], v[142:145], v[212:215], v[2:5]
	v_mfma_f32_16x16x32_bf16 v[6:9], v[134:137], v[212:215], v[6:9]
	v_mfma_f32_16x16x32_bf16 v[6:9], v[130:133], v[208:211], v[6:9]
	s_barrier
; #define PG8_STAGE(bufoff, gbase, voff) do { _Pragma("unroll") for (int _i = 0; _i < 2; ++_i) \
;         __builtin_amdgcn_global_load_lds((const unsigned*)((const char*)(gbase) + (voff)[_i]), (PG8_LAS unsigned*)(lds + (bufoff) + ldsw + _i * 8192), 16, 0, 0); } while (0)
; #define PG8_LDA(dst, b, h) do { _Pragma("unroll") for (int m = 0; m < 4; ++m) _Pragma("unroll") for (int k = 0; k < 2; ++k) dst[m][k] = *(const PG8_LAS bf16x8*)(lds + PG8_SA(b, h) + aoff + m * 2048 + k * 1024); } while (0)
; #define PG8_LDB(dst, b, h) do { _Pragma("unroll") for (int n = 0; n < 2; ++n) _Pragma("unroll") for (int k = 0; k < 2; ++k) dst[n][k] = *(const PG8_LAS bf16x8*)(lds + PG8_SB(b, h) + boff + n * 2048 + k * 1024); } while (0)
; #define PG8_MMA(ai, bj, At, Bt) do { __builtin_amdgcn_s_setprio(1); _Pragma("unroll") for (int m = 0; m < 4; ++m) _Pragma("unroll") for (int n = 0; n < 2; ++n) _Pragma("unroll") for (int k = 0; k < 2; ++k) \
;         acc[ai][bj][m][n] = __builtin_amdgcn_mfma_f32_16x16x32_bf16(Bt[n][k], At[m][k], acc[ai][bj][m][n], 0, 0, 0); __builtin_amdgcn_s_setprio(0); } while (0)
; #define PG8_WAIT_V(n) asm volatile("s_waitcnt vmcnt(" #n ")" ::: "memory")
; #define PG8_WAIT_L(n) asm volatile("s_waitcnt lgkmcnt(" #n ")" ::: "memory")
; #define PG8_BAR __builtin_amdgcn_s_barrier()
; #define PG8_SCHED __builtin_amdgcn_sched_barrier(0)
; template <class Epi, class Sched, bool ALIGN_EPI = false, bool SP2 = false>
; __device__ __forceinline__ void gemm_phase(PG8_LAS unsigned char* lds, const Gemm g, const Sched& S, const Epi& E) {
;     ...
;         for (int t = 0; t < nt; t += 2) {
;             const bool last = (t == nt - 2);
;             const char* a1 = cA + (size_t)(t + 1) * kstep;
;             const char* a2 = last ? nA : cA + (size_t)(t + 2) * kstep; const char* b2 = last ? nB : cB + (size_t)(t + 2) * kstep;
;     ...
;             PG8_LDB(B0, 1, 0); PG8_LDB(B1, 1, 1); PG8_SCHED; PG8_LDA(At, 1, 0); PG8_STAGE(PG8_SA(0, 1), a2 + hstep, voffA);
;             PG8_WAIT_V(8); PG8_WAIT_L(0); PG8_BAR; PG8_MMA(0, 0, At, B0); PG8_MMA(0, 1, At, B1); PG8_BAR; PG8_SCHED;
;             PG8_LDA(At, 1, 1); PG8_STAGE(PG8_SB(1, 0), b3, voffB); PG8_STAGE(PG8_SB(1, 1), b3 + hstep, voffB); PG8_STAGE(PG8_SA(1, 0), a3, voffA);
;             PG8_WAIT_V(8); PG8_WAIT_L(0); PG8_BAR; PG8_MMA(1, 0, At, B0); PG8_MMA(1, 1, At, B1); PG8_BAR; PG8_SCHED;
	s_add_i32 s33, 0, 0x18000
	s_add_i32 s42, 0, 0x1c000
	ds_read_b128 v[130:133], v241 offset:32768
	ds_read_b128 v[134:137], v241 offset:33792
	ds_read_b128 v[138:141], v241 offset:34816
	ds_read_b128 v[142:145], v241 offset:35840
	ds_read_b128 v[146:149], v241 offset:49152
	ds_read_b128 v[150:153], v241 offset:50176
	ds_read_b128 v[172:175], v241 offset:51200
	ds_read_b128 v[176:179], v241 offset:52224
	s_add_u32 s28, s28, 0x100000
	s_addc_u32 s29, s29, 0
	s_mov_b32 m0, s40
	ds_read_b128 v[180:183], v185 offset:32768
	ds_read_b128 v[188:191], v185 offset:33792
	ds_read_b128 v[192:195], v185 offset:34816
	ds_read_b128 v[196:199], v185 offset:35840
	ds_read_b128 v[200:203], v185 offset:36864
	ds_read_b128 v[204:207], v185 offset:37888
	ds_read_b128 v[208:211], v185 offset:38912
	ds_read_b128 v[212:215], v185 offset:39936
	global_load_lds_dwordx4 v154, s[28:29]
	s_mov_b32 m0, s41
	s_nop 0
	global_load_lds_dwordx4 v158, s[28:29]
	s_waitcnt vmcnt(8)
	s_waitcnt lgkmcnt(0)
	s_barrier
	s_waitcnt lgkmcnt(0)
	v_mfma_f32_16x16x32_bf16 v[114:117], v[130:133], v[180:183], v[114:117]
	v_mfma_f32_16x16x32_bf16 v[114:117], v[134:137], v[188:191], v[114:117]
	v_mfma_f32_16x16x32_bf16 v[118:121], v[142:145], v[188:191], v[118:121]
	v_mfma_f32_16x16x32_bf16 v[118:121], v[138:141], v[180:183], v[118:121]
	v_mfma_f32_16x16x32_bf16 v[122:125], v[146:149], v[180:183], v[122:125]
	v_mfma_f32_16x16x32_bf16 v[122:125], v[150:153], v[188:191], v[122:125]
	v_mfma_f32_16x16x32_bf16 v[126:129], v[176:179], v[188:191], v[126:129]
	v_mfma_f32_16x16x32_bf16 v[126:129], v[172:175], v[180:183], v[126:129]
	v_mfma_f32_16x16x32_bf16 v[102:105], v[172:175], v[192:195], v[102:105]
	v_mfma_f32_16x16x32_bf16 v[102:105], v[176:179], v[196:199], v[102:105]
	v_mfma_f32_16x16x32_bf16 v[110:113], v[150:153], v[196:199], v[110:113]
	v_mfma_f32_16x16x32_bf16 v[110:113], v[146:149], v[192:195], v[110:113]
	v_mfma_f32_16x16x32_bf16 v[98:101], v[138:141], v[192:195], v[98:101]
	v_mfma_f32_16x16x32_bf16 v[98:101], v[142:145], v[196:199], v[98:101]
	v_mfma_f32_16x16x32_bf16 v[106:109], v[134:137], v[196:199], v[106:109]
	v_mfma_f32_16x16x32_bf16 v[106:109], v[130:133], v[192:195], v[106:109]
	v_mfma_f32_16x16x32_bf16 v[90:93], v[130:133], v[200:203], v[90:93]
	v_mfma_f32_16x16x32_bf16 v[90:93], v[134:137], v[204:207], v[90:93]
	v_mfma_f32_16x16x32_bf16 v[82:85], v[142:145], v[204:207], v[82:85]
	v_mfma_f32_16x16x32_bf16 v[82:85], v[138:141], v[200:203], v[82:85]
	v_mfma_f32_16x16x32_bf16 v[94:97], v[146:149], v[200:203], v[94:97]
	v_mfma_f32_16x16x32_bf16 v[94:97], v[150:153], v[204:207], v[94:97]
	v_mfma_f32_16x16x32_bf16 v[86:89], v[176:179], v[204:207], v[86:89]
	v_mfma_f32_16x16x32_bf16 v[86:89], v[172:175], v[200:203], v[86:89]
	v_mfma_f32_16x16x32_bf16 v[70:73], v[172:175], v[208:211], v[70:73]
	v_mfma_f32_16x16x32_bf16 v[70:73], v[176:179], v[212:215], v[70:73]
	v_mfma_f32_16x16x32_bf16 v[78:81], v[150:153], v[212:215], v[78:81]
	v_mfma_f32_16x16x32_bf16 v[78:81], v[146:149], v[208:211], v[78:81]
	v_mfma_f32_16x16x32_bf16 v[66:69], v[138:141], v[208:211], v[66:69]
	v_mfma_f32_16x16x32_bf16 v[66:69], v[142:145], v[212:215], v[66:69]
	v_mfma_f32_16x16x32_bf16 v[74:77], v[134:137], v[212:215], v[74:77]
	v_mfma_f32_16x16x32_bf16 v[74:77], v[130:133], v[208:211], v[74:77]
	s_barrier
	s_add_i32 s28, s33, s36
	s_add_i32 m0, s28, 0xffffff80
	ds_read_b128 v[180:183], v185 offset:49152
	ds_read_b128 v[188:191], v185 offset:50176
	ds_read_b128 v[192:195], v185 offset:51200
	ds_read_b128 v[196:199], v185 offset:52224
	ds_read_b128 v[200:203], v185 offset:53248
	ds_read_b128 v[204:207], v185 offset:54272
	ds_read_b128 v[208:211], v185 offset:55296
	ds_read_b128 v[212:215], v185 offset:56320
	global_load_lds_dwordx4 v156, s[24:25] offset:128
	s_add_i32 m0, s28, 0x1f80
	s_add_i32 s28, s42, s36
	global_load_lds_dwordx4 v160, s[24:25] offset:128
	s_add_u32 s24, s24, 0x100080
	s_addc_u32 s25, s25, 0
	s_mov_b32 m0, s28
	s_nop 0
	global_load_lds_dwordx4 v156, s[24:25]
	s_add_i32 m0, s28, 0x2000
	s_nop 0
	global_load_lds_dwordx4 v160, s[24:25]
	s_mov_b32 m0, s46
	s_nop 0
	global_load_lds_dwordx4 v154, s[100:101]
	s_mov_b32 m0, s47
	s_nop 0
	global_load_lds_dwordx4 v158, s[100:101]
	s_waitcnt vmcnt(8)
	s_waitcnt lgkmcnt(0)
	s_barrier
	s_waitcnt lgkmcnt(0)
	v_mfma_f32_16x16x32_bf16 v[58:61], v[130:133], v[180:183], v[58:61]
	v_mfma_f32_16x16x32_bf16 v[58:61], v[134:137], v[188:191], v[58:61]
	v_mfma_f32_16x16x32_bf16 v[54:57], v[142:145], v[188:191], v[54:57]
	v_mfma_f32_16x16x32_bf16 v[54:57], v[138:141], v[180:183], v[54:57]
	v_mfma_f32_16x16x32_bf16 v[62:65], v[146:149], v[180:183], v[62:65]
	v_mfma_f32_16x16x32_bf16 v[62:65], v[150:153], v[188:191], v[62:65]
	v_mfma_f32_16x16x32_bf16 v[50:53], v[176:179], v[188:191], v[50:53]
	v_mfma_f32_16x16x32_bf16 v[50:53], v[172:175], v[180:183], v[50:53]
	v_mfma_f32_16x16x32_bf16 v[38:41], v[172:175], v[192:195], v[38:41]
	v_mfma_f32_16x16x32_bf16 v[38:41], v[176:179], v[196:199], v[38:41]
	v_mfma_f32_16x16x32_bf16 v[46:49], v[150:153], v[196:199], v[46:49]
	v_mfma_f32_16x16x32_bf16 v[46:49], v[146:149], v[192:195], v[46:49]
	v_mfma_f32_16x16x32_bf16 v[34:37], v[138:141], v[192:195], v[34:37]
	v_mfma_f32_16x16x32_bf16 v[34:37], v[142:145], v[196:199], v[34:37]
	v_mfma_f32_16x16x32_bf16 v[42:45], v[134:137], v[196:199], v[42:45]
	v_mfma_f32_16x16x32_bf16 v[42:45], v[130:133], v[192:195], v[42:45]
	v_mfma_f32_16x16x32_bf16 v[26:29], v[130:133], v[200:203], v[26:29]
	v_mfma_f32_16x16x32_bf16 v[26:29], v[134:137], v[204:207], v[26:29]
	v_mfma_f32_16x16x32_bf16 v[18:21], v[142:145], v[204:207], v[18:21]
	v_mfma_f32_16x16x32_bf16 v[18:21], v[138:141], v[200:203], v[18:21]
	v_mfma_f32_16x16x32_bf16 v[30:33], v[146:149], v[200:203], v[30:33]
	v_mfma_f32_16x16x32_bf16 v[30:33], v[150:153], v[204:207], v[30:33]
	v_mfma_f32_16x16x32_bf16 v[22:25], v[176:179], v[204:207], v[22:25]
	v_mfma_f32_16x16x32_bf16 v[22:25], v[172:175], v[200:203], v[22:25]
	v_mfma_f32_16x16x32_bf16 v[14:17], v[172:175], v[208:211], v[14:17]
	v_mfma_f32_16x16x32_bf16 v[14:17], v[176:179], v[212:215], v[14:17]
	v_mfma_f32_16x16x32_bf16 v[10:13], v[150:153], v[212:215], v[10:13]
	v_mfma_f32_16x16x32_bf16 v[10:13], v[146:149], v[208:211], v[10:13]
	v_mfma_f32_16x16x32_bf16 v[2:5], v[138:141], v[208:211], v[2:5]
	v_mfma_f32_16x16x32_bf16 v[2:5], v[142:145], v[212:215], v[2:5]
	v_mfma_f32_16x16x32_bf16 v[6:9], v[134:137], v[212:215], v[6:9]
	v_mfma_f32_16x16x32_bf16 v[6:9], v[130:133], v[208:211], v[6:9]
	s_barrier
	s_add_i32 s68, s68, 2
	s_add_u32 s26, s26, 0x100
	s_addc_u32 s27, s27, 0
	s_add_u32 s66, s66, 0x100
	s_addc_u32 s67, s67, 0
	s_cmp_gt_u32 s68, 61
	s_cbranch_scc0 .LBB0_1039
	s_and_b64 vcc, exec, s[10:11]
	s_cbranch_vccz .LBB0_1042
	s_barrier

; #define PG8_STAGE(bufoff, gbase, voff) do { _Pragma("unroll") for (int _i = 0; _i < 2; ++_i) \
;         __builtin_amdgcn_global_load_lds((const unsigned*)((const char*)(gbase) + (voff)[_i]), (PG8_LAS unsigned*)(lds + (bufoff) + ldsw + _i * 8192), 16, 0, 0); } while (0)
; #define PG8_LDA(dst, b, h) do { _Pragma("unroll") for (int m = 0; m < 4; ++m) _Pragma("unroll") for (int k = 0; k < 2; ++k) dst[m][k] = *(const PG8_LAS bf16x8*)(lds + PG8_SA(b, h) + aoff + m * 2048 + k * 1024); } while (0)
; #define PG8_LDB(dst, b, h) do { _Pragma("unroll") for (int n = 0; n < 2; ++n) _Pragma("unroll") for (int k = 0; k < 2; ++k) dst[n][k] = *(const PG8_LAS bf16x8*)(lds + PG8_SB(b, h) + boff + n * 2048 + k * 1024); } while (0)
; #define PG8_MMA(ai, bj, At, Bt) do { __builtin_amdgcn_s_setprio(1); _Pragma("unroll") for (int m = 0; m < 4; ++m) _Pragma("unroll") for (int n = 0; n < 2; ++n) _Pragma("unroll") for (int k = 0; k < 2; ++k) \
;         acc[ai][bj][m][n] = __builtin_amdgcn_mfma_f32_16x16x32_bf16(Bt[n][k], At[m][k], acc[ai][bj][m][n], 0, 0, 0); __builtin_amdgcn_s_setprio(0); } while (0)
; #define PG8_WAIT_V(n) asm volatile("s_waitcnt vmcnt(" #n ")" ::: "memory")
; #define PG8_BAR __builtin_amdgcn_s_barrier()
; template <class Epi, class Sched, bool ALIGN_EPI = false, bool SP2 = false>
; __device__ __forceinline__ void gemm_phase(PG8_LAS unsigned char* lds, const Gemm g, const Sched& S, const Epi& E) {
;     ...
;         for (int t = 0; t < nt; t += 2) {
;             const bool last = (t == nt - 2);
;             const char* a1 = cA + (size_t)(t + 1) * kstep;
;             const char* a2 = last ? nA : cA + (size_t)(t + 2) * kstep; const char* b2 = last ? nB : cB + (size_t)(t + 2) * kstep;
;             const char* a3 = a2 + kstep; const char* b3 = b2 + kstep;
;             if (last && has_next) S.a_ready(nxt);
;             if constexpr (SP2) {
;             PG8_LDB(B0, 0, 0); PG8_LDB(B1, 0, 1); PG8_SCHED; PG8_LDA(At, 0, 0); PG8_STAGE(PG8_SA(1, 1), a1 + hstep, voffA);
;             PG8_WAIT_V(8); PG8_WAIT_L(0); PG8_BAR; PG8_MMA(0, 0, At, B0); PG8_MMA(0, 1, At, B1); PG8_BAR; PG8_SCHED;
;             PG8_LDA(At, 0, 1); PG8_STAGE(PG8_SB(0, 0), b2, voffB); PG8_STAGE(PG8_SB(0, 1), b2 + hstep, voffB); PG8_STAGE(PG8_SA(0, 0), a2, voffA);
;             PG8_WAIT_V(8); PG8_WAIT_L(0); PG8_BAR; PG8_MMA(1, 0, At, B0); PG8_MMA(1, 1, At, B1); PG8_BAR; PG8_SCHED;
.LBB0_1126:
	ds_read_b128 v[160:163], v241 offset:0
	ds_read_b128 v[166:169], v241 offset:1024
	ds_read_b128 v[170:173], v241 offset:2048
	ds_read_b128 v[174:177], v241 offset:3072
	ds_read_b128 v[178:181], v241 offset:16384
	ds_read_b128 v[182:185], v241 offset:17408
	ds_read_b128 v[186:189], v241 offset:18432
	ds_read_b128 v[190:193], v241 offset:19456
	s_add_u32 s22, s24, 0xfff00080
	s_addc_u32 s23, s25, -1
	s_cmp_eq_u32 s68, 60
	s_cselect_b32 s27, s15, s23
	s_cselect_b32 s26, s64, s22
	s_cselect_b32 s23, s13, s67
	s_cselect_b32 s22, s65, s66
	s_add_i32 m0, s21, 0xc000
	ds_read_b128 v[194:197], v155
	ds_read_b128 v[198:201], v155 offset:1024
	ds_read_b128 v[202:205], v155 offset:2048
	ds_read_b128 v[206:209], v155 offset:3072
	ds_read_b128 v[210:213], v155 offset:4096
	ds_read_b128 v[214:217], v155 offset:5120
	ds_read_b128 v[218:221], v155 offset:6144
	ds_read_b128 v[222:225], v155 offset:7168
	global_load_lds_dwordx4 v138, s[24:25]
	s_add_i32 m0, s21, 0xe000
	s_nop 0
	global_load_lds_dwordx4 v140, s[24:25]
	s_waitcnt vmcnt(8)
	s_waitcnt lgkmcnt(0)
	s_barrier
	s_waitcnt lgkmcnt(0)
	v_mfma_f32_16x16x32_bf16 v[122:125], v[160:163], v[194:197], v[122:125]
	v_mfma_f32_16x16x32_bf16 v[122:125], v[166:169], v[198:201], v[122:125]
	v_mfma_f32_16x16x32_bf16 v[114:117], v[174:177], v[198:201], v[114:117]
	v_mfma_f32_16x16x32_bf16 v[114:117], v[170:173], v[194:197], v[114:117]
	v_mfma_f32_16x16x32_bf16 v[126:129], v[178:181], v[194:197], v[126:129]
	v_mfma_f32_16x16x32_bf16 v[126:129], v[182:185], v[198:201], v[126:129]
	v_mfma_f32_16x16x32_bf16 v[118:121], v[190:193], v[198:201], v[118:121]
	v_mfma_f32_16x16x32_bf16 v[118:121], v[186:189], v[194:197], v[118:121]
	v_mfma_f32_16x16x32_bf16 v[102:105], v[186:189], v[202:205], v[102:105]
	v_mfma_f32_16x16x32_bf16 v[102:105], v[190:193], v[206:209], v[102:105]
	v_mfma_f32_16x16x32_bf16 v[110:113], v[182:185], v[206:209], v[110:113]
	v_mfma_f32_16x16x32_bf16 v[110:113], v[178:181], v[202:205], v[110:113]
	v_mfma_f32_16x16x32_bf16 v[98:101], v[170:173], v[202:205], v[98:101]
	v_mfma_f32_16x16x32_bf16 v[98:101], v[174:177], v[206:209], v[98:101]
	v_mfma_f32_16x16x32_bf16 v[106:109], v[166:169], v[206:209], v[106:109]
	v_mfma_f32_16x16x32_bf16 v[106:109], v[160:163], v[202:205], v[106:109]
	v_mfma_f32_16x16x32_bf16 v[90:93], v[160:163], v[210:213], v[90:93]
	v_mfma_f32_16x16x32_bf16 v[90:93], v[166:169], v[214:217], v[90:93]
	v_mfma_f32_16x16x32_bf16 v[82:85], v[174:177], v[214:217], v[82:85]
	v_mfma_f32_16x16x32_bf16 v[82:85], v[170:173], v[210:213], v[82:85]
	v_mfma_f32_16x16x32_bf16 v[94:97], v[178:181], v[210:213], v[94:97]
	v_mfma_f32_16x16x32_bf16 v[94:97], v[182:185], v[214:217], v[94:97]
	v_mfma_f32_16x16x32_bf16 v[86:89], v[190:193], v[214:217], v[86:89]
	v_mfma_f32_16x16x32_bf16 v[86:89], v[186:189], v[210:213], v[86:89]
	v_mfma_f32_16x16x32_bf16 v[70:73], v[186:189], v[218:221], v[70:73]
	v_mfma_f32_16x16x32_bf16 v[70:73], v[190:193], v[222:225], v[70:73]
	v_mfma_f32_16x16x32_bf16 v[78:81], v[182:185], v[222:225], v[78:81]
	v_mfma_f32_16x16x32_bf16 v[78:81], v[178:181], v[218:221], v[78:81]
	v_mfma_f32_16x16x32_bf16 v[62:65], v[170:173], v[218:221], v[62:65]
	v_mfma_f32_16x16x32_bf16 v[62:65], v[174:177], v[222:225], v[62:65]
	v_mfma_f32_16x16x32_bf16 v[74:77], v[166:169], v[222:225], v[74:77]
	v_mfma_f32_16x16x32_bf16 v[74:77], v[160:163], v[218:221], v[74:77]
	s_barrier
	s_add_i32 s33, s52, s29
	s_mov_b32 m0, s33
	ds_read_b128 v[194:197], v155 offset:16384
	ds_read_b128 v[198:201], v155 offset:17408
	ds_read_b128 v[202:205], v155 offset:18432
	ds_read_b128 v[206:209], v155 offset:19456
	ds_read_b128 v[210:213], v155 offset:20480
	ds_read_b128 v[214:217], v155 offset:21504
	ds_read_b128 v[218:221], v155 offset:22528
	ds_read_b128 v[222:225], v155 offset:23552
	global_load_lds_dwordx4 v132, s[22:23]
	s_add_i32 m0, s33, 0x2000
	s_add_u32 s72, s22, 0x100000
	s_addc_u32 s73, s23, 0
	s_add_i32 s33, s53, s29
	global_load_lds_dwordx4 v136, s[22:23]
	s_mov_b32 m0, s33
	s_add_u32 s100, s26, 0x80
	s_addc_u32 s101, s27, 0
	global_load_lds_dwordx4 v132, s[72:73]
	s_add_i32 m0, s33, 0x2000
	s_nop 0
	global_load_lds_dwordx4 v136, s[72:73]
	s_mov_b32 m0, s21
	s_nop 0
	global_load_lds_dwordx4 v130, s[26:27]
	s_mov_b32 m0, s36
	s_nop 0
	global_load_lds_dwordx4 v134, s[26:27]
	s_waitcnt vmcnt(8)
	s_waitcnt lgkmcnt(0)
	s_barrier
	s_waitcnt lgkmcnt(0)
	v_mfma_f32_16x16x32_bf16 v[58:61], v[160:163], v[194:197], v[58:61]
	v_mfma_f32_16x16x32_bf16 v[58:61], v[166:169], v[198:201], v[58:61]
	v_mfma_f32_16x16x32_bf16 v[50:53], v[174:177], v[198:201], v[50:53]
	v_mfma_f32_16x16x32_bf16 v[50:53], v[170:173], v[194:197], v[50:53]
	v_mfma_f32_16x16x32_bf16 v[66:69], v[178:181], v[194:197], v[66:69]
	v_mfma_f32_16x16x32_bf16 v[66:69], v[182:185], v[198:201], v[66:69]
	v_mfma_f32_16x16x32_bf16 v[54:57], v[190:193], v[198:201], v[54:57]
	v_mfma_f32_16x16x32_bf16 v[54:57], v[186:189], v[194:197], v[54:57]
	v_mfma_f32_16x16x32_bf16 v[38:41], v[186:189], v[202:205], v[38:41]
	v_mfma_f32_16x16x32_bf16 v[38:41], v[190:193], v[206:209], v[38:41]
	v_mfma_f32_16x16x32_bf16 v[46:49], v[182:185], v[206:209], v[46:49]
	v_mfma_f32_16x16x32_bf16 v[46:49], v[178:181], v[202:205], v[46:49]
	v_mfma_f32_16x16x32_bf16 v[34:37], v[170:173], v[202:205], v[34:37]
	v_mfma_f32_16x16x32_bf16 v[34:37], v[174:177], v[206:209], v[34:37]
	v_mfma_f32_16x16x32_bf16 v[42:45], v[166:169], v[206:209], v[42:45]
	v_mfma_f32_16x16x32_bf16 v[42:45], v[160:163], v[202:205], v[42:45]
	v_mfma_f32_16x16x32_bf16 v[26:29], v[160:163], v[210:213], v[26:29]
	v_mfma_f32_16x16x32_bf16 v[26:29], v[166:169], v[214:217], v[26:29]
	v_mfma_f32_16x16x32_bf16 v[18:21], v[174:177], v[214:217], v[18:21]
	v_mfma_f32_16x16x32_bf16 v[18:21], v[170:173], v[210:213], v[18:21]
	v_mfma_f32_16x16x32_bf16 v[30:33], v[178:181], v[210:213], v[30:33]
	v_mfma_f32_16x16x32_bf16 v[30:33], v[182:185], v[214:217], v[30:33]
	v_mfma_f32_16x16x32_bf16 v[22:25], v[190:193], v[214:217], v[22:25]
	v_mfma_f32_16x16x32_bf16 v[22:25], v[186:189], v[210:213], v[22:25]
	v_mfma_f32_16x16x32_bf16 v[6:9], v[186:189], v[218:221], v[6:9]
	v_mfma_f32_16x16x32_bf16 v[6:9], v[190:193], v[222:225], v[6:9]
	v_mfma_f32_16x16x32_bf16 v[14:17], v[182:185], v[222:225], v[14:17]
	v_mfma_f32_16x16x32_bf16 v[14:17], v[178:181], v[218:221], v[14:17]
	v_mfma_f32_16x16x32_bf16 v[2:5], v[170:173], v[218:221], v[2:5]
	v_mfma_f32_16x16x32_bf16 v[2:5], v[174:177], v[222:225], v[2:5]
	v_mfma_f32_16x16x32_bf16 v[10:13], v[166:169], v[222:225], v[10:13]
	v_mfma_f32_16x16x32_bf16 v[10:13], v[160:163], v[218:221], v[10:13]
	s_barrier
; #define PG8_STAGE(bufoff, gbase, voff) do { _Pragma("unroll") for (int _i = 0; _i < 2; ++_i) \
;         __builtin_amdgcn_global_load_lds((const unsigned*)((const char*)(gbase) + (voff)[_i]), (PG8_LAS unsigned*)(lds + (bufoff) + ldsw + _i * 8192), 16, 0, 0); } while (0)
; #define PG8_LDA(dst, b, h) do { _Pragma("unroll") for (int m = 0; m < 4; ++m) _Pragma("unroll") for (int k = 0; k < 2; ++k) dst[m][k] = *(const PG8_LAS bf16x8*)(lds + PG8_SA(b, h) + aoff + m * 2048 + k * 1024); } while (0)
; #define PG8_LDB(dst, b, h) do { _Pragma("unroll") for (int n = 0; n < 2; ++n) _Pragma("unroll") for (int k = 0; k < 2; ++k) dst[n][k] = *(const PG8_LAS bf16x8*)(lds + PG8_SB(b, h) + boff + n * 2048 + k * 1024); } while (0)
; #define PG8_MMA(ai, bj, At, Bt) do { __builtin_amdgcn_s_setprio(1); _Pragma("unroll") for (int m = 0; m < 4; ++m) _Pragma("unroll") for (int n = 0; n < 2; ++n) _Pragma("unroll") for (int k = 0; k < 2; ++k) \
;         acc[ai][bj][m][n] = __builtin_amdgcn_mfma_f32_16x16x32_bf16(Bt[n][k], At[m][k], acc[ai][bj][m][n], 0, 0, 0); __builtin_amdgcn_s_setprio(0); } while (0)
; #define PG8_WAIT_V(n) asm volatile("s_waitcnt vmcnt(" #n ")" ::: "memory")
; #define PG8_WAIT_L(n) asm volatile("s_waitcnt lgkmcnt(" #n ")" ::: "memory")
; #define PG8_BAR __builtin_amdgcn_s_barrier()
; #define PG8_SCHED __builtin_amdgcn_sched_barrier(0)
; template <class Epi, class Sched, bool ALIGN_EPI = false, bool SP2 = false>
; __device__ __forceinline__ void gemm_phase(PG8_LAS unsigned char* lds, const Gemm g, const Sched& S, const Epi& E) {
;     ...
;         for (int t = 0; t < nt; t += 2) {
;             const bool last = (t == nt - 2);
;             const char* a1 = cA + (size_t)(t + 1) * kstep;
;             const char* a2 = last ? nA : cA + (size_t)(t + 2) * kstep; const char* b2 = last ? nB : cB + (size_t)(t + 2) * kstep;
;     ...
;             PG8_LDB(B0, 1, 0); PG8_LDB(B1, 1, 1); PG8_SCHED; PG8_LDA(At, 1, 0); PG8_STAGE(PG8_SA(0, 1), a2 + hstep, voffA);
;             PG8_WAIT_V(8); PG8_WAIT_L(0); PG8_BAR; PG8_MMA(0, 0, At, B0); PG8_MMA(0, 1, At, B1); PG8_BAR; PG8_SCHED;
;             PG8_LDA(At, 1, 1); PG8_STAGE(PG8_SB(1, 0), b3, voffB); PG8_STAGE(PG8_SB(1, 1), b3 + hstep, voffB); PG8_STAGE(PG8_SA(1, 0), a3, voffA);
;             PG8_WAIT_V(8); PG8_WAIT_L(0); PG8_BAR; PG8_MMA(1, 0, At, B0); PG8_MMA(1, 1, At, B1); PG8_BAR; PG8_SCHED;
	s_add_i32 s33, 0, 0x18000
	s_add_i32 s42, 0, 0x1c000
	ds_read_b128 v[160:163], v241 offset:32768
	ds_read_b128 v[166:169], v241 offset:33792
	ds_read_b128 v[170:173], v241 offset:34816
	ds_read_b128 v[174:177], v241 offset:35840
	ds_read_b128 v[178:181], v241 offset:49152
	ds_read_b128 v[182:185], v241 offset:50176
	ds_read_b128 v[186:189], v241 offset:51200
	ds_read_b128 v[190:193], v241 offset:52224
	s_add_u32 s26, s26, 0x100000
	s_addc_u32 s27, s27, 0
	s_mov_b32 m0, s37
	ds_read_b128 v[194:197], v155 offset:32768
	ds_read_b128 v[198:201], v155 offset:33792
	ds_read_b128 v[202:205], v155 offset:34816
	ds_read_b128 v[206:209], v155 offset:35840
	ds_read_b128 v[210:213], v155 offset:36864
	ds_read_b128 v[214:217], v155 offset:37888
	ds_read_b128 v[218:221], v155 offset:38912
	ds_read_b128 v[222:225], v155 offset:39936
	global_load_lds_dwordx4 v130, s[26:27]
	s_mov_b32 m0, s40
	s_nop 0
	global_load_lds_dwordx4 v134, s[26:27]
	s_waitcnt vmcnt(8)
	s_waitcnt lgkmcnt(0)
	s_barrier
	s_waitcnt lgkmcnt(0)
	v_mfma_f32_16x16x32_bf16 v[122:125], v[160:163], v[194:197], v[122:125]
	v_mfma_f32_16x16x32_bf16 v[122:125], v[166:169], v[198:201], v[122:125]
	v_mfma_f32_16x16x32_bf16 v[114:117], v[174:177], v[198:201], v[114:117]
	v_mfma_f32_16x16x32_bf16 v[114:117], v[170:173], v[194:197], v[114:117]
	v_mfma_f32_16x16x32_bf16 v[126:129], v[178:181], v[194:197], v[126:129]
	v_mfma_f32_16x16x32_bf16 v[126:129], v[182:185], v[198:201], v[126:129]
	v_mfma_f32_16x16x32_bf16 v[118:121], v[190:193], v[198:201], v[118:121]
	v_mfma_f32_16x16x32_bf16 v[118:121], v[186:189], v[194:197], v[118:121]
	v_mfma_f32_16x16x32_bf16 v[102:105], v[186:189], v[202:205], v[102:105]
	v_mfma_f32_16x16x32_bf16 v[102:105], v[190:193], v[206:209], v[102:105]
	v_mfma_f32_16x16x32_bf16 v[110:113], v[182:185], v[206:209], v[110:113]
	v_mfma_f32_16x16x32_bf16 v[110:113], v[178:181], v[202:205], v[110:113]
	v_mfma_f32_16x16x32_bf16 v[98:101], v[170:173], v[202:205], v[98:101]
	v_mfma_f32_16x16x32_bf16 v[98:101], v[174:177], v[206:209], v[98:101]
	v_mfma_f32_16x16x32_bf16 v[106:109], v[166:169], v[206:209], v[106:109]
	v_mfma_f32_16x16x32_bf16 v[106:109], v[160:163], v[202:205], v[106:109]
	v_mfma_f32_16x16x32_bf16 v[90:93], v[160:163], v[210:213], v[90:93]
	v_mfma_f32_16x16x32_bf16 v[90:93], v[166:169], v[214:217], v[90:93]
	v_mfma_f32_16x16x32_bf16 v[82:85], v[174:177], v[214:217], v[82:85]
	v_mfma_f32_16x16x32_bf16 v[82:85], v[170:173], v[210:213], v[82:85]
	v_mfma_f32_16x16x32_bf16 v[94:97], v[178:181], v[210:213], v[94:97]
	v_mfma_f32_16x16x32_bf16 v[94:97], v[182:185], v[214:217], v[94:97]
	v_mfma_f32_16x16x32_bf16 v[86:89], v[190:193], v[214:217], v[86:89]
	v_mfma_f32_16x16x32_bf16 v[86:89], v[186:189], v[210:213], v[86:89]
	v_mfma_f32_16x16x32_bf16 v[70:73], v[186:189], v[218:221], v[70:73]
	v_mfma_f32_16x16x32_bf16 v[70:73], v[190:193], v[222:225], v[70:73]
	v_mfma_f32_16x16x32_bf16 v[78:81], v[182:185], v[222:225], v[78:81]
	v_mfma_f32_16x16x32_bf16 v[78:81], v[178:181], v[218:221], v[78:81]
	v_mfma_f32_16x16x32_bf16 v[62:65], v[170:173], v[218:221], v[62:65]
	v_mfma_f32_16x16x32_bf16 v[62:65], v[174:177], v[222:225], v[62:65]
	v_mfma_f32_16x16x32_bf16 v[74:77], v[166:169], v[222:225], v[74:77]
	v_mfma_f32_16x16x32_bf16 v[74:77], v[160:163], v[218:221], v[74:77]
	s_barrier
	s_add_i32 s26, s33, s29
	s_add_i32 m0, s26, 0xffffff80
	ds_read_b128 v[194:197], v155 offset:49152
	ds_read_b128 v[198:201], v155 offset:50176
	ds_read_b128 v[202:205], v155 offset:51200
	ds_read_b128 v[206:209], v155 offset:52224
	ds_read_b128 v[210:213], v155 offset:53248
	ds_read_b128 v[214:217], v155 offset:54272
	ds_read_b128 v[218:221], v155 offset:55296
	ds_read_b128 v[222:225], v155 offset:56320
	global_load_lds_dwordx4 v132, s[22:23] offset:128
	s_add_i32 m0, s26, 0x1f80
	s_add_i32 s26, s42, s29
	global_load_lds_dwordx4 v136, s[22:23] offset:128
	s_add_u32 s22, s22, 0x100080
	s_addc_u32 s23, s23, 0
	s_mov_b32 m0, s26
	s_nop 0
	global_load_lds_dwordx4 v132, s[22:23]
	s_add_i32 m0, s26, 0x2000
	s_nop 0
	global_load_lds_dwordx4 v136, s[22:23]
	s_mov_b32 m0, s46
	s_nop 0
	global_load_lds_dwordx4 v130, s[100:101]
	s_mov_b32 m0, s47
	s_nop 0
	global_load_lds_dwordx4 v134, s[100:101]
	s_waitcnt vmcnt(8)
	s_waitcnt lgkmcnt(0)
	s_barrier
	s_waitcnt lgkmcnt(0)
	v_mfma_f32_16x16x32_bf16 v[58:61], v[160:163], v[194:197], v[58:61]
	v_mfma_f32_16x16x32_bf16 v[58:61], v[166:169], v[198:201], v[58:61]
	v_mfma_f32_16x16x32_bf16 v[50:53], v[174:177], v[198:201], v[50:53]
	v_mfma_f32_16x16x32_bf16 v[50:53], v[170:173], v[194:197], v[50:53]
	v_mfma_f32_16x16x32_bf16 v[66:69], v[178:181], v[194:197], v[66:69]
	v_mfma_f32_16x16x32_bf16 v[66:69], v[182:185], v[198:201], v[66:69]
	v_mfma_f32_16x16x32_bf16 v[54:57], v[190:193], v[198:201], v[54:57]
	v_mfma_f32_16x16x32_bf16 v[54:57], v[186:189], v[194:197], v[54:57]
	v_mfma_f32_16x16x32_bf16 v[38:41], v[186:189], v[202:205], v[38:41]
	v_mfma_f32_16x16x32_bf16 v[38:41], v[190:193], v[206:209], v[38:41]
	v_mfma_f32_16x16x32_bf16 v[46:49], v[182:185], v[206:209], v[46:49]
	v_mfma_f32_16x16x32_bf16 v[46:49], v[178:181], v[202:205], v[46:49]
	v_mfma_f32_16x16x32_bf16 v[34:37], v[170:173], v[202:205], v[34:37]
	v_mfma_f32_16x16x32_bf16 v[34:37], v[174:177], v[206:209], v[34:37]
	v_mfma_f32_16x16x32_bf16 v[42:45], v[166:169], v[206:209], v[42:45]
	v_mfma_f32_16x16x32_bf16 v[42:45], v[160:163], v[202:205], v[42:45]
	v_mfma_f32_16x16x32_bf16 v[26:29], v[160:163], v[210:213], v[26:29]
	v_mfma_f32_16x16x32_bf16 v[26:29], v[166:169], v[214:217], v[26:29]
	v_mfma_f32_16x16x32_bf16 v[18:21], v[174:177], v[214:217], v[18:21]
	v_mfma_f32_16x16x32_bf16 v[18:21], v[170:173], v[210:213], v[18:21]
	v_mfma_f32_16x16x32_bf16 v[30:33], v[178:181], v[210:213], v[30:33]
	v_mfma_f32_16x16x32_bf16 v[30:33], v[182:185], v[214:217], v[30:33]
	v_mfma_f32_16x16x32_bf16 v[22:25], v[190:193], v[214:217], v[22:25]
	v_mfma_f32_16x16x32_bf16 v[22:25], v[186:189], v[210:213], v[22:25]
	v_mfma_f32_16x16x32_bf16 v[6:9], v[186:189], v[218:221], v[6:9]
	v_mfma_f32_16x16x32_bf16 v[6:9], v[190:193], v[222:225], v[6:9]
	v_mfma_f32_16x16x32_bf16 v[14:17], v[182:185], v[222:225], v[14:17]
	v_mfma_f32_16x16x32_bf16 v[14:17], v[178:181], v[218:221], v[14:17]
	v_mfma_f32_16x16x32_bf16 v[2:5], v[170:173], v[218:221], v[2:5]
	v_mfma_f32_16x16x32_bf16 v[2:5], v[174:177], v[222:225], v[2:5]
	v_mfma_f32_16x16x32_bf16 v[10:13], v[166:169], v[222:225], v[10:13]
	v_mfma_f32_16x16x32_bf16 v[10:13], v[160:163], v[218:221], v[10:13]
	s_barrier
	s_add_i32 s68, s68, 2
	s_add_u32 s24, s24, 0x100
	s_addc_u32 s25, s25, 0
	s_add_u32 s66, s66, 0x100
	s_addc_u32 s67, s67, 0
	s_cmp_gt_u32 s68, 61
	s_cbranch_scc0 .LBB0_1126
	s_and_b64 vcc, exec, s[8:9]
	s_cbranch_vccz .LBB0_1129
	s_barrier

; #define PG8_STAGE(bufoff, gbase, voff) do { _Pragma("unroll") for (int _i = 0; _i < 2; ++_i) \
;         __builtin_amdgcn_global_load_lds((const unsigned*)((const char*)(gbase) + (voff)[_i]), (PG8_LAS unsigned*)(lds + (bufoff) + ldsw + _i * 8192), 16, 0, 0); } while (0)
; #define PG8_LDA(dst, b, h) do { _Pragma("unroll") for (int m = 0; m < 4; ++m) _Pragma("unroll") for (int k = 0; k < 2; ++k) dst[m][k] = *(const PG8_LAS bf16x8*)(lds + PG8_SA(b, h) + aoff + m * 2048 + k * 1024); } while (0)
; #define PG8_LDB(dst, b, h) do { _Pragma("unroll") for (int n = 0; n < 2; ++n) _Pragma("unroll") for (int k = 0; k < 2; ++k) dst[n][k] = *(const PG8_LAS bf16x8*)(lds + PG8_SB(b, h) + boff + n * 2048 + k * 1024); } while (0)
; #define PG8_MMA(ai, bj, At, Bt) do { __builtin_amdgcn_s_setprio(1); _Pragma("unroll") for (int m = 0; m < 4; ++m) _Pragma("unroll") for (int n = 0; n < 2; ++n) _Pragma("unroll") for (int k = 0; k < 2; ++k) \
;         acc[ai][bj][m][n] = __builtin_amdgcn_mfma_f32_16x16x32_bf16(Bt[n][k], At[m][k], acc[ai][bj][m][n], 0, 0, 0); __builtin_amdgcn_s_setprio(0); } while (0)
; #define PG8_WAIT_V(n) asm volatile("s_waitcnt vmcnt(" #n ")" ::: "memory")
; #define PG8_BAR __builtin_amdgcn_s_barrier()
; template <class Epi, class Sched, bool ALIGN_EPI = false, bool SP2 = false>
; __device__ __forceinline__ void gemm_phase(PG8_LAS unsigned char* lds, const Gemm g, const Sched& S, const Epi& E) {
;     ...
;         for (int t = 0; t < nt; t += 2) {
;             const bool last = (t == nt - 2);
;             const char* a1 = cA + (size_t)(t + 1) * kstep;
;             const char* a2 = last ? nA : cA + (size_t)(t + 2) * kstep; const char* b2 = last ? nB : cB + (size_t)(t + 2) * kstep;
;             const char* a3 = a2 + kstep; const char* b3 = b2 + kstep;
;             if (last && has_next) S.a_ready(nxt);
;             if constexpr (SP2) {
;             PG8_LDB(B0, 0, 0); PG8_LDB(B1, 0, 1); PG8_SCHED; PG8_LDA(At, 0, 0); PG8_STAGE(PG8_SA(1, 1), a1 + hstep, voffA);
;             PG8_WAIT_V(8); PG8_WAIT_L(0); PG8_BAR; PG8_MMA(0, 0, At, B0); PG8_MMA(0, 1, At, B1); PG8_BAR; PG8_SCHED;
;             PG8_LDA(At, 0, 1); PG8_STAGE(PG8_SB(0, 0), b2, voffB); PG8_STAGE(PG8_SB(0, 1), b2 + hstep, voffB); PG8_STAGE(PG8_SA(0, 0), a2, voffA);
;             PG8_WAIT_V(8); PG8_WAIT_L(0); PG8_BAR; PG8_MMA(1, 0, At, B0); PG8_MMA(1, 1, At, B1); PG8_BAR; PG8_SCHED;
.LBB0_1245:
	ds_read_b128 v[130:133], v241 offset:0
	ds_read_b128 v[134:137], v241 offset:1024
	ds_read_b128 v[138:141], v241 offset:2048
	ds_read_b128 v[142:145], v241 offset:3072
	ds_read_b128 v[146:149], v241 offset:16384
	ds_read_b128 v[150:153], v241 offset:17408
	ds_read_b128 v[172:175], v241 offset:18432
	ds_read_b128 v[176:179], v241 offset:19456
	s_add_u32 s16, s18, 0xffd50080
	s_addc_u32 s17, s19, -1
	s_cmpk_eq_i32 s64, 0xa8
	s_cselect_b32 s21, s5, s17
	s_cselect_b32 s20, s4, s16
	s_cselect_b32 s17, s15, s63
	s_cselect_b32 s16, s14, s62
	s_add_i32 m0, s25, 0xc000
	ds_read_b128 v[180:183], v185
	ds_read_b128 v[188:191], v185 offset:1024
	ds_read_b128 v[192:195], v185 offset:2048
	ds_read_b128 v[196:199], v185 offset:3072
	ds_read_b128 v[200:203], v185 offset:4096
	ds_read_b128 v[204:207], v185 offset:5120
	ds_read_b128 v[208:211], v185 offset:6144
	ds_read_b128 v[212:215], v185 offset:7168
	global_load_lds_dwordx4 v162, s[18:19]
	s_add_i32 m0, s25, 0xe000
	s_nop 0
	global_load_lds_dwordx4 v166, s[18:19]
	s_waitcnt vmcnt(8)
	s_waitcnt lgkmcnt(0)
	s_barrier
	s_waitcnt lgkmcnt(0)
	v_mfma_f32_16x16x32_bf16 v[114:117], v[130:133], v[180:183], v[114:117]
	v_mfma_f32_16x16x32_bf16 v[114:117], v[134:137], v[188:191], v[114:117]
	v_mfma_f32_16x16x32_bf16 v[118:121], v[142:145], v[188:191], v[118:121]
	v_mfma_f32_16x16x32_bf16 v[118:121], v[138:141], v[180:183], v[118:121]
	v_mfma_f32_16x16x32_bf16 v[122:125], v[146:149], v[180:183], v[122:125]
	v_mfma_f32_16x16x32_bf16 v[122:125], v[150:153], v[188:191], v[122:125]
	v_mfma_f32_16x16x32_bf16 v[126:129], v[176:179], v[188:191], v[126:129]
	v_mfma_f32_16x16x32_bf16 v[126:129], v[172:175], v[180:183], v[126:129]
	v_mfma_f32_16x16x32_bf16 v[102:105], v[172:175], v[192:195], v[102:105]
	v_mfma_f32_16x16x32_bf16 v[102:105], v[176:179], v[196:199], v[102:105]
	v_mfma_f32_16x16x32_bf16 v[110:113], v[150:153], v[196:199], v[110:113]
	v_mfma_f32_16x16x32_bf16 v[110:113], v[146:149], v[192:195], v[110:113]
	v_mfma_f32_16x16x32_bf16 v[98:101], v[138:141], v[192:195], v[98:101]
	v_mfma_f32_16x16x32_bf16 v[98:101], v[142:145], v[196:199], v[98:101]
	v_mfma_f32_16x16x32_bf16 v[106:109], v[134:137], v[196:199], v[106:109]
	v_mfma_f32_16x16x32_bf16 v[106:109], v[130:133], v[192:195], v[106:109]
	v_mfma_f32_16x16x32_bf16 v[90:93], v[130:133], v[200:203], v[90:93]
	v_mfma_f32_16x16x32_bf16 v[90:93], v[134:137], v[204:207], v[90:93]
	v_mfma_f32_16x16x32_bf16 v[82:85], v[142:145], v[204:207], v[82:85]
	v_mfma_f32_16x16x32_bf16 v[82:85], v[138:141], v[200:203], v[82:85]
	v_mfma_f32_16x16x32_bf16 v[94:97], v[146:149], v[200:203], v[94:97]
	v_mfma_f32_16x16x32_bf16 v[94:97], v[150:153], v[204:207], v[94:97]
	v_mfma_f32_16x16x32_bf16 v[86:89], v[176:179], v[204:207], v[86:89]
	v_mfma_f32_16x16x32_bf16 v[86:89], v[172:175], v[200:203], v[86:89]
	v_mfma_f32_16x16x32_bf16 v[70:73], v[172:175], v[208:211], v[70:73]
	v_mfma_f32_16x16x32_bf16 v[70:73], v[176:179], v[212:215], v[70:73]
	v_mfma_f32_16x16x32_bf16 v[78:81], v[150:153], v[212:215], v[78:81]
	v_mfma_f32_16x16x32_bf16 v[78:81], v[146:149], v[208:211], v[78:81]
	v_mfma_f32_16x16x32_bf16 v[66:69], v[138:141], v[208:211], v[66:69]
	v_mfma_f32_16x16x32_bf16 v[66:69], v[142:145], v[212:215], v[66:69]
	v_mfma_f32_16x16x32_bf16 v[74:77], v[134:137], v[212:215], v[74:77]
	v_mfma_f32_16x16x32_bf16 v[74:77], v[130:133], v[208:211], v[74:77]
	s_barrier
	s_add_i32 s33, s40, s24
	s_mov_b32 m0, s33
	ds_read_b128 v[180:183], v185 offset:16384
	ds_read_b128 v[188:191], v185 offset:17408
	ds_read_b128 v[192:195], v185 offset:18432
	ds_read_b128 v[196:199], v185 offset:19456
	ds_read_b128 v[200:203], v185 offset:20480
	ds_read_b128 v[204:207], v185 offset:21504
	ds_read_b128 v[208:211], v185 offset:22528
	ds_read_b128 v[212:215], v185 offset:23552
	global_load_lds_dwordx4 v156, s[16:17]
	s_add_i32 m0, s33, 0x2000
	s_add_u32 s66, s16, 0x2b0000
	s_addc_u32 s67, s17, 0
	s_add_i32 s33, s41, s24
	global_load_lds_dwordx4 v160, s[16:17]
	s_mov_b32 m0, s33
	s_add_u32 s100, s20, 0x80
	s_addc_u32 s101, s21, 0
	global_load_lds_dwordx4 v156, s[66:67]
	s_add_i32 m0, s33, 0x2000
	s_nop 0
	global_load_lds_dwordx4 v160, s[66:67]
	s_mov_b32 m0, s25
	s_nop 0
	global_load_lds_dwordx4 v154, s[20:21]
	s_mov_b32 m0, s26
	s_nop 0
	global_load_lds_dwordx4 v158, s[20:21]
	s_waitcnt vmcnt(8)
	s_waitcnt lgkmcnt(0)
	s_barrier
	s_waitcnt lgkmcnt(0)
	v_mfma_f32_16x16x32_bf16 v[58:61], v[130:133], v[180:183], v[58:61]
	v_mfma_f32_16x16x32_bf16 v[58:61], v[134:137], v[188:191], v[58:61]
	v_mfma_f32_16x16x32_bf16 v[54:57], v[142:145], v[188:191], v[54:57]
	v_mfma_f32_16x16x32_bf16 v[54:57], v[138:141], v[180:183], v[54:57]
	v_mfma_f32_16x16x32_bf16 v[62:65], v[146:149], v[180:183], v[62:65]
	v_mfma_f32_16x16x32_bf16 v[62:65], v[150:153], v[188:191], v[62:65]
	v_mfma_f32_16x16x32_bf16 v[50:53], v[176:179], v[188:191], v[50:53]
	v_mfma_f32_16x16x32_bf16 v[50:53], v[172:175], v[180:183], v[50:53]
	v_mfma_f32_16x16x32_bf16 v[38:41], v[172:175], v[192:195], v[38:41]
	v_mfma_f32_16x16x32_bf16 v[38:41], v[176:179], v[196:199], v[38:41]
	v_mfma_f32_16x16x32_bf16 v[46:49], v[150:153], v[196:199], v[46:49]
	v_mfma_f32_16x16x32_bf16 v[46:49], v[146:149], v[192:195], v[46:49]
	v_mfma_f32_16x16x32_bf16 v[34:37], v[138:141], v[192:195], v[34:37]
	v_mfma_f32_16x16x32_bf16 v[34:37], v[142:145], v[196:199], v[34:37]
	v_mfma_f32_16x16x32_bf16 v[42:45], v[134:137], v[196:199], v[42:45]
	v_mfma_f32_16x16x32_bf16 v[42:45], v[130:133], v[192:195], v[42:45]
	v_mfma_f32_16x16x32_bf16 v[26:29], v[130:133], v[200:203], v[26:29]
	v_mfma_f32_16x16x32_bf16 v[26:29], v[134:137], v[204:207], v[26:29]
	v_mfma_f32_16x16x32_bf16 v[18:21], v[142:145], v[204:207], v[18:21]
	v_mfma_f32_16x16x32_bf16 v[18:21], v[138:141], v[200:203], v[18:21]
	v_mfma_f32_16x16x32_bf16 v[30:33], v[146:149], v[200:203], v[30:33]
	v_mfma_f32_16x16x32_bf16 v[30:33], v[150:153], v[204:207], v[30:33]
	v_mfma_f32_16x16x32_bf16 v[22:25], v[176:179], v[204:207], v[22:25]
	v_mfma_f32_16x16x32_bf16 v[22:25], v[172:175], v[200:203], v[22:25]
	v_mfma_f32_16x16x32_bf16 v[14:17], v[172:175], v[208:211], v[14:17]
	v_mfma_f32_16x16x32_bf16 v[14:17], v[176:179], v[212:215], v[14:17]
	v_mfma_f32_16x16x32_bf16 v[10:13], v[150:153], v[212:215], v[10:13]
	v_mfma_f32_16x16x32_bf16 v[10:13], v[146:149], v[208:211], v[10:13]
	v_mfma_f32_16x16x32_bf16 v[2:5], v[138:141], v[208:211], v[2:5]
	v_mfma_f32_16x16x32_bf16 v[2:5], v[142:145], v[212:215], v[2:5]
	v_mfma_f32_16x16x32_bf16 v[6:9], v[134:137], v[212:215], v[6:9]
	v_mfma_f32_16x16x32_bf16 v[6:9], v[130:133], v[208:211], v[6:9]
	s_barrier
; #define PG8_STAGE(bufoff, gbase, voff) do { _Pragma("unroll") for (int _i = 0; _i < 2; ++_i) \
;         __builtin_amdgcn_global_load_lds((const unsigned*)((const char*)(gbase) + (voff)[_i]), (PG8_LAS unsigned*)(lds + (bufoff) + ldsw + _i * 8192), 16, 0, 0); } while (0)
; #define PG8_LDA(dst, b, h) do { _Pragma("unroll") for (int m = 0; m < 4; ++m) _Pragma("unroll") for (int k = 0; k < 2; ++k) dst[m][k] = *(const PG8_LAS bf16x8*)(lds + PG8_SA(b, h) + aoff + m * 2048 + k * 1024); } while (0)
; #define PG8_LDB(dst, b, h) do { _Pragma("unroll") for (int n = 0; n < 2; ++n) _Pragma("unroll") for (int k = 0; k < 2; ++k) dst[n][k] = *(const PG8_LAS bf16x8*)(lds + PG8_SB(b, h) + boff + n * 2048 + k * 1024); } while (0)
; #define PG8_MMA(ai, bj, At, Bt) do { __builtin_amdgcn_s_setprio(1); _Pragma("unroll") for (int m = 0; m < 4; ++m) _Pragma("unroll") for (int n = 0; n < 2; ++n) _Pragma("unroll") for (int k = 0; k < 2; ++k) \
;         acc[ai][bj][m][n] = __builtin_amdgcn_mfma_f32_16x16x32_bf16(Bt[n][k], At[m][k], acc[ai][bj][m][n], 0, 0, 0); __builtin_amdgcn_s_setprio(0); } while (0)
; #define PG8_WAIT_V(n) asm volatile("s_waitcnt vmcnt(" #n ")" ::: "memory")
; #define PG8_WAIT_L(n) asm volatile("s_waitcnt lgkmcnt(" #n ")" ::: "memory")
; #define PG8_BAR __builtin_amdgcn_s_barrier()
; #define PG8_SCHED __builtin_amdgcn_sched_barrier(0)
; template <class Epi, class Sched, bool ALIGN_EPI = false, bool SP2 = false>
; __device__ __forceinline__ void gemm_phase(PG8_LAS unsigned char* lds, const Gemm g, const Sched& S, const Epi& E) {
;     ...
;         for (int t = 0; t < nt; t += 2) {
;             const bool last = (t == nt - 2);
;             const char* a1 = cA + (size_t)(t + 1) * kstep;
;             const char* a2 = last ? nA : cA + (size_t)(t + 2) * kstep; const char* b2 = last ? nB : cB + (size_t)(t + 2) * kstep;
;     ...
;             PG8_LDB(B0, 1, 0); PG8_LDB(B1, 1, 1); PG8_SCHED; PG8_LDA(At, 1, 0); PG8_STAGE(PG8_SA(0, 1), a2 + hstep, voffA);
;             PG8_WAIT_V(8); PG8_WAIT_L(0); PG8_BAR; PG8_MMA(0, 0, At, B0); PG8_MMA(0, 1, At, B1); PG8_BAR; PG8_SCHED;
;             PG8_LDA(At, 1, 1); PG8_STAGE(PG8_SB(1, 0), b3, voffB); PG8_STAGE(PG8_SB(1, 1), b3 + hstep, voffB); PG8_STAGE(PG8_SA(1, 0), a3, voffA);
;             PG8_WAIT_V(8); PG8_WAIT_L(0); PG8_BAR; PG8_MMA(1, 0, At, B0); PG8_MMA(1, 1, At, B1); PG8_BAR; PG8_SCHED;
	s_add_i32 s33, 0, 0x18000
	s_add_i32 s42, 0, 0x1c000
	ds_read_b128 v[130:133], v241 offset:32768
	ds_read_b128 v[134:137], v241 offset:33792
	ds_read_b128 v[138:141], v241 offset:34816
	ds_read_b128 v[142:145], v241 offset:35840
	ds_read_b128 v[146:149], v241 offset:49152
	ds_read_b128 v[150:153], v241 offset:50176
	ds_read_b128 v[172:175], v241 offset:51200
	ds_read_b128 v[176:179], v241 offset:52224
	s_add_u32 s20, s20, 0x2b0000
	s_addc_u32 s21, s21, 0
	s_mov_b32 m0, s27
	ds_read_b128 v[180:183], v185 offset:32768
	ds_read_b128 v[188:191], v185 offset:33792
	ds_read_b128 v[192:195], v185 offset:34816
	ds_read_b128 v[196:199], v185 offset:35840
	ds_read_b128 v[200:203], v185 offset:36864
	ds_read_b128 v[204:207], v185 offset:37888
	ds_read_b128 v[208:211], v185 offset:38912
	ds_read_b128 v[212:215], v185 offset:39936
	global_load_lds_dwordx4 v154, s[20:21]
	s_mov_b32 m0, s28
	s_nop 0
	global_load_lds_dwordx4 v158, s[20:21]
	s_waitcnt vmcnt(8)
	s_waitcnt lgkmcnt(0)
	s_barrier
	s_waitcnt lgkmcnt(0)
	v_mfma_f32_16x16x32_bf16 v[114:117], v[130:133], v[180:183], v[114:117]
	v_mfma_f32_16x16x32_bf16 v[114:117], v[134:137], v[188:191], v[114:117]
	v_mfma_f32_16x16x32_bf16 v[118:121], v[142:145], v[188:191], v[118:121]
	v_mfma_f32_16x16x32_bf16 v[118:121], v[138:141], v[180:183], v[118:121]
	v_mfma_f32_16x16x32_bf16 v[122:125], v[146:149], v[180:183], v[122:125]
	v_mfma_f32_16x16x32_bf16 v[122:125], v[150:153], v[188:191], v[122:125]
	v_mfma_f32_16x16x32_bf16 v[126:129], v[176:179], v[188:191], v[126:129]
	v_mfma_f32_16x16x32_bf16 v[126:129], v[172:175], v[180:183], v[126:129]
	v_mfma_f32_16x16x32_bf16 v[102:105], v[172:175], v[192:195], v[102:105]
	v_mfma_f32_16x16x32_bf16 v[102:105], v[176:179], v[196:199], v[102:105]
	v_mfma_f32_16x16x32_bf16 v[110:113], v[150:153], v[196:199], v[110:113]
	v_mfma_f32_16x16x32_bf16 v[110:113], v[146:149], v[192:195], v[110:113]
	v_mfma_f32_16x16x32_bf16 v[98:101], v[138:141], v[192:195], v[98:101]
	v_mfma_f32_16x16x32_bf16 v[98:101], v[142:145], v[196:199], v[98:101]
	v_mfma_f32_16x16x32_bf16 v[106:109], v[134:137], v[196:199], v[106:109]
	v_mfma_f32_16x16x32_bf16 v[106:109], v[130:133], v[192:195], v[106:109]
	v_mfma_f32_16x16x32_bf16 v[90:93], v[130:133], v[200:203], v[90:93]
	v_mfma_f32_16x16x32_bf16 v[90:93], v[134:137], v[204:207], v[90:93]
	v_mfma_f32_16x16x32_bf16 v[82:85], v[142:145], v[204:207], v[82:85]
	v_mfma_f32_16x16x32_bf16 v[82:85], v[138:141], v[200:203], v[82:85]
	v_mfma_f32_16x16x32_bf16 v[94:97], v[146:149], v[200:203], v[94:97]
	v_mfma_f32_16x16x32_bf16 v[94:97], v[150:153], v[204:207], v[94:97]
	v_mfma_f32_16x16x32_bf16 v[86:89], v[176:179], v[204:207], v[86:89]
	v_mfma_f32_16x16x32_bf16 v[86:89], v[172:175], v[200:203], v[86:89]
	v_mfma_f32_16x16x32_bf16 v[70:73], v[172:175], v[208:211], v[70:73]
	v_mfma_f32_16x16x32_bf16 v[70:73], v[176:179], v[212:215], v[70:73]
	v_mfma_f32_16x16x32_bf16 v[78:81], v[150:153], v[212:215], v[78:81]
	v_mfma_f32_16x16x32_bf16 v[78:81], v[146:149], v[208:211], v[78:81]
	v_mfma_f32_16x16x32_bf16 v[66:69], v[138:141], v[208:211], v[66:69]
	v_mfma_f32_16x16x32_bf16 v[66:69], v[142:145], v[212:215], v[66:69]
	v_mfma_f32_16x16x32_bf16 v[74:77], v[134:137], v[212:215], v[74:77]
	v_mfma_f32_16x16x32_bf16 v[74:77], v[130:133], v[208:211], v[74:77]
	s_barrier
	s_add_i32 s20, s33, s24
	s_add_i32 m0, s20, 0xffffff80
	ds_read_b128 v[180:183], v185 offset:49152
	ds_read_b128 v[188:191], v185 offset:50176
	ds_read_b128 v[192:195], v185 offset:51200
	ds_read_b128 v[196:199], v185 offset:52224
	ds_read_b128 v[200:203], v185 offset:53248
	ds_read_b128 v[204:207], v185 offset:54272
	ds_read_b128 v[208:211], v185 offset:55296
	ds_read_b128 v[212:215], v185 offset:56320
	global_load_lds_dwordx4 v156, s[16:17] offset:128
	s_add_i32 m0, s20, 0x1f80
	s_add_i32 s20, s42, s24
	global_load_lds_dwordx4 v160, s[16:17] offset:128
	s_add_u32 s16, s16, 0x2b0080
	s_addc_u32 s17, s17, 0
	s_mov_b32 m0, s20
	s_nop 0
	global_load_lds_dwordx4 v156, s[16:17]
	s_add_i32 m0, s20, 0x2000
	s_nop 0
	global_load_lds_dwordx4 v160, s[16:17]
	s_mov_b32 m0, s34
	s_nop 0
	global_load_lds_dwordx4 v154, s[100:101]
	s_mov_b32 m0, s35
	s_nop 0
	global_load_lds_dwordx4 v158, s[100:101]
	s_waitcnt vmcnt(8)
	s_waitcnt lgkmcnt(0)
	s_barrier
	s_waitcnt lgkmcnt(0)
	v_mfma_f32_16x16x32_bf16 v[58:61], v[130:133], v[180:183], v[58:61]
	v_mfma_f32_16x16x32_bf16 v[58:61], v[134:137], v[188:191], v[58:61]
	v_mfma_f32_16x16x32_bf16 v[54:57], v[142:145], v[188:191], v[54:57]
	v_mfma_f32_16x16x32_bf16 v[54:57], v[138:141], v[180:183], v[54:57]
	v_mfma_f32_16x16x32_bf16 v[62:65], v[146:149], v[180:183], v[62:65]
	v_mfma_f32_16x16x32_bf16 v[62:65], v[150:153], v[188:191], v[62:65]
	v_mfma_f32_16x16x32_bf16 v[50:53], v[176:179], v[188:191], v[50:53]
	v_mfma_f32_16x16x32_bf16 v[50:53], v[172:175], v[180:183], v[50:53]
	v_mfma_f32_16x16x32_bf16 v[38:41], v[172:175], v[192:195], v[38:41]
	v_mfma_f32_16x16x32_bf16 v[38:41], v[176:179], v[196:199], v[38:41]
	v_mfma_f32_16x16x32_bf16 v[46:49], v[150:153], v[196:199], v[46:49]
	v_mfma_f32_16x16x32_bf16 v[46:49], v[146:149], v[192:195], v[46:49]
	v_mfma_f32_16x16x32_bf16 v[34:37], v[138:141], v[192:195], v[34:37]
	v_mfma_f32_16x16x32_bf16 v[34:37], v[142:145], v[196:199], v[34:37]
	v_mfma_f32_16x16x32_bf16 v[42:45], v[134:137], v[196:199], v[42:45]
	v_mfma_f32_16x16x32_bf16 v[42:45], v[130:133], v[192:195], v[42:45]
	v_mfma_f32_16x16x32_bf16 v[26:29], v[130:133], v[200:203], v[26:29]
	v_mfma_f32_16x16x32_bf16 v[26:29], v[134:137], v[204:207], v[26:29]
	v_mfma_f32_16x16x32_bf16 v[18:21], v[142:145], v[204:207], v[18:21]
	v_mfma_f32_16x16x32_bf16 v[18:21], v[138:141], v[200:203], v[18:21]
	v_mfma_f32_16x16x32_bf16 v[30:33], v[146:149], v[200:203], v[30:33]
	v_mfma_f32_16x16x32_bf16 v[30:33], v[150:153], v[204:207], v[30:33]
	v_mfma_f32_16x16x32_bf16 v[22:25], v[176:179], v[204:207], v[22:25]
	v_mfma_f32_16x16x32_bf16 v[22:25], v[172:175], v[200:203], v[22:25]
	v_mfma_f32_16x16x32_bf16 v[14:17], v[172:175], v[208:211], v[14:17]
	v_mfma_f32_16x16x32_bf16 v[14:17], v[176:179], v[212:215], v[14:17]
	v_mfma_f32_16x16x32_bf16 v[10:13], v[150:153], v[212:215], v[10:13]
	v_mfma_f32_16x16x32_bf16 v[10:13], v[146:149], v[208:211], v[10:13]
	v_mfma_f32_16x16x32_bf16 v[2:5], v[138:141], v[208:211], v[2:5]
	v_mfma_f32_16x16x32_bf16 v[2:5], v[142:145], v[212:215], v[2:5]
	v_mfma_f32_16x16x32_bf16 v[6:9], v[134:137], v[212:215], v[6:9]
	v_mfma_f32_16x16x32_bf16 v[6:9], v[130:133], v[208:211], v[6:9]
	s_barrier
	s_add_i32 s64, s64, 2
	s_add_u32 s18, s18, 0x100
	s_addc_u32 s19, s19, 0
	s_add_u32 s62, s62, 0x100
	s_addc_u32 s63, s63, 0
	s_cmpk_gt_u32 s64, 0xa9
	s_cbranch_scc0 .LBB0_1245
	s_and_b64 vcc, exec, s[12:13]
	s_cbranch_vccz .LBB0_1248
	s_barrier

; #define PG8_STAGE(bufoff, gbase, voff) do { _Pragma("unroll") for (int _i = 0; _i < 2; ++_i) \
;         __builtin_amdgcn_global_load_lds((const unsigned*)((const char*)(gbase) + (voff)[_i]), (PG8_LAS unsigned*)(lds + (bufoff) + ldsw + _i * 8192), 16, 0, 0); } while (0)
; #define PG8_LDA(dst, b, h) do { _Pragma("unroll") for (int m = 0; m < 4; ++m) _Pragma("unroll") for (int k = 0; k < 2; ++k) dst[m][k] = *(const PG8_LAS bf16x8*)(lds + PG8_SA(b, h) + aoff + m * 2048 + k * 1024); } while (0)
; #define PG8_LDB(dst, b, h) do { _Pragma("unroll") for (int n = 0; n < 2; ++n) _Pragma("unroll") for (int k = 0; k < 2; ++k) dst[n][k] = *(const PG8_LAS bf16x8*)(lds + PG8_SB(b, h) + boff + n * 2048 + k * 1024); } while (0)
; #define PG8_MMA(ai, bj, At, Bt) do { __builtin_amdgcn_s_setprio(1); _Pragma("unroll") for (int m = 0; m < 4; ++m) _Pragma("unroll") for (int n = 0; n < 2; ++n) _Pragma("unroll") for (int k = 0; k < 2; ++k) \
;         acc[ai][bj][m][n] = __builtin_amdgcn_mfma_f32_16x16x32_bf16(Bt[n][k], At[m][k], acc[ai][bj][m][n], 0, 0, 0); __builtin_amdgcn_s_setprio(0); } while (0)
; #define PG8_WAIT_V(n) asm volatile("s_waitcnt vmcnt(" #n ")" ::: "memory")
; #define PG8_BAR __builtin_amdgcn_s_barrier()
; template <class Epi, class Sched, bool ALIGN_EPI = false, bool SP2 = false>
; __device__ __forceinline__ void gemm_phase(PG8_LAS unsigned char* lds, const Gemm g, const Sched& S, const Epi& E) {
;     ...
;         for (int t = 0; t < nt; t += 2) {
;             const bool last = (t == nt - 2);
;             const char* a1 = cA + (size_t)(t + 1) * kstep;
;             const char* a2 = last ? nA : cA + (size_t)(t + 2) * kstep; const char* b2 = last ? nB : cB + (size_t)(t + 2) * kstep;
;             const char* a3 = a2 + kstep; const char* b3 = b2 + kstep;
;             if (last && has_next) S.a_ready(nxt);
;             if constexpr (SP2) {
;             PG8_LDB(B0, 0, 0); PG8_LDB(B1, 0, 1); PG8_SCHED; PG8_LDA(At, 0, 0); PG8_STAGE(PG8_SA(1, 1), a1 + hstep, voffA);
;             PG8_WAIT_V(8); PG8_WAIT_L(0); PG8_BAR; PG8_MMA(0, 0, At, B0); PG8_MMA(0, 1, At, B1); PG8_BAR; PG8_SCHED;
;             PG8_LDA(At, 0, 1); PG8_STAGE(PG8_SB(0, 0), b2, voffB); PG8_STAGE(PG8_SB(0, 1), b2 + hstep, voffB); PG8_STAGE(PG8_SA(0, 0), a2, voffA);
;             PG8_WAIT_V(8); PG8_WAIT_L(0); PG8_BAR; PG8_MMA(1, 0, At, B0); PG8_MMA(1, 1, At, B1); PG8_BAR; PG8_SCHED;
.LBB0_1332:
	ds_read_b128 v[148:151], v241 offset:0
	ds_read_b128 v[156:159], v241 offset:1024
	ds_read_b128 v[166:169], v241 offset:2048
	ds_read_b128 v[170:173], v241 offset:3072
	ds_read_b128 v[174:177], v241 offset:16384
	ds_read_b128 v[178:181], v241 offset:17408
	ds_read_b128 v[182:185], v241 offset:18432
	ds_read_b128 v[186:189], v241 offset:19456
	s_add_u32 s20, s22, 0xfff00080
	s_addc_u32 s21, s23, -1
	s_cmp_eq_u32 s67, 60
	s_cselect_b32 s25, s13, s21
	s_cselect_b32 s24, s63, s20
	s_cselect_b32 s21, s11, s66
	s_cselect_b32 s20, s64, s65
	s_add_i32 m0, s19, 0xc000
	ds_read_b128 v[190:193], v155
	ds_read_b128 v[194:197], v155 offset:1024
	ds_read_b128 v[198:201], v155 offset:2048
	ds_read_b128 v[202:205], v155 offset:3072
	ds_read_b128 v[206:209], v155 offset:4096
	ds_read_b128 v[210:213], v155 offset:5120
	ds_read_b128 v[214:217], v155 offset:6144
	ds_read_b128 v[218:221], v155 offset:7168
	global_load_lds_dwordx4 v138, s[22:23]
	s_add_i32 m0, s19, 0xe000
	s_nop 0
	global_load_lds_dwordx4 v140, s[22:23]
	s_waitcnt vmcnt(8)
	s_waitcnt lgkmcnt(0)
	s_barrier
	s_waitcnt lgkmcnt(0)
	v_mfma_f32_16x16x32_bf16 v[118:121], v[148:151], v[190:193], v[118:121]
	v_mfma_f32_16x16x32_bf16 v[118:121], v[156:159], v[194:197], v[118:121]
	v_mfma_f32_16x16x32_bf16 v[114:117], v[170:173], v[194:197], v[114:117]
	v_mfma_f32_16x16x32_bf16 v[114:117], v[166:169], v[190:193], v[114:117]
	v_mfma_f32_16x16x32_bf16 v[126:129], v[174:177], v[190:193], v[126:129]
	v_mfma_f32_16x16x32_bf16 v[126:129], v[178:181], v[194:197], v[126:129]
	v_mfma_f32_16x16x32_bf16 v[122:125], v[186:189], v[194:197], v[122:125]
	v_mfma_f32_16x16x32_bf16 v[122:125], v[182:185], v[190:193], v[122:125]
	v_mfma_f32_16x16x32_bf16 v[106:109], v[182:185], v[198:201], v[106:109]
	v_mfma_f32_16x16x32_bf16 v[106:109], v[186:189], v[202:205], v[106:109]
	v_mfma_f32_16x16x32_bf16 v[110:113], v[178:181], v[202:205], v[110:113]
	v_mfma_f32_16x16x32_bf16 v[110:113], v[174:177], v[198:201], v[110:113]
	v_mfma_f32_16x16x32_bf16 v[98:101], v[166:169], v[198:201], v[98:101]
	v_mfma_f32_16x16x32_bf16 v[98:101], v[170:173], v[202:205], v[98:101]
	v_mfma_f32_16x16x32_bf16 v[102:105], v[156:159], v[202:205], v[102:105]
	v_mfma_f32_16x16x32_bf16 v[102:105], v[148:151], v[198:201], v[102:105]
	v_mfma_f32_16x16x32_bf16 v[86:89], v[148:151], v[206:209], v[86:89]
	v_mfma_f32_16x16x32_bf16 v[86:89], v[156:159], v[210:213], v[86:89]
	v_mfma_f32_16x16x32_bf16 v[82:85], v[170:173], v[210:213], v[82:85]
	v_mfma_f32_16x16x32_bf16 v[82:85], v[166:169], v[206:209], v[82:85]
	v_mfma_f32_16x16x32_bf16 v[94:97], v[174:177], v[206:209], v[94:97]
	v_mfma_f32_16x16x32_bf16 v[94:97], v[178:181], v[210:213], v[94:97]
	v_mfma_f32_16x16x32_bf16 v[90:93], v[186:189], v[210:213], v[90:93]
	v_mfma_f32_16x16x32_bf16 v[90:93], v[182:185], v[206:209], v[90:93]
	v_mfma_f32_16x16x32_bf16 v[74:77], v[182:185], v[214:217], v[74:77]
	v_mfma_f32_16x16x32_bf16 v[74:77], v[186:189], v[218:221], v[74:77]
	v_mfma_f32_16x16x32_bf16 v[78:81], v[178:181], v[218:221], v[78:81]
	v_mfma_f32_16x16x32_bf16 v[78:81], v[174:177], v[214:217], v[78:81]
	v_mfma_f32_16x16x32_bf16 v[66:69], v[166:169], v[214:217], v[66:69]
	v_mfma_f32_16x16x32_bf16 v[66:69], v[170:173], v[218:221], v[66:69]
	v_mfma_f32_16x16x32_bf16 v[70:73], v[156:159], v[218:221], v[70:73]
	v_mfma_f32_16x16x32_bf16 v[70:73], v[148:151], v[214:217], v[70:73]
	s_barrier
	s_add_i32 s33, s47, s28
	s_mov_b32 m0, s33
	ds_read_b128 v[190:193], v155 offset:16384
	ds_read_b128 v[194:197], v155 offset:17408
	ds_read_b128 v[198:201], v155 offset:18432
	ds_read_b128 v[202:205], v155 offset:19456
	ds_read_b128 v[206:209], v155 offset:20480
	ds_read_b128 v[210:213], v155 offset:21504
	ds_read_b128 v[214:217], v155 offset:22528
	ds_read_b128 v[218:221], v155 offset:23552
	global_load_lds_dwordx4 v132, s[20:21]
	s_add_i32 m0, s33, 0x2000
	s_add_u32 s68, s20, 0x100000
	s_addc_u32 s69, s21, 0
	s_add_i32 s33, s52, s28
	global_load_lds_dwordx4 v136, s[20:21]
	s_mov_b32 m0, s33
	s_add_u32 s100, s24, 0x80
	s_addc_u32 s101, s25, 0
	global_load_lds_dwordx4 v132, s[68:69]
	s_add_i32 m0, s33, 0x2000
	s_nop 0
	global_load_lds_dwordx4 v136, s[68:69]
	s_mov_b32 m0, s19
	s_nop 0
	global_load_lds_dwordx4 v130, s[24:25]
	s_mov_b32 m0, s35
	s_nop 0
	global_load_lds_dwordx4 v134, s[24:25]
	s_waitcnt vmcnt(8)
	s_waitcnt lgkmcnt(0)
	s_barrier
	s_waitcnt lgkmcnt(0)
	v_mfma_f32_16x16x32_bf16 v[54:57], v[148:151], v[190:193], v[54:57]
	v_mfma_f32_16x16x32_bf16 v[54:57], v[156:159], v[194:197], v[54:57]
	v_mfma_f32_16x16x32_bf16 v[50:53], v[170:173], v[194:197], v[50:53]
	v_mfma_f32_16x16x32_bf16 v[50:53], v[166:169], v[190:193], v[50:53]
	v_mfma_f32_16x16x32_bf16 v[62:65], v[174:177], v[190:193], v[62:65]
	v_mfma_f32_16x16x32_bf16 v[62:65], v[178:181], v[194:197], v[62:65]
	v_mfma_f32_16x16x32_bf16 v[58:61], v[186:189], v[194:197], v[58:61]
	v_mfma_f32_16x16x32_bf16 v[58:61], v[182:185], v[190:193], v[58:61]
	v_mfma_f32_16x16x32_bf16 v[42:45], v[182:185], v[198:201], v[42:45]
	v_mfma_f32_16x16x32_bf16 v[42:45], v[186:189], v[202:205], v[42:45]
	v_mfma_f32_16x16x32_bf16 v[46:49], v[178:181], v[202:205], v[46:49]
	v_mfma_f32_16x16x32_bf16 v[46:49], v[174:177], v[198:201], v[46:49]
	v_mfma_f32_16x16x32_bf16 v[34:37], v[166:169], v[198:201], v[34:37]
	v_mfma_f32_16x16x32_bf16 v[34:37], v[170:173], v[202:205], v[34:37]
	v_mfma_f32_16x16x32_bf16 v[38:41], v[156:159], v[202:205], v[38:41]
	v_mfma_f32_16x16x32_bf16 v[38:41], v[148:151], v[198:201], v[38:41]
	v_mfma_f32_16x16x32_bf16 v[22:25], v[148:151], v[206:209], v[22:25]
	v_mfma_f32_16x16x32_bf16 v[22:25], v[156:159], v[210:213], v[22:25]
	v_mfma_f32_16x16x32_bf16 v[18:21], v[170:173], v[210:213], v[18:21]
	v_mfma_f32_16x16x32_bf16 v[18:21], v[166:169], v[206:209], v[18:21]
	v_mfma_f32_16x16x32_bf16 v[30:33], v[174:177], v[206:209], v[30:33]
	v_mfma_f32_16x16x32_bf16 v[30:33], v[178:181], v[210:213], v[30:33]
	v_mfma_f32_16x16x32_bf16 v[26:29], v[186:189], v[210:213], v[26:29]
	v_mfma_f32_16x16x32_bf16 v[26:29], v[182:185], v[206:209], v[26:29]
	v_mfma_f32_16x16x32_bf16 v[14:17], v[182:185], v[214:217], v[14:17]
	v_mfma_f32_16x16x32_bf16 v[14:17], v[186:189], v[218:221], v[14:17]
	v_mfma_f32_16x16x32_bf16 v[10:13], v[178:181], v[218:221], v[10:13]
	v_mfma_f32_16x16x32_bf16 v[10:13], v[174:177], v[214:217], v[10:13]
	v_mfma_f32_16x16x32_bf16 v[2:5], v[166:169], v[214:217], v[2:5]
	v_mfma_f32_16x16x32_bf16 v[2:5], v[170:173], v[218:221], v[2:5]
	v_mfma_f32_16x16x32_bf16 v[6:9], v[156:159], v[218:221], v[6:9]
	v_mfma_f32_16x16x32_bf16 v[6:9], v[148:151], v[214:217], v[6:9]
	s_barrier
; #define PG8_STAGE(bufoff, gbase, voff) do { _Pragma("unroll") for (int _i = 0; _i < 2; ++_i) \
;         __builtin_amdgcn_global_load_lds((const unsigned*)((const char*)(gbase) + (voff)[_i]), (PG8_LAS unsigned*)(lds + (bufoff) + ldsw + _i * 8192), 16, 0, 0); } while (0)
; #define PG8_LDA(dst, b, h) do { _Pragma("unroll") for (int m = 0; m < 4; ++m) _Pragma("unroll") for (int k = 0; k < 2; ++k) dst[m][k] = *(const PG8_LAS bf16x8*)(lds + PG8_SA(b, h) + aoff + m * 2048 + k * 1024); } while (0)
; #define PG8_LDB(dst, b, h) do { _Pragma("unroll") for (int n = 0; n < 2; ++n) _Pragma("unroll") for (int k = 0; k < 2; ++k) dst[n][k] = *(const PG8_LAS bf16x8*)(lds + PG8_SB(b, h) + boff + n * 2048 + k * 1024); } while (0)
; #define PG8_MMA(ai, bj, At, Bt) do { __builtin_amdgcn_s_setprio(1); _Pragma("unroll") for (int m = 0; m < 4; ++m) _Pragma("unroll") for (int n = 0; n < 2; ++n) _Pragma("unroll") for (int k = 0; k < 2; ++k) \
;         acc[ai][bj][m][n] = __builtin_amdgcn_mfma_f32_16x16x32_bf16(Bt[n][k], At[m][k], acc[ai][bj][m][n], 0, 0, 0); __builtin_amdgcn_s_setprio(0); } while (0)
; #define PG8_WAIT_V(n) asm volatile("s_waitcnt vmcnt(" #n ")" ::: "memory")
; #define PG8_WAIT_L(n) asm volatile("s_waitcnt lgkmcnt(" #n ")" ::: "memory")
; #define PG8_BAR __builtin_amdgcn_s_barrier()
; #define PG8_SCHED __builtin_amdgcn_sched_barrier(0)
; template <class Epi, class Sched, bool ALIGN_EPI = false, bool SP2 = false>
; __device__ __forceinline__ void gemm_phase(PG8_LAS unsigned char* lds, const Gemm g, const Sched& S, const Epi& E) {
;     ...
;         for (int t = 0; t < nt; t += 2) {
;             const bool last = (t == nt - 2);
;             const char* a1 = cA + (size_t)(t + 1) * kstep;
;             const char* a2 = last ? nA : cA + (size_t)(t + 2) * kstep; const char* b2 = last ? nB : cB + (size_t)(t + 2) * kstep;
;     ...
;             PG8_LDB(B0, 1, 0); PG8_LDB(B1, 1, 1); PG8_SCHED; PG8_LDA(At, 1, 0); PG8_STAGE(PG8_SA(0, 1), a2 + hstep, voffA);
;             PG8_WAIT_V(8); PG8_WAIT_L(0); PG8_BAR; PG8_MMA(0, 0, At, B0); PG8_MMA(0, 1, At, B1); PG8_BAR; PG8_SCHED;
;             PG8_LDA(At, 1, 1); PG8_STAGE(PG8_SB(1, 0), b3, voffB); PG8_STAGE(PG8_SB(1, 1), b3 + hstep, voffB); PG8_STAGE(PG8_SA(1, 0), a3, voffA);
;             PG8_WAIT_V(8); PG8_WAIT_L(0); PG8_BAR; PG8_MMA(1, 0, At, B0); PG8_MMA(1, 1, At, B1); PG8_BAR; PG8_SCHED;
	s_add_i32 s33, 0, 0x18000
	s_add_i32 s42, 0, 0x1c000
	ds_read_b128 v[148:151], v241 offset:32768
	ds_read_b128 v[156:159], v241 offset:33792
	ds_read_b128 v[166:169], v241 offset:34816
	ds_read_b128 v[170:173], v241 offset:35840
	ds_read_b128 v[174:177], v241 offset:49152
	ds_read_b128 v[178:181], v241 offset:50176
	ds_read_b128 v[182:185], v241 offset:51200
	ds_read_b128 v[186:189], v241 offset:52224
	s_add_u32 s24, s24, 0x100000
	s_addc_u32 s25, s25, 0
	s_mov_b32 m0, s36
	ds_read_b128 v[190:193], v155 offset:32768
	ds_read_b128 v[194:197], v155 offset:33792
	ds_read_b128 v[198:201], v155 offset:34816
	ds_read_b128 v[202:205], v155 offset:35840
	ds_read_b128 v[206:209], v155 offset:36864
	ds_read_b128 v[210:213], v155 offset:37888
	ds_read_b128 v[214:217], v155 offset:38912
	ds_read_b128 v[218:221], v155 offset:39936
	global_load_lds_dwordx4 v130, s[24:25]
	s_mov_b32 m0, s37
	s_nop 0
	global_load_lds_dwordx4 v134, s[24:25]
	s_waitcnt vmcnt(8)
	s_waitcnt lgkmcnt(0)
	s_barrier
	s_waitcnt lgkmcnt(0)
	v_mfma_f32_16x16x32_bf16 v[118:121], v[148:151], v[190:193], v[118:121]
	v_mfma_f32_16x16x32_bf16 v[118:121], v[156:159], v[194:197], v[118:121]
	v_mfma_f32_16x16x32_bf16 v[114:117], v[170:173], v[194:197], v[114:117]
	v_mfma_f32_16x16x32_bf16 v[114:117], v[166:169], v[190:193], v[114:117]
	v_mfma_f32_16x16x32_bf16 v[126:129], v[174:177], v[190:193], v[126:129]
	v_mfma_f32_16x16x32_bf16 v[126:129], v[178:181], v[194:197], v[126:129]
	v_mfma_f32_16x16x32_bf16 v[122:125], v[186:189], v[194:197], v[122:125]
	v_mfma_f32_16x16x32_bf16 v[122:125], v[182:185], v[190:193], v[122:125]
	v_mfma_f32_16x16x32_bf16 v[106:109], v[182:185], v[198:201], v[106:109]
	v_mfma_f32_16x16x32_bf16 v[106:109], v[186:189], v[202:205], v[106:109]
	v_mfma_f32_16x16x32_bf16 v[110:113], v[178:181], v[202:205], v[110:113]
	v_mfma_f32_16x16x32_bf16 v[110:113], v[174:177], v[198:201], v[110:113]
	v_mfma_f32_16x16x32_bf16 v[98:101], v[166:169], v[198:201], v[98:101]
	v_mfma_f32_16x16x32_bf16 v[98:101], v[170:173], v[202:205], v[98:101]
	v_mfma_f32_16x16x32_bf16 v[102:105], v[156:159], v[202:205], v[102:105]
	v_mfma_f32_16x16x32_bf16 v[102:105], v[148:151], v[198:201], v[102:105]
	v_mfma_f32_16x16x32_bf16 v[86:89], v[148:151], v[206:209], v[86:89]
	v_mfma_f32_16x16x32_bf16 v[86:89], v[156:159], v[210:213], v[86:89]
	v_mfma_f32_16x16x32_bf16 v[82:85], v[170:173], v[210:213], v[82:85]
	v_mfma_f32_16x16x32_bf16 v[82:85], v[166:169], v[206:209], v[82:85]
	v_mfma_f32_16x16x32_bf16 v[94:97], v[174:177], v[206:209], v[94:97]
	v_mfma_f32_16x16x32_bf16 v[94:97], v[178:181], v[210:213], v[94:97]
	v_mfma_f32_16x16x32_bf16 v[90:93], v[186:189], v[210:213], v[90:93]
	v_mfma_f32_16x16x32_bf16 v[90:93], v[182:185], v[206:209], v[90:93]
	v_mfma_f32_16x16x32_bf16 v[74:77], v[182:185], v[214:217], v[74:77]
	v_mfma_f32_16x16x32_bf16 v[74:77], v[186:189], v[218:221], v[74:77]
	v_mfma_f32_16x16x32_bf16 v[78:81], v[178:181], v[218:221], v[78:81]
	v_mfma_f32_16x16x32_bf16 v[78:81], v[174:177], v[214:217], v[78:81]
	v_mfma_f32_16x16x32_bf16 v[66:69], v[166:169], v[214:217], v[66:69]
	v_mfma_f32_16x16x32_bf16 v[66:69], v[170:173], v[218:221], v[66:69]
	v_mfma_f32_16x16x32_bf16 v[70:73], v[156:159], v[218:221], v[70:73]
	v_mfma_f32_16x16x32_bf16 v[70:73], v[148:151], v[214:217], v[70:73]
	s_barrier
	s_add_i32 s24, s33, s28
	s_add_i32 m0, s24, 0xffffff80
	ds_read_b128 v[190:193], v155 offset:49152
	ds_read_b128 v[194:197], v155 offset:50176
	ds_read_b128 v[198:201], v155 offset:51200
	ds_read_b128 v[202:205], v155 offset:52224
	ds_read_b128 v[206:209], v155 offset:53248
	ds_read_b128 v[210:213], v155 offset:54272
	ds_read_b128 v[214:217], v155 offset:55296
	ds_read_b128 v[218:221], v155 offset:56320
	global_load_lds_dwordx4 v132, s[20:21] offset:128
	s_add_i32 m0, s24, 0x1f80
	s_add_i32 s24, s42, s28
	global_load_lds_dwordx4 v136, s[20:21] offset:128
	s_add_u32 s20, s20, 0x100080
	s_addc_u32 s21, s21, 0
	s_mov_b32 m0, s24
	s_nop 0
	global_load_lds_dwordx4 v132, s[20:21]
	s_add_i32 m0, s24, 0x2000
	s_nop 0
	global_load_lds_dwordx4 v136, s[20:21]
	s_mov_b32 m0, s43
	s_nop 0
	global_load_lds_dwordx4 v130, s[100:101]
	s_mov_b32 m0, s46
	s_nop 0
	global_load_lds_dwordx4 v134, s[100:101]
	s_waitcnt vmcnt(8)
	s_waitcnt lgkmcnt(0)
	s_barrier
	s_waitcnt lgkmcnt(0)
	v_mfma_f32_16x16x32_bf16 v[54:57], v[148:151], v[190:193], v[54:57]
	v_mfma_f32_16x16x32_bf16 v[54:57], v[156:159], v[194:197], v[54:57]
	v_mfma_f32_16x16x32_bf16 v[50:53], v[170:173], v[194:197], v[50:53]
	v_mfma_f32_16x16x32_bf16 v[50:53], v[166:169], v[190:193], v[50:53]
	v_mfma_f32_16x16x32_bf16 v[62:65], v[174:177], v[190:193], v[62:65]
	v_mfma_f32_16x16x32_bf16 v[62:65], v[178:181], v[194:197], v[62:65]
	v_mfma_f32_16x16x32_bf16 v[58:61], v[186:189], v[194:197], v[58:61]
	v_mfma_f32_16x16x32_bf16 v[58:61], v[182:185], v[190:193], v[58:61]
	v_mfma_f32_16x16x32_bf16 v[42:45], v[182:185], v[198:201], v[42:45]
	v_mfma_f32_16x16x32_bf16 v[42:45], v[186:189], v[202:205], v[42:45]
	v_mfma_f32_16x16x32_bf16 v[46:49], v[178:181], v[202:205], v[46:49]
	v_mfma_f32_16x16x32_bf16 v[46:49], v[174:177], v[198:201], v[46:49]
	v_mfma_f32_16x16x32_bf16 v[34:37], v[166:169], v[198:201], v[34:37]
	v_mfma_f32_16x16x32_bf16 v[34:37], v[170:173], v[202:205], v[34:37]
	v_mfma_f32_16x16x32_bf16 v[38:41], v[156:159], v[202:205], v[38:41]
	v_mfma_f32_16x16x32_bf16 v[38:41], v[148:151], v[198:201], v[38:41]
	v_mfma_f32_16x16x32_bf16 v[22:25], v[148:151], v[206:209], v[22:25]
	v_mfma_f32_16x16x32_bf16 v[22:25], v[156:159], v[210:213], v[22:25]
	v_mfma_f32_16x16x32_bf16 v[18:21], v[170:173], v[210:213], v[18:21]
	v_mfma_f32_16x16x32_bf16 v[18:21], v[166:169], v[206:209], v[18:21]
	v_mfma_f32_16x16x32_bf16 v[30:33], v[174:177], v[206:209], v[30:33]
	v_mfma_f32_16x16x32_bf16 v[30:33], v[178:181], v[210:213], v[30:33]
	v_mfma_f32_16x16x32_bf16 v[26:29], v[186:189], v[210:213], v[26:29]
	v_mfma_f32_16x16x32_bf16 v[26:29], v[182:185], v[206:209], v[26:29]
	v_mfma_f32_16x16x32_bf16 v[14:17], v[182:185], v[214:217], v[14:17]
	v_mfma_f32_16x16x32_bf16 v[14:17], v[186:189], v[218:221], v[14:17]
	v_mfma_f32_16x16x32_bf16 v[10:13], v[178:181], v[218:221], v[10:13]
	v_mfma_f32_16x16x32_bf16 v[10:13], v[174:177], v[214:217], v[10:13]
	v_mfma_f32_16x16x32_bf16 v[2:5], v[166:169], v[214:217], v[2:5]
	v_mfma_f32_16x16x32_bf16 v[2:5], v[170:173], v[218:221], v[2:5]
	v_mfma_f32_16x16x32_bf16 v[6:9], v[156:159], v[218:221], v[6:9]
	v_mfma_f32_16x16x32_bf16 v[6:9], v[148:151], v[214:217], v[6:9]
	s_barrier
	s_add_i32 s67, s67, 2
	s_add_u32 s22, s22, 0x100
	s_addc_u32 s23, s23, 0
	s_add_u32 s65, s65, 0x100
	s_addc_u32 s66, s66, 0
	s_cmp_gt_u32 s67, 61
	s_cbranch_scc0 .LBB0_1332
	s_and_b64 vcc, exec, s[8:9]
	s_cbranch_vccz .LBB0_1335
	s_barrier

; #define PG8_STAGE(bufoff, gbase, voff) do { _Pragma("unroll") for (int _i = 0; _i < 2; ++_i) \
;         __builtin_amdgcn_global_load_lds((const unsigned*)((const char*)(gbase) + (voff)[_i]), (PG8_LAS unsigned*)(lds + (bufoff) + ldsw + _i * 8192), 16, 0, 0); } while (0)
; #define PG8_LDA(dst, b, h) do { _Pragma("unroll") for (int m = 0; m < 4; ++m) _Pragma("unroll") for (int k = 0; k < 2; ++k) dst[m][k] = *(const PG8_LAS bf16x8*)(lds + PG8_SA(b, h) + aoff + m * 2048 + k * 1024); } while (0)
; #define PG8_LDB(dst, b, h) do { _Pragma("unroll") for (int n = 0; n < 2; ++n) _Pragma("unroll") for (int k = 0; k < 2; ++k) dst[n][k] = *(const PG8_LAS bf16x8*)(lds + PG8_SB(b, h) + boff + n * 2048 + k * 1024); } while (0)
; #define PG8_MMA(ai, bj, At, Bt) do { __builtin_amdgcn_s_setprio(1); _Pragma("unroll") for (int m = 0; m < 4; ++m) _Pragma("unroll") for (int n = 0; n < 2; ++n) _Pragma("unroll") for (int k = 0; k < 2; ++k) \
;         acc[ai][bj][m][n] = __builtin_amdgcn_mfma_f32_16x16x32_bf16(Bt[n][k], At[m][k], acc[ai][bj][m][n], 0, 0, 0); __builtin_amdgcn_s_setprio(0); } while (0)
; #define PG8_WAIT_V(n) asm volatile("s_waitcnt vmcnt(" #n ")" ::: "memory")
; #define PG8_BAR __builtin_amdgcn_s_barrier()
; template <class Epi, class Sched, bool ALIGN_EPI = false, bool SP2 = false>
; __device__ __forceinline__ void gemm_phase(PG8_LAS unsigned char* lds, const Gemm g, const Sched& S, const Epi& E) {
;     ...
;         for (int t = 0; t < nt; t += 2) {
;             const bool last = (t == nt - 2);
;             const char* a1 = cA + (size_t)(t + 1) * kstep;
;             const char* a2 = last ? nA : cA + (size_t)(t + 2) * kstep; const char* b2 = last ? nB : cB + (size_t)(t + 2) * kstep;
;             const char* a3 = a2 + kstep; const char* b3 = b2 + kstep;
;             if (last && has_next) S.a_ready(nxt);
;             if constexpr (SP2) {
;             PG8_LDB(B0, 0, 0); PG8_LDB(B1, 0, 1); PG8_SCHED; PG8_LDA(At, 0, 0); PG8_STAGE(PG8_SA(1, 1), a1 + hstep, voffA);
;             PG8_WAIT_V(8); PG8_WAIT_L(0); PG8_BAR; PG8_MMA(0, 0, At, B0); PG8_MMA(0, 1, At, B1); PG8_BAR; PG8_SCHED;
;             PG8_LDA(At, 0, 1); PG8_STAGE(PG8_SB(0, 0), b2, voffB); PG8_STAGE(PG8_SB(0, 1), b2 + hstep, voffB); PG8_STAGE(PG8_SA(0, 0), a2, voffA);
;             PG8_WAIT_V(8); PG8_WAIT_L(0); PG8_BAR; PG8_MMA(1, 0, At, B0); PG8_MMA(1, 1, At, B1); PG8_BAR; PG8_SCHED;
.LBB0_1595:
	ds_read_b128 v[130:133], v241 offset:0
	ds_read_b128 v[134:137], v241 offset:1024
	ds_read_b128 v[138:141], v241 offset:2048
	ds_read_b128 v[142:145], v241 offset:3072
	ds_read_b128 v[146:149], v241 offset:16384
	ds_read_b128 v[150:153], v241 offset:17408
	ds_read_b128 v[172:175], v241 offset:18432
	ds_read_b128 v[176:179], v241 offset:19456
	s_add_u32 s24, s26, 0xfff00080
	s_addc_u32 s25, s27, -1
	s_cmp_eq_u32 s62, 60
	s_cselect_b32 s29, s15, s25
	s_cselect_b32 s28, s21, s24
	s_cselect_b32 s25, s13, s53
	s_cselect_b32 s24, s51, s52
	s_add_i32 m0, s23, 0xc000
	ds_read_b128 v[180:183], v185
	ds_read_b128 v[188:191], v185 offset:1024
	ds_read_b128 v[192:195], v185 offset:2048
	ds_read_b128 v[196:199], v185 offset:3072
	ds_read_b128 v[200:203], v185 offset:4096
	ds_read_b128 v[204:207], v185 offset:5120
	ds_read_b128 v[208:211], v185 offset:6144
	ds_read_b128 v[212:215], v185 offset:7168
	global_load_lds_dwordx4 v162, s[26:27]
	s_add_i32 m0, s23, 0xe000
	s_nop 0
	global_load_lds_dwordx4 v166, s[26:27]
	s_waitcnt vmcnt(8)
	s_waitcnt lgkmcnt(0)
	s_barrier
	s_waitcnt lgkmcnt(0)
	v_mfma_f32_16x16x32_bf16 v[114:117], v[130:133], v[180:183], v[114:117]
	v_mfma_f32_16x16x32_bf16 v[114:117], v[134:137], v[188:191], v[114:117]
	v_mfma_f32_16x16x32_bf16 v[118:121], v[142:145], v[188:191], v[118:121]
	v_mfma_f32_16x16x32_bf16 v[118:121], v[138:141], v[180:183], v[118:121]
	v_mfma_f32_16x16x32_bf16 v[122:125], v[146:149], v[180:183], v[122:125]
	v_mfma_f32_16x16x32_bf16 v[122:125], v[150:153], v[188:191], v[122:125]
	v_mfma_f32_16x16x32_bf16 v[126:129], v[176:179], v[188:191], v[126:129]
	v_mfma_f32_16x16x32_bf16 v[126:129], v[172:175], v[180:183], v[126:129]
	v_mfma_f32_16x16x32_bf16 v[102:105], v[172:175], v[192:195], v[102:105]
	v_mfma_f32_16x16x32_bf16 v[102:105], v[176:179], v[196:199], v[102:105]
	v_mfma_f32_16x16x32_bf16 v[110:113], v[150:153], v[196:199], v[110:113]
	v_mfma_f32_16x16x32_bf16 v[110:113], v[146:149], v[192:195], v[110:113]
	v_mfma_f32_16x16x32_bf16 v[98:101], v[138:141], v[192:195], v[98:101]
	v_mfma_f32_16x16x32_bf16 v[98:101], v[142:145], v[196:199], v[98:101]
	v_mfma_f32_16x16x32_bf16 v[106:109], v[134:137], v[196:199], v[106:109]
	v_mfma_f32_16x16x32_bf16 v[106:109], v[130:133], v[192:195], v[106:109]
	v_mfma_f32_16x16x32_bf16 v[90:93], v[130:133], v[200:203], v[90:93]
	v_mfma_f32_16x16x32_bf16 v[90:93], v[134:137], v[204:207], v[90:93]
	v_mfma_f32_16x16x32_bf16 v[82:85], v[142:145], v[204:207], v[82:85]
	v_mfma_f32_16x16x32_bf16 v[82:85], v[138:141], v[200:203], v[82:85]
	v_mfma_f32_16x16x32_bf16 v[94:97], v[146:149], v[200:203], v[94:97]
	v_mfma_f32_16x16x32_bf16 v[94:97], v[150:153], v[204:207], v[94:97]
	v_mfma_f32_16x16x32_bf16 v[86:89], v[176:179], v[204:207], v[86:89]
	v_mfma_f32_16x16x32_bf16 v[86:89], v[172:175], v[200:203], v[86:89]
	v_mfma_f32_16x16x32_bf16 v[70:73], v[172:175], v[208:211], v[70:73]
	v_mfma_f32_16x16x32_bf16 v[70:73], v[176:179], v[212:215], v[70:73]
	v_mfma_f32_16x16x32_bf16 v[78:81], v[150:153], v[212:215], v[78:81]
	v_mfma_f32_16x16x32_bf16 v[78:81], v[146:149], v[208:211], v[78:81]
	v_mfma_f32_16x16x32_bf16 v[66:69], v[138:141], v[208:211], v[66:69]
	v_mfma_f32_16x16x32_bf16 v[66:69], v[142:145], v[212:215], v[66:69]
	v_mfma_f32_16x16x32_bf16 v[74:77], v[134:137], v[212:215], v[74:77]
	v_mfma_f32_16x16x32_bf16 v[74:77], v[130:133], v[208:211], v[74:77]
	s_barrier
	s_add_i32 s33, s48, s36
	s_mov_b32 m0, s33
	ds_read_b128 v[180:183], v185 offset:16384
	ds_read_b128 v[188:191], v185 offset:17408
	ds_read_b128 v[192:195], v185 offset:18432
	ds_read_b128 v[196:199], v185 offset:19456
	ds_read_b128 v[200:203], v185 offset:20480
	ds_read_b128 v[204:207], v185 offset:21504
	ds_read_b128 v[208:211], v185 offset:22528
	ds_read_b128 v[212:215], v185 offset:23552
	global_load_lds_dwordx4 v156, s[24:25]
	s_add_i32 m0, s33, 0x2000
	s_add_u32 s64, s24, 0x100000
	s_addc_u32 s65, s25, 0
	s_add_i32 s33, s49, s36
	global_load_lds_dwordx4 v160, s[24:25]
	s_mov_b32 m0, s33
	s_add_u32 s100, s28, 0x80
	s_addc_u32 s101, s29, 0
	global_load_lds_dwordx4 v156, s[64:65]
	s_add_i32 m0, s33, 0x2000
	s_nop 0
	global_load_lds_dwordx4 v160, s[64:65]
	s_mov_b32 m0, s23
	s_nop 0
	global_load_lds_dwordx4 v154, s[28:29]
	s_mov_b32 m0, s37
	s_nop 0
	global_load_lds_dwordx4 v158, s[28:29]
	s_waitcnt vmcnt(8)
	s_waitcnt lgkmcnt(0)
	s_barrier
	s_waitcnt lgkmcnt(0)
	v_mfma_f32_16x16x32_bf16 v[58:61], v[130:133], v[180:183], v[58:61]
	v_mfma_f32_16x16x32_bf16 v[58:61], v[134:137], v[188:191], v[58:61]
	v_mfma_f32_16x16x32_bf16 v[54:57], v[142:145], v[188:191], v[54:57]
	v_mfma_f32_16x16x32_bf16 v[54:57], v[138:141], v[180:183], v[54:57]
	v_mfma_f32_16x16x32_bf16 v[62:65], v[146:149], v[180:183], v[62:65]
	v_mfma_f32_16x16x32_bf16 v[62:65], v[150:153], v[188:191], v[62:65]
	v_mfma_f32_16x16x32_bf16 v[50:53], v[176:179], v[188:191], v[50:53]
	v_mfma_f32_16x16x32_bf16 v[50:53], v[172:175], v[180:183], v[50:53]
	v_mfma_f32_16x16x32_bf16 v[38:41], v[172:175], v[192:195], v[38:41]
	v_mfma_f32_16x16x32_bf16 v[38:41], v[176:179], v[196:199], v[38:41]
	v_mfma_f32_16x16x32_bf16 v[46:49], v[150:153], v[196:199], v[46:49]
	v_mfma_f32_16x16x32_bf16 v[46:49], v[146:149], v[192:195], v[46:49]
	v_mfma_f32_16x16x32_bf16 v[34:37], v[138:141], v[192:195], v[34:37]
	v_mfma_f32_16x16x32_bf16 v[34:37], v[142:145], v[196:199], v[34:37]
	v_mfma_f32_16x16x32_bf16 v[42:45], v[134:137], v[196:199], v[42:45]
	v_mfma_f32_16x16x32_bf16 v[42:45], v[130:133], v[192:195], v[42:45]
	v_mfma_f32_16x16x32_bf16 v[26:29], v[130:133], v[200:203], v[26:29]
	v_mfma_f32_16x16x32_bf16 v[26:29], v[134:137], v[204:207], v[26:29]
	v_mfma_f32_16x16x32_bf16 v[18:21], v[142:145], v[204:207], v[18:21]
	v_mfma_f32_16x16x32_bf16 v[18:21], v[138:141], v[200:203], v[18:21]
	v_mfma_f32_16x16x32_bf16 v[30:33], v[146:149], v[200:203], v[30:33]
	v_mfma_f32_16x16x32_bf16 v[30:33], v[150:153], v[204:207], v[30:33]
	v_mfma_f32_16x16x32_bf16 v[22:25], v[176:179], v[204:207], v[22:25]
	v_mfma_f32_16x16x32_bf16 v[22:25], v[172:175], v[200:203], v[22:25]
	v_mfma_f32_16x16x32_bf16 v[14:17], v[172:175], v[208:211], v[14:17]
	v_mfma_f32_16x16x32_bf16 v[14:17], v[176:179], v[212:215], v[14:17]
	v_mfma_f32_16x16x32_bf16 v[10:13], v[150:153], v[212:215], v[10:13]
	v_mfma_f32_16x16x32_bf16 v[10:13], v[146:149], v[208:211], v[10:13]
	v_mfma_f32_16x16x32_bf16 v[2:5], v[138:141], v[208:211], v[2:5]
	v_mfma_f32_16x16x32_bf16 v[2:5], v[142:145], v[212:215], v[2:5]
	v_mfma_f32_16x16x32_bf16 v[6:9], v[134:137], v[212:215], v[6:9]
	v_mfma_f32_16x16x32_bf16 v[6:9], v[130:133], v[208:211], v[6:9]
	s_barrier
; #define PG8_STAGE(bufoff, gbase, voff) do { _Pragma("unroll") for (int _i = 0; _i < 2; ++_i) \
;         __builtin_amdgcn_global_load_lds((const unsigned*)((const char*)(gbase) + (voff)[_i]), (PG8_LAS unsigned*)(lds + (bufoff) + ldsw + _i * 8192), 16, 0, 0); } while (0)
; #define PG8_LDA(dst, b, h) do { _Pragma("unroll") for (int m = 0; m < 4; ++m) _Pragma("unroll") for (int k = 0; k < 2; ++k) dst[m][k] = *(const PG8_LAS bf16x8*)(lds + PG8_SA(b, h) + aoff + m * 2048 + k * 1024); } while (0)
; #define PG8_LDB(dst, b, h) do { _Pragma("unroll") for (int n = 0; n < 2; ++n) _Pragma("unroll") for (int k = 0; k < 2; ++k) dst[n][k] = *(const PG8_LAS bf16x8*)(lds + PG8_SB(b, h) + boff + n * 2048 + k * 1024); } while (0)
; #define PG8_MMA(ai, bj, At, Bt) do { __builtin_amdgcn_s_setprio(1); _Pragma("unroll") for (int m = 0; m < 4; ++m) _Pragma("unroll") for (int n = 0; n < 2; ++n) _Pragma("unroll") for (int k = 0; k < 2; ++k) \
;         acc[ai][bj][m][n] = __builtin_amdgcn_mfma_f32_16x16x32_bf16(Bt[n][k], At[m][k], acc[ai][bj][m][n], 0, 0, 0); __builtin_amdgcn_s_setprio(0); } while (0)
; #define PG8_WAIT_V(n) asm volatile("s_waitcnt vmcnt(" #n ")" ::: "memory")
; #define PG8_WAIT_L(n) asm volatile("s_waitcnt lgkmcnt(" #n ")" ::: "memory")
; #define PG8_BAR __builtin_amdgcn_s_barrier()
; #define PG8_SCHED __builtin_amdgcn_sched_barrier(0)
; template <class Epi, class Sched, bool ALIGN_EPI = false, bool SP2 = false>
; __device__ __forceinline__ void gemm_phase(PG8_LAS unsigned char* lds, const Gemm g, const Sched& S, const Epi& E) {
;     ...
;         for (int t = 0; t < nt; t += 2) {
;             const bool last = (t == nt - 2);
;             const char* a1 = cA + (size_t)(t + 1) * kstep;
;             const char* a2 = last ? nA : cA + (size_t)(t + 2) * kstep; const char* b2 = last ? nB : cB + (size_t)(t + 2) * kstep;
;     ...
;             PG8_LDB(B0, 1, 0); PG8_LDB(B1, 1, 1); PG8_SCHED; PG8_LDA(At, 1, 0); PG8_STAGE(PG8_SA(0, 1), a2 + hstep, voffA);
;             PG8_WAIT_V(8); PG8_WAIT_L(0); PG8_BAR; PG8_MMA(0, 0, At, B0); PG8_MMA(0, 1, At, B1); PG8_BAR; PG8_SCHED;
;             PG8_LDA(At, 1, 1); PG8_STAGE(PG8_SB(1, 0), b3, voffB); PG8_STAGE(PG8_SB(1, 1), b3 + hstep, voffB); PG8_STAGE(PG8_SA(1, 0), a3, voffA);
;             PG8_WAIT_V(8); PG8_WAIT_L(0); PG8_BAR; PG8_MMA(1, 0, At, B0); PG8_MMA(1, 1, At, B1); PG8_BAR; PG8_SCHED;
	s_add_i32 s33, 0, 0x18000
	s_add_i32 s42, 0, 0x1c000
	ds_read_b128 v[130:133], v241 offset:32768
	ds_read_b128 v[134:137], v241 offset:33792
	ds_read_b128 v[138:141], v241 offset:34816
	ds_read_b128 v[142:145], v241 offset:35840
	ds_read_b128 v[146:149], v241 offset:49152
	ds_read_b128 v[150:153], v241 offset:50176
	ds_read_b128 v[172:175], v241 offset:51200
	ds_read_b128 v[176:179], v241 offset:52224
	s_add_u32 s28, s28, 0x100000
	s_addc_u32 s29, s29, 0
	s_mov_b32 m0, s40
	ds_read_b128 v[180:183], v185 offset:32768
	ds_read_b128 v[188:191], v185 offset:33792
	ds_read_b128 v[192:195], v185 offset:34816
	ds_read_b128 v[196:199], v185 offset:35840
	ds_read_b128 v[200:203], v185 offset:36864
	ds_read_b128 v[204:207], v185 offset:37888
	ds_read_b128 v[208:211], v185 offset:38912
	ds_read_b128 v[212:215], v185 offset:39936
	global_load_lds_dwordx4 v154, s[28:29]
	s_mov_b32 m0, s41
	s_nop 0
	global_load_lds_dwordx4 v158, s[28:29]
	s_waitcnt vmcnt(8)
	s_waitcnt lgkmcnt(0)
	s_barrier
	s_waitcnt lgkmcnt(0)
	v_mfma_f32_16x16x32_bf16 v[114:117], v[130:133], v[180:183], v[114:117]
	v_mfma_f32_16x16x32_bf16 v[114:117], v[134:137], v[188:191], v[114:117]
	v_mfma_f32_16x16x32_bf16 v[118:121], v[142:145], v[188:191], v[118:121]
	v_mfma_f32_16x16x32_bf16 v[118:121], v[138:141], v[180:183], v[118:121]
	v_mfma_f32_16x16x32_bf16 v[122:125], v[146:149], v[180:183], v[122:125]
	v_mfma_f32_16x16x32_bf16 v[122:125], v[150:153], v[188:191], v[122:125]
	v_mfma_f32_16x16x32_bf16 v[126:129], v[176:179], v[188:191], v[126:129]
	v_mfma_f32_16x16x32_bf16 v[126:129], v[172:175], v[180:183], v[126:129]
	v_mfma_f32_16x16x32_bf16 v[102:105], v[172:175], v[192:195], v[102:105]
	v_mfma_f32_16x16x32_bf16 v[102:105], v[176:179], v[196:199], v[102:105]
	v_mfma_f32_16x16x32_bf16 v[110:113], v[150:153], v[196:199], v[110:113]
	v_mfma_f32_16x16x32_bf16 v[110:113], v[146:149], v[192:195], v[110:113]
	v_mfma_f32_16x16x32_bf16 v[98:101], v[138:141], v[192:195], v[98:101]
	v_mfma_f32_16x16x32_bf16 v[98:101], v[142:145], v[196:199], v[98:101]
	v_mfma_f32_16x16x32_bf16 v[106:109], v[134:137], v[196:199], v[106:109]
	v_mfma_f32_16x16x32_bf16 v[106:109], v[130:133], v[192:195], v[106:109]
	v_mfma_f32_16x16x32_bf16 v[90:93], v[130:133], v[200:203], v[90:93]
	v_mfma_f32_16x16x32_bf16 v[90:93], v[134:137], v[204:207], v[90:93]
	v_mfma_f32_16x16x32_bf16 v[82:85], v[142:145], v[204:207], v[82:85]
	v_mfma_f32_16x16x32_bf16 v[82:85], v[138:141], v[200:203], v[82:85]
	v_mfma_f32_16x16x32_bf16 v[94:97], v[146:149], v[200:203], v[94:97]
	v_mfma_f32_16x16x32_bf16 v[94:97], v[150:153], v[204:207], v[94:97]
	v_mfma_f32_16x16x32_bf16 v[86:89], v[176:179], v[204:207], v[86:89]
	v_mfma_f32_16x16x32_bf16 v[86:89], v[172:175], v[200:203], v[86:89]
	v_mfma_f32_16x16x32_bf16 v[70:73], v[172:175], v[208:211], v[70:73]
	v_mfma_f32_16x16x32_bf16 v[70:73], v[176:179], v[212:215], v[70:73]
	v_mfma_f32_16x16x32_bf16 v[78:81], v[150:153], v[212:215], v[78:81]
	v_mfma_f32_16x16x32_bf16 v[78:81], v[146:149], v[208:211], v[78:81]
	v_mfma_f32_16x16x32_bf16 v[66:69], v[138:141], v[208:211], v[66:69]
	v_mfma_f32_16x16x32_bf16 v[66:69], v[142:145], v[212:215], v[66:69]
	v_mfma_f32_16x16x32_bf16 v[74:77], v[134:137], v[212:215], v[74:77]
	v_mfma_f32_16x16x32_bf16 v[74:77], v[130:133], v[208:211], v[74:77]
	s_barrier
	s_add_i32 s28, s33, s36
	s_add_i32 m0, s28, 0xffffff80
	ds_read_b128 v[180:183], v185 offset:49152
	ds_read_b128 v[188:191], v185 offset:50176
	ds_read_b128 v[192:195], v185 offset:51200
	ds_read_b128 v[196:199], v185 offset:52224
	ds_read_b128 v[200:203], v185 offset:53248
	ds_read_b128 v[204:207], v185 offset:54272
	ds_read_b128 v[208:211], v185 offset:55296
	ds_read_b128 v[212:215], v185 offset:56320
	global_load_lds_dwordx4 v156, s[24:25] offset:128
	s_add_i32 m0, s28, 0x1f80
	s_add_i32 s28, s42, s36
	global_load_lds_dwordx4 v160, s[24:25] offset:128
	s_add_u32 s24, s24, 0x100080
	s_addc_u32 s25, s25, 0
	s_mov_b32 m0, s28
	s_nop 0
	global_load_lds_dwordx4 v156, s[24:25]
	s_add_i32 m0, s28, 0x2000
	s_nop 0
	global_load_lds_dwordx4 v160, s[24:25]
	s_mov_b32 m0, s44
	s_nop 0
	global_load_lds_dwordx4 v154, s[100:101]
	s_mov_b32 m0, s45
	s_nop 0
	global_load_lds_dwordx4 v158, s[100:101]
	s_waitcnt vmcnt(8)
	s_waitcnt lgkmcnt(0)
	s_barrier
	s_waitcnt lgkmcnt(0)
	v_mfma_f32_16x16x32_bf16 v[58:61], v[130:133], v[180:183], v[58:61]
	v_mfma_f32_16x16x32_bf16 v[58:61], v[134:137], v[188:191], v[58:61]
	v_mfma_f32_16x16x32_bf16 v[54:57], v[142:145], v[188:191], v[54:57]
	v_mfma_f32_16x16x32_bf16 v[54:57], v[138:141], v[180:183], v[54:57]
	v_mfma_f32_16x16x32_bf16 v[62:65], v[146:149], v[180:183], v[62:65]
	v_mfma_f32_16x16x32_bf16 v[62:65], v[150:153], v[188:191], v[62:65]
	v_mfma_f32_16x16x32_bf16 v[50:53], v[176:179], v[188:191], v[50:53]
	v_mfma_f32_16x16x32_bf16 v[50:53], v[172:175], v[180:183], v[50:53]
	v_mfma_f32_16x16x32_bf16 v[38:41], v[172:175], v[192:195], v[38:41]
	v_mfma_f32_16x16x32_bf16 v[38:41], v[176:179], v[196:199], v[38:41]
	v_mfma_f32_16x16x32_bf16 v[46:49], v[150:153], v[196:199], v[46:49]
	v_mfma_f32_16x16x32_bf16 v[46:49], v[146:149], v[192:195], v[46:49]
	v_mfma_f32_16x16x32_bf16 v[34:37], v[138:141], v[192:195], v[34:37]
	v_mfma_f32_16x16x32_bf16 v[34:37], v[142:145], v[196:199], v[34:37]
	v_mfma_f32_16x16x32_bf16 v[42:45], v[134:137], v[196:199], v[42:45]
	v_mfma_f32_16x16x32_bf16 v[42:45], v[130:133], v[192:195], v[42:45]
	v_mfma_f32_16x16x32_bf16 v[26:29], v[130:133], v[200:203], v[26:29]
	v_mfma_f32_16x16x32_bf16 v[26:29], v[134:137], v[204:207], v[26:29]
	v_mfma_f32_16x16x32_bf16 v[18:21], v[142:145], v[204:207], v[18:21]
	v_mfma_f32_16x16x32_bf16 v[18:21], v[138:141], v[200:203], v[18:21]
	v_mfma_f32_16x16x32_bf16 v[30:33], v[146:149], v[200:203], v[30:33]
	v_mfma_f32_16x16x32_bf16 v[30:33], v[150:153], v[204:207], v[30:33]
	v_mfma_f32_16x16x32_bf16 v[22:25], v[176:179], v[204:207], v[22:25]
	v_mfma_f32_16x16x32_bf16 v[22:25], v[172:175], v[200:203], v[22:25]
	v_mfma_f32_16x16x32_bf16 v[14:17], v[172:175], v[208:211], v[14:17]
	v_mfma_f32_16x16x32_bf16 v[14:17], v[176:179], v[212:215], v[14:17]
	v_mfma_f32_16x16x32_bf16 v[10:13], v[150:153], v[212:215], v[10:13]
	v_mfma_f32_16x16x32_bf16 v[10:13], v[146:149], v[208:211], v[10:13]
	v_mfma_f32_16x16x32_bf16 v[2:5], v[138:141], v[208:211], v[2:5]
	v_mfma_f32_16x16x32_bf16 v[2:5], v[142:145], v[212:215], v[2:5]
	v_mfma_f32_16x16x32_bf16 v[6:9], v[134:137], v[212:215], v[6:9]
	v_mfma_f32_16x16x32_bf16 v[6:9], v[130:133], v[208:211], v[6:9]
	s_barrier
	s_add_i32 s62, s62, 2
	s_add_u32 s26, s26, 0x100
	s_addc_u32 s27, s27, 0
	s_add_u32 s52, s52, 0x100
	s_addc_u32 s53, s53, 0
	s_cmp_gt_u32 s62, 61
	s_cbranch_scc0 .LBB0_1595
	s_and_b64 vcc, exec, s[10:11]
	s_cbranch_vccz .LBB0_1598
	s_barrier

; #define PG8_STAGE(bufoff, gbase, voff) do { _Pragma("unroll") for (int _i = 0; _i < 2; ++_i) \
;         __builtin_amdgcn_global_load_lds((const unsigned*)((const char*)(gbase) + (voff)[_i]), (PG8_LAS unsigned*)(lds + (bufoff) + ldsw + _i * 8192), 16, 0, 0); } while (0)
; #define PG8_LDA(dst, b, h) do { _Pragma("unroll") for (int m = 0; m < 4; ++m) _Pragma("unroll") for (int k = 0; k < 2; ++k) dst[m][k] = *(const PG8_LAS bf16x8*)(lds + PG8_SA(b, h) + aoff + m * 2048 + k * 1024); } while (0)
; #define PG8_LDB(dst, b, h) do { _Pragma("unroll") for (int n = 0; n < 2; ++n) _Pragma("unroll") for (int k = 0; k < 2; ++k) dst[n][k] = *(const PG8_LAS bf16x8*)(lds + PG8_SB(b, h) + boff + n * 2048 + k * 1024); } while (0)
; #define PG8_MMA(ai, bj, At, Bt) do { __builtin_amdgcn_s_setprio(1); _Pragma("unroll") for (int m = 0; m < 4; ++m) _Pragma("unroll") for (int n = 0; n < 2; ++n) _Pragma("unroll") for (int k = 0; k < 2; ++k) \
;         acc[ai][bj][m][n] = __builtin_amdgcn_mfma_f32_16x16x32_bf16(Bt[n][k], At[m][k], acc[ai][bj][m][n], 0, 0, 0); __builtin_amdgcn_s_setprio(0); } while (0)
; #define PG8_WAIT_V(n) asm volatile("s_waitcnt vmcnt(" #n ")" ::: "memory")
; #define PG8_WAIT_L(n) asm volatile("s_waitcnt lgkmcnt(" #n ")" ::: "memory")
; template <class Epi, class Sched, bool ALIGN_EPI = false, bool SP2 = false>
; __device__ __forceinline__ void gemm_phase(PG8_LAS unsigned char* lds, const Gemm g, const Sched& S, const Epi& E) {
;     ...
;             const bool last = (t == nt - 2);
;             const char* a1 = cA + (size_t)(t + 1) * kstep;
;             const char* a2 = last ? nA : cA + (size_t)(t + 2) * kstep; const char* b2 = last ? nB : cB + (size_t)(t + 2) * kstep;
;             const char* a3 = a2 + kstep; const char* b3 = b2 + kstep;
;             if (last && has_next) S.a_ready(nxt);
;             if constexpr (SP2) {
;             PG8_LDB(B0, 0, 0); PG8_LDB(B1, 0, 1); PG8_SCHED; PG8_LDA(At, 0, 0); PG8_STAGE(PG8_SA(1, 1), a1 + hstep, voffA);
;             PG8_WAIT_V(8); PG8_WAIT_L(0); PG8_BAR; PG8_MMA(0, 0, At, B0); PG8_MMA(0, 1, At, B1); PG8_BAR; PG8_SCHED;
;             PG8_LDA(At, 0, 1); PG8_STAGE(PG8_SB(0, 0), b2, voffB); PG8_STAGE(PG8_SB(0, 1), b2 + hstep, voffB); PG8_STAGE(PG8_SA(0, 0), a2, voffA);
;             PG8_WAIT_V(8); PG8_WAIT_L(0); PG8_BAR; PG8_MMA(1, 0, At, B0); PG8_MMA(1, 1, At, B1); PG8_BAR; PG8_SCHED;
.LBB0_1681:
	ds_read_b128 v[160:163], v241 offset:0
	ds_read_b128 v[166:169], v241 offset:1024
	ds_read_b128 v[170:173], v241 offset:2048
	ds_read_b128 v[174:177], v241 offset:3072
	ds_read_b128 v[178:181], v241 offset:16384
	ds_read_b128 v[182:185], v241 offset:17408
	ds_read_b128 v[186:189], v241 offset:18432
	ds_read_b128 v[190:193], v241 offset:19456
	s_add_u32 s22, s24, 0xfff00080
	s_addc_u32 s23, s25, -1
	s_cmp_eq_u32 s52, 60
	s_cselect_b32 s27, s15, s23
	s_cselect_b32 s26, s48, s22
	s_cselect_b32 s23, s13, s51
	s_cselect_b32 s22, s49, s50
	s_add_i32 m0, s21, 0xc000
	ds_read_b128 v[194:197], v155
	ds_read_b128 v[198:201], v155 offset:1024
	ds_read_b128 v[202:205], v155 offset:2048
	ds_read_b128 v[206:209], v155 offset:3072
	ds_read_b128 v[210:213], v155 offset:4096
	ds_read_b128 v[214:217], v155 offset:5120
	ds_read_b128 v[218:221], v155 offset:6144
	ds_read_b128 v[222:225], v155 offset:7168
	global_load_lds_dwordx4 v138, s[24:25]
	s_add_i32 m0, s21, 0xe000
	s_nop 0
	global_load_lds_dwordx4 v140, s[24:25]
	s_waitcnt vmcnt(8)
	s_waitcnt lgkmcnt(0)
	s_barrier
	s_waitcnt lgkmcnt(0)
	v_mfma_f32_16x16x32_bf16 v[122:125], v[160:163], v[194:197], v[122:125]
	v_mfma_f32_16x16x32_bf16 v[122:125], v[166:169], v[198:201], v[122:125]
	v_mfma_f32_16x16x32_bf16 v[114:117], v[174:177], v[198:201], v[114:117]
	v_mfma_f32_16x16x32_bf16 v[114:117], v[170:173], v[194:197], v[114:117]
	v_mfma_f32_16x16x32_bf16 v[126:129], v[178:181], v[194:197], v[126:129]
	v_mfma_f32_16x16x32_bf16 v[126:129], v[182:185], v[198:201], v[126:129]
	v_mfma_f32_16x16x32_bf16 v[118:121], v[190:193], v[198:201], v[118:121]
	v_mfma_f32_16x16x32_bf16 v[118:121], v[186:189], v[194:197], v[118:121]
	v_mfma_f32_16x16x32_bf16 v[102:105], v[186:189], v[202:205], v[102:105]
	v_mfma_f32_16x16x32_bf16 v[102:105], v[190:193], v[206:209], v[102:105]
	v_mfma_f32_16x16x32_bf16 v[110:113], v[182:185], v[206:209], v[110:113]
	v_mfma_f32_16x16x32_bf16 v[110:113], v[178:181], v[202:205], v[110:113]
	v_mfma_f32_16x16x32_bf16 v[98:101], v[170:173], v[202:205], v[98:101]
	v_mfma_f32_16x16x32_bf16 v[98:101], v[174:177], v[206:209], v[98:101]
	v_mfma_f32_16x16x32_bf16 v[106:109], v[166:169], v[206:209], v[106:109]
	v_mfma_f32_16x16x32_bf16 v[106:109], v[160:163], v[202:205], v[106:109]
	v_mfma_f32_16x16x32_bf16 v[90:93], v[160:163], v[210:213], v[90:93]
	v_mfma_f32_16x16x32_bf16 v[90:93], v[166:169], v[214:217], v[90:93]
	v_mfma_f32_16x16x32_bf16 v[82:85], v[174:177], v[214:217], v[82:85]
	v_mfma_f32_16x16x32_bf16 v[82:85], v[170:173], v[210:213], v[82:85]
	v_mfma_f32_16x16x32_bf16 v[94:97], v[178:181], v[210:213], v[94:97]
	v_mfma_f32_16x16x32_bf16 v[94:97], v[182:185], v[214:217], v[94:97]
	v_mfma_f32_16x16x32_bf16 v[86:89], v[190:193], v[214:217], v[86:89]
	v_mfma_f32_16x16x32_bf16 v[86:89], v[186:189], v[210:213], v[86:89]
	v_mfma_f32_16x16x32_bf16 v[70:73], v[186:189], v[218:221], v[70:73]
	v_mfma_f32_16x16x32_bf16 v[70:73], v[190:193], v[222:225], v[70:73]
	v_mfma_f32_16x16x32_bf16 v[78:81], v[182:185], v[222:225], v[78:81]
	v_mfma_f32_16x16x32_bf16 v[78:81], v[178:181], v[218:221], v[78:81]
	v_mfma_f32_16x16x32_bf16 v[62:65], v[170:173], v[218:221], v[62:65]
	v_mfma_f32_16x16x32_bf16 v[62:65], v[174:177], v[222:225], v[62:65]
	v_mfma_f32_16x16x32_bf16 v[74:77], v[166:169], v[222:225], v[74:77]
	v_mfma_f32_16x16x32_bf16 v[74:77], v[160:163], v[218:221], v[74:77]
	s_barrier
	s_add_i32 s33, s44, s29
	s_mov_b32 m0, s33
	ds_read_b128 v[194:197], v155 offset:16384
	ds_read_b128 v[198:201], v155 offset:17408
	ds_read_b128 v[202:205], v155 offset:18432
	ds_read_b128 v[206:209], v155 offset:19456
	ds_read_b128 v[210:213], v155 offset:20480
	ds_read_b128 v[214:217], v155 offset:21504
	ds_read_b128 v[218:221], v155 offset:22528
	ds_read_b128 v[222:225], v155 offset:23552
	global_load_lds_dwordx4 v132, s[22:23]
	s_add_i32 m0, s33, 0x2000
	s_add_u32 s62, s22, 0x100000
	s_addc_u32 s63, s23, 0
	s_add_i32 s33, s45, s29
	global_load_lds_dwordx4 v136, s[22:23]
	s_mov_b32 m0, s33
	s_add_u32 s100, s26, 0x80
	s_addc_u32 s101, s27, 0
	global_load_lds_dwordx4 v132, s[62:63]
	s_add_i32 m0, s33, 0x2000
	s_nop 0
	global_load_lds_dwordx4 v136, s[62:63]
	s_mov_b32 m0, s21
	s_nop 0
	global_load_lds_dwordx4 v130, s[26:27]
	s_mov_b32 m0, s34
	s_nop 0
	global_load_lds_dwordx4 v134, s[26:27]
	s_waitcnt vmcnt(8)
	s_waitcnt lgkmcnt(0)
	s_barrier
	s_waitcnt lgkmcnt(0)
	v_mfma_f32_16x16x32_bf16 v[58:61], v[160:163], v[194:197], v[58:61]
	v_mfma_f32_16x16x32_bf16 v[58:61], v[166:169], v[198:201], v[58:61]
	v_mfma_f32_16x16x32_bf16 v[50:53], v[174:177], v[198:201], v[50:53]
	v_mfma_f32_16x16x32_bf16 v[50:53], v[170:173], v[194:197], v[50:53]
	v_mfma_f32_16x16x32_bf16 v[66:69], v[178:181], v[194:197], v[66:69]
	v_mfma_f32_16x16x32_bf16 v[66:69], v[182:185], v[198:201], v[66:69]
	v_mfma_f32_16x16x32_bf16 v[54:57], v[190:193], v[198:201], v[54:57]
	v_mfma_f32_16x16x32_bf16 v[54:57], v[186:189], v[194:197], v[54:57]
	v_mfma_f32_16x16x32_bf16 v[38:41], v[186:189], v[202:205], v[38:41]
	v_mfma_f32_16x16x32_bf16 v[38:41], v[190:193], v[206:209], v[38:41]
	v_mfma_f32_16x16x32_bf16 v[46:49], v[182:185], v[206:209], v[46:49]
	v_mfma_f32_16x16x32_bf16 v[46:49], v[178:181], v[202:205], v[46:49]
	v_mfma_f32_16x16x32_bf16 v[34:37], v[170:173], v[202:205], v[34:37]
	v_mfma_f32_16x16x32_bf16 v[34:37], v[174:177], v[206:209], v[34:37]
	v_mfma_f32_16x16x32_bf16 v[42:45], v[166:169], v[206:209], v[42:45]
	v_mfma_f32_16x16x32_bf16 v[42:45], v[160:163], v[202:205], v[42:45]
	v_mfma_f32_16x16x32_bf16 v[26:29], v[160:163], v[210:213], v[26:29]
	v_mfma_f32_16x16x32_bf16 v[26:29], v[166:169], v[214:217], v[26:29]
	v_mfma_f32_16x16x32_bf16 v[18:21], v[174:177], v[214:217], v[18:21]
	v_mfma_f32_16x16x32_bf16 v[18:21], v[170:173], v[210:213], v[18:21]
	v_mfma_f32_16x16x32_bf16 v[30:33], v[178:181], v[210:213], v[30:33]
	v_mfma_f32_16x16x32_bf16 v[30:33], v[182:185], v[214:217], v[30:33]
	v_mfma_f32_16x16x32_bf16 v[22:25], v[190:193], v[214:217], v[22:25]
	v_mfma_f32_16x16x32_bf16 v[22:25], v[186:189], v[210:213], v[22:25]
	v_mfma_f32_16x16x32_bf16 v[6:9], v[186:189], v[218:221], v[6:9]
	v_mfma_f32_16x16x32_bf16 v[6:9], v[190:193], v[222:225], v[6:9]
	v_mfma_f32_16x16x32_bf16 v[14:17], v[182:185], v[222:225], v[14:17]
	v_mfma_f32_16x16x32_bf16 v[14:17], v[178:181], v[218:221], v[14:17]
	v_mfma_f32_16x16x32_bf16 v[2:5], v[170:173], v[218:221], v[2:5]
	v_mfma_f32_16x16x32_bf16 v[2:5], v[174:177], v[222:225], v[2:5]
	v_mfma_f32_16x16x32_bf16 v[10:13], v[166:169], v[222:225], v[10:13]
	v_mfma_f32_16x16x32_bf16 v[10:13], v[160:163], v[218:221], v[10:13]
	s_barrier
; #define PG8_STAGE(bufoff, gbase, voff) do { _Pragma("unroll") for (int _i = 0; _i < 2; ++_i) \
;         __builtin_amdgcn_global_load_lds((const unsigned*)((const char*)(gbase) + (voff)[_i]), (PG8_LAS unsigned*)(lds + (bufoff) + ldsw + _i * 8192), 16, 0, 0); } while (0)
; #define PG8_LDA(dst, b, h) do { _Pragma("unroll") for (int m = 0; m < 4; ++m) _Pragma("unroll") for (int k = 0; k < 2; ++k) dst[m][k] = *(const PG8_LAS bf16x8*)(lds + PG8_SA(b, h) + aoff + m * 2048 + k * 1024); } while (0)
; #define PG8_LDB(dst, b, h) do { _Pragma("unroll") for (int n = 0; n < 2; ++n) _Pragma("unroll") for (int k = 0; k < 2; ++k) dst[n][k] = *(const PG8_LAS bf16x8*)(lds + PG8_SB(b, h) + boff + n * 2048 + k * 1024); } while (0)
; #define PG8_MMA(ai, bj, At, Bt) do { __builtin_amdgcn_s_setprio(1); _Pragma("unroll") for (int m = 0; m < 4; ++m) _Pragma("unroll") for (int n = 0; n < 2; ++n) _Pragma("unroll") for (int k = 0; k < 2; ++k) \
;         acc[ai][bj][m][n] = __builtin_amdgcn_mfma_f32_16x16x32_bf16(Bt[n][k], At[m][k], acc[ai][bj][m][n], 0, 0, 0); __builtin_amdgcn_s_setprio(0); } while (0)
; #define PG8_WAIT_V(n) asm volatile("s_waitcnt vmcnt(" #n ")" ::: "memory")
; #define PG8_WAIT_L(n) asm volatile("s_waitcnt lgkmcnt(" #n ")" ::: "memory")
; #define PG8_BAR __builtin_amdgcn_s_barrier()
; template <class Epi, class Sched, bool ALIGN_EPI = false, bool SP2 = false>
; __device__ __forceinline__ void gemm_phase(PG8_LAS unsigned char* lds, const Gemm g, const Sched& S, const Epi& E) {
;     ...
;         for (int t = 0; t < nt; t += 2) {
;             const bool last = (t == nt - 2);
;             const char* a1 = cA + (size_t)(t + 1) * kstep;
;             const char* a2 = last ? nA : cA + (size_t)(t + 2) * kstep; const char* b2 = last ? nB : cB + (size_t)(t + 2) * kstep;
;             const char* a3 = a2 + kstep; const char* b3 = b2 + kstep;
;     ...
;             PG8_LDB(B0, 1, 0); PG8_LDB(B1, 1, 1); PG8_SCHED; PG8_LDA(At, 1, 0); PG8_STAGE(PG8_SA(0, 1), a2 + hstep, voffA);
;             PG8_WAIT_V(8); PG8_WAIT_L(0); PG8_BAR; PG8_MMA(0, 0, At, B0); PG8_MMA(0, 1, At, B1); PG8_BAR; PG8_SCHED;
;             PG8_LDA(At, 1, 1); PG8_STAGE(PG8_SB(1, 0), b3, voffB); PG8_STAGE(PG8_SB(1, 1), b3 + hstep, voffB); PG8_STAGE(PG8_SA(1, 0), a3, voffA);
;             PG8_WAIT_V(8); PG8_WAIT_L(0); PG8_BAR; PG8_MMA(1, 0, At, B0); PG8_MMA(1, 1, At, B1); PG8_BAR; PG8_SCHED;
	s_add_i32 s33, 0, 0x18000
	s_add_i32 s42, 0, 0x1c000
	ds_read_b128 v[160:163], v241 offset:32768
	ds_read_b128 v[166:169], v241 offset:33792
	ds_read_b128 v[170:173], v241 offset:34816
	ds_read_b128 v[174:177], v241 offset:35840
	ds_read_b128 v[178:181], v241 offset:49152
	ds_read_b128 v[182:185], v241 offset:50176
	ds_read_b128 v[186:189], v241 offset:51200
	ds_read_b128 v[190:193], v241 offset:52224
	s_add_u32 s26, s26, 0x100000
	s_addc_u32 s27, s27, 0
	s_mov_b32 m0, s35
	ds_read_b128 v[194:197], v155 offset:32768
	ds_read_b128 v[198:201], v155 offset:33792
	ds_read_b128 v[202:205], v155 offset:34816
	ds_read_b128 v[206:209], v155 offset:35840
	ds_read_b128 v[210:213], v155 offset:36864
	ds_read_b128 v[214:217], v155 offset:37888
	ds_read_b128 v[218:221], v155 offset:38912
	ds_read_b128 v[222:225], v155 offset:39936
	global_load_lds_dwordx4 v130, s[26:27]
	s_mov_b32 m0, s36
	s_nop 0
	global_load_lds_dwordx4 v134, s[26:27]
	s_waitcnt vmcnt(8)
	s_waitcnt lgkmcnt(0)
	s_barrier
	s_waitcnt lgkmcnt(0)
	v_mfma_f32_16x16x32_bf16 v[122:125], v[160:163], v[194:197], v[122:125]
	v_mfma_f32_16x16x32_bf16 v[122:125], v[166:169], v[198:201], v[122:125]
	v_mfma_f32_16x16x32_bf16 v[114:117], v[174:177], v[198:201], v[114:117]
	v_mfma_f32_16x16x32_bf16 v[114:117], v[170:173], v[194:197], v[114:117]
	v_mfma_f32_16x16x32_bf16 v[126:129], v[178:181], v[194:197], v[126:129]
	v_mfma_f32_16x16x32_bf16 v[126:129], v[182:185], v[198:201], v[126:129]
	v_mfma_f32_16x16x32_bf16 v[118:121], v[190:193], v[198:201], v[118:121]
	v_mfma_f32_16x16x32_bf16 v[118:121], v[186:189], v[194:197], v[118:121]
	v_mfma_f32_16x16x32_bf16 v[102:105], v[186:189], v[202:205], v[102:105]
	v_mfma_f32_16x16x32_bf16 v[102:105], v[190:193], v[206:209], v[102:105]
	v_mfma_f32_16x16x32_bf16 v[110:113], v[182:185], v[206:209], v[110:113]
	v_mfma_f32_16x16x32_bf16 v[110:113], v[178:181], v[202:205], v[110:113]
	v_mfma_f32_16x16x32_bf16 v[98:101], v[170:173], v[202:205], v[98:101]
	v_mfma_f32_16x16x32_bf16 v[98:101], v[174:177], v[206:209], v[98:101]
	v_mfma_f32_16x16x32_bf16 v[106:109], v[166:169], v[206:209], v[106:109]
	v_mfma_f32_16x16x32_bf16 v[106:109], v[160:163], v[202:205], v[106:109]
	v_mfma_f32_16x16x32_bf16 v[90:93], v[160:163], v[210:213], v[90:93]
	v_mfma_f32_16x16x32_bf16 v[90:93], v[166:169], v[214:217], v[90:93]
	v_mfma_f32_16x16x32_bf16 v[82:85], v[174:177], v[214:217], v[82:85]
	v_mfma_f32_16x16x32_bf16 v[82:85], v[170:173], v[210:213], v[82:85]
	v_mfma_f32_16x16x32_bf16 v[94:97], v[178:181], v[210:213], v[94:97]
	v_mfma_f32_16x16x32_bf16 v[94:97], v[182:185], v[214:217], v[94:97]
	v_mfma_f32_16x16x32_bf16 v[86:89], v[190:193], v[214:217], v[86:89]
	v_mfma_f32_16x16x32_bf16 v[86:89], v[186:189], v[210:213], v[86:89]
	v_mfma_f32_16x16x32_bf16 v[70:73], v[186:189], v[218:221], v[70:73]
	v_mfma_f32_16x16x32_bf16 v[70:73], v[190:193], v[222:225], v[70:73]
	v_mfma_f32_16x16x32_bf16 v[78:81], v[182:185], v[222:225], v[78:81]
	v_mfma_f32_16x16x32_bf16 v[78:81], v[178:181], v[218:221], v[78:81]
	v_mfma_f32_16x16x32_bf16 v[62:65], v[170:173], v[218:221], v[62:65]
	v_mfma_f32_16x16x32_bf16 v[62:65], v[174:177], v[222:225], v[62:65]
	v_mfma_f32_16x16x32_bf16 v[74:77], v[166:169], v[222:225], v[74:77]
	v_mfma_f32_16x16x32_bf16 v[74:77], v[160:163], v[218:221], v[74:77]
	s_barrier
	s_add_i32 s26, s33, s29
	s_add_i32 m0, s26, 0xffffff80
	ds_read_b128 v[194:197], v155 offset:49152
	ds_read_b128 v[198:201], v155 offset:50176
	ds_read_b128 v[202:205], v155 offset:51200
	ds_read_b128 v[206:209], v155 offset:52224
	ds_read_b128 v[210:213], v155 offset:53248
	ds_read_b128 v[214:217], v155 offset:54272
	ds_read_b128 v[218:221], v155 offset:55296
	ds_read_b128 v[222:225], v155 offset:56320
	global_load_lds_dwordx4 v132, s[22:23] offset:128
	s_add_i32 m0, s26, 0x1f80
	s_add_i32 s26, s42, s29
	global_load_lds_dwordx4 v136, s[22:23] offset:128
	s_add_u32 s22, s22, 0x100080
	s_addc_u32 s23, s23, 0
	s_mov_b32 m0, s26
	s_nop 0
	global_load_lds_dwordx4 v132, s[22:23]
	s_add_i32 m0, s26, 0x2000
	s_nop 0
	global_load_lds_dwordx4 v136, s[22:23]
	s_mov_b32 m0, s41
	s_nop 0
	global_load_lds_dwordx4 v130, s[100:101]
	s_mov_b32 m0, s43
	s_nop 0
	global_load_lds_dwordx4 v134, s[100:101]
	s_waitcnt vmcnt(8)
	s_waitcnt lgkmcnt(0)
	s_barrier
	s_waitcnt lgkmcnt(0)
	v_mfma_f32_16x16x32_bf16 v[58:61], v[160:163], v[194:197], v[58:61]
	v_mfma_f32_16x16x32_bf16 v[58:61], v[166:169], v[198:201], v[58:61]
	v_mfma_f32_16x16x32_bf16 v[50:53], v[174:177], v[198:201], v[50:53]
	v_mfma_f32_16x16x32_bf16 v[50:53], v[170:173], v[194:197], v[50:53]
	v_mfma_f32_16x16x32_bf16 v[66:69], v[178:181], v[194:197], v[66:69]
	v_mfma_f32_16x16x32_bf16 v[66:69], v[182:185], v[198:201], v[66:69]
	v_mfma_f32_16x16x32_bf16 v[54:57], v[190:193], v[198:201], v[54:57]
	v_mfma_f32_16x16x32_bf16 v[54:57], v[186:189], v[194:197], v[54:57]
	v_mfma_f32_16x16x32_bf16 v[38:41], v[186:189], v[202:205], v[38:41]
	v_mfma_f32_16x16x32_bf16 v[38:41], v[190:193], v[206:209], v[38:41]
	v_mfma_f32_16x16x32_bf16 v[46:49], v[182:185], v[206:209], v[46:49]
	v_mfma_f32_16x16x32_bf16 v[46:49], v[178:181], v[202:205], v[46:49]
	v_mfma_f32_16x16x32_bf16 v[34:37], v[170:173], v[202:205], v[34:37]
	v_mfma_f32_16x16x32_bf16 v[34:37], v[174:177], v[206:209], v[34:37]
	v_mfma_f32_16x16x32_bf16 v[42:45], v[166:169], v[206:209], v[42:45]
	v_mfma_f32_16x16x32_bf16 v[42:45], v[160:163], v[202:205], v[42:45]
	v_mfma_f32_16x16x32_bf16 v[26:29], v[160:163], v[210:213], v[26:29]
	v_mfma_f32_16x16x32_bf16 v[26:29], v[166:169], v[214:217], v[26:29]
	v_mfma_f32_16x16x32_bf16 v[18:21], v[174:177], v[214:217], v[18:21]
	v_mfma_f32_16x16x32_bf16 v[18:21], v[170:173], v[210:213], v[18:21]
	v_mfma_f32_16x16x32_bf16 v[30:33], v[178:181], v[210:213], v[30:33]
	v_mfma_f32_16x16x32_bf16 v[30:33], v[182:185], v[214:217], v[30:33]
	v_mfma_f32_16x16x32_bf16 v[22:25], v[190:193], v[214:217], v[22:25]
	v_mfma_f32_16x16x32_bf16 v[22:25], v[186:189], v[210:213], v[22:25]
	v_mfma_f32_16x16x32_bf16 v[6:9], v[186:189], v[218:221], v[6:9]
	v_mfma_f32_16x16x32_bf16 v[6:9], v[190:193], v[222:225], v[6:9]
	v_mfma_f32_16x16x32_bf16 v[14:17], v[182:185], v[222:225], v[14:17]
	v_mfma_f32_16x16x32_bf16 v[14:17], v[178:181], v[218:221], v[14:17]
	v_mfma_f32_16x16x32_bf16 v[2:5], v[170:173], v[218:221], v[2:5]
	v_mfma_f32_16x16x32_bf16 v[2:5], v[174:177], v[222:225], v[2:5]
	v_mfma_f32_16x16x32_bf16 v[10:13], v[166:169], v[222:225], v[10:13]
	v_mfma_f32_16x16x32_bf16 v[10:13], v[160:163], v[218:221], v[10:13]
	s_barrier
	s_add_i32 s52, s52, 2
	s_add_u32 s24, s24, 0x100
	s_addc_u32 s25, s25, 0
	s_add_u32 s50, s50, 0x100
	s_addc_u32 s51, s51, 0
	s_cmp_gt_u32 s52, 61
	s_cbranch_scc0 .LBB0_1681
	s_and_b64 vcc, exec, s[8:9]
	s_cbranch_vccz .LBB0_1684
	s_barrier

; #define PG8_STAGE(bufoff, gbase, voff) do { _Pragma("unroll") for (int _i = 0; _i < 2; ++_i) \
;         __builtin_amdgcn_global_load_lds((const unsigned*)((const char*)(gbase) + (voff)[_i]), (PG8_LAS unsigned*)(lds + (bufoff) + ldsw + _i * 8192), 16, 0, 0); } while (0)
; #define PG8_LDA(dst, b, h) do { _Pragma("unroll") for (int m = 0; m < 4; ++m) _Pragma("unroll") for (int k = 0; k < 2; ++k) dst[m][k] = *(const PG8_LAS bf16x8*)(lds + PG8_SA(b, h) + aoff + m * 2048 + k * 1024); } while (0)
; #define PG8_LDB(dst, b, h) do { _Pragma("unroll") for (int n = 0; n < 2; ++n) _Pragma("unroll") for (int k = 0; k < 2; ++k) dst[n][k] = *(const PG8_LAS bf16x8*)(lds + PG8_SB(b, h) + boff + n * 2048 + k * 1024); } while (0)
; #define PG8_MMA(ai, bj, At, Bt) do { __builtin_amdgcn_s_setprio(1); _Pragma("unroll") for (int m = 0; m < 4; ++m) _Pragma("unroll") for (int n = 0; n < 2; ++n) _Pragma("unroll") for (int k = 0; k < 2; ++k) \
;         acc[ai][bj][m][n] = __builtin_amdgcn_mfma_f32_16x16x32_bf16(Bt[n][k], At[m][k], acc[ai][bj][m][n], 0, 0, 0); __builtin_amdgcn_s_setprio(0); } while (0)
; #define PG8_WAIT_V(n) asm volatile("s_waitcnt vmcnt(" #n ")" ::: "memory")
; #define PG8_WAIT_L(n) asm volatile("s_waitcnt lgkmcnt(" #n ")" ::: "memory")
; template <class Epi, class Sched, bool ALIGN_EPI = false, bool SP2 = false>
; __device__ __forceinline__ void gemm_phase(PG8_LAS unsigned char* lds, const Gemm g, const Sched& S, const Epi& E) {
;     ...
;             const bool last = (t == nt - 2);
;             const char* a1 = cA + (size_t)(t + 1) * kstep;
;             const char* a2 = last ? nA : cA + (size_t)(t + 2) * kstep; const char* b2 = last ? nB : cB + (size_t)(t + 2) * kstep;
;             const char* a3 = a2 + kstep; const char* b3 = b2 + kstep;
;             if (last && has_next) S.a_ready(nxt);
;             if constexpr (SP2) {
;             PG8_LDB(B0, 0, 0); PG8_LDB(B1, 0, 1); PG8_SCHED; PG8_LDA(At, 0, 0); PG8_STAGE(PG8_SA(1, 1), a1 + hstep, voffA);
;             PG8_WAIT_V(8); PG8_WAIT_L(0); PG8_BAR; PG8_MMA(0, 0, At, B0); PG8_MMA(0, 1, At, B1); PG8_BAR; PG8_SCHED;
;             PG8_LDA(At, 0, 1); PG8_STAGE(PG8_SB(0, 0), b2, voffB); PG8_STAGE(PG8_SB(0, 1), b2 + hstep, voffB); PG8_STAGE(PG8_SA(0, 0), a2, voffA);
;             PG8_WAIT_V(8); PG8_WAIT_L(0); PG8_BAR; PG8_MMA(1, 0, At, B0); PG8_MMA(1, 1, At, B1); PG8_BAR; PG8_SCHED;
.LBB0_1801:
	ds_read_b128 v[130:133], v241 offset:0
	ds_read_b128 v[134:137], v241 offset:1024
	ds_read_b128 v[138:141], v241 offset:2048
	ds_read_b128 v[142:145], v241 offset:3072
	ds_read_b128 v[146:149], v241 offset:16384
	ds_read_b128 v[150:153], v241 offset:17408
	ds_read_b128 v[170:173], v241 offset:18432
	ds_read_b128 v[174:177], v241 offset:19456
	s_add_u32 s16, s18, 0xffd50080
	s_addc_u32 s17, s19, -1
	s_cmpk_eq_i32 s48, 0xa8
	s_cselect_b32 s21, s5, s17
	s_cselect_b32 s20, s4, s16
	s_cselect_b32 s17, s15, s47
	s_cselect_b32 s16, s14, s46
	s_add_i32 m0, s25, 0xc000
	ds_read_b128 v[178:181], v184
	ds_read_b128 v[186:189], v184 offset:1024
	ds_read_b128 v[190:193], v184 offset:2048
	ds_read_b128 v[194:197], v184 offset:3072
	ds_read_b128 v[198:201], v184 offset:4096
	ds_read_b128 v[202:205], v184 offset:5120
	ds_read_b128 v[206:209], v184 offset:6144
	ds_read_b128 v[210:213], v184 offset:7168
	global_load_lds_dwordx4 v0, s[18:19]
	s_add_i32 m0, s25, 0xe000
	s_nop 0
	global_load_lds_dwordx4 v162, s[18:19]
	s_waitcnt vmcnt(8)
	s_waitcnt lgkmcnt(0)
	s_barrier
	s_waitcnt lgkmcnt(0)
	v_mfma_f32_16x16x32_bf16 v[114:117], v[130:133], v[178:181], v[114:117]
	v_mfma_f32_16x16x32_bf16 v[114:117], v[134:137], v[186:189], v[114:117]
	v_mfma_f32_16x16x32_bf16 v[118:121], v[142:145], v[186:189], v[118:121]
	v_mfma_f32_16x16x32_bf16 v[118:121], v[138:141], v[178:181], v[118:121]
	v_mfma_f32_16x16x32_bf16 v[122:125], v[146:149], v[178:181], v[122:125]
	v_mfma_f32_16x16x32_bf16 v[122:125], v[150:153], v[186:189], v[122:125]
	v_mfma_f32_16x16x32_bf16 v[126:129], v[174:177], v[186:189], v[126:129]
	v_mfma_f32_16x16x32_bf16 v[126:129], v[170:173], v[178:181], v[126:129]
	v_mfma_f32_16x16x32_bf16 v[102:105], v[170:173], v[190:193], v[102:105]
	v_mfma_f32_16x16x32_bf16 v[102:105], v[174:177], v[194:197], v[102:105]
	v_mfma_f32_16x16x32_bf16 v[110:113], v[150:153], v[194:197], v[110:113]
	v_mfma_f32_16x16x32_bf16 v[110:113], v[146:149], v[190:193], v[110:113]
	v_mfma_f32_16x16x32_bf16 v[98:101], v[138:141], v[190:193], v[98:101]
	v_mfma_f32_16x16x32_bf16 v[98:101], v[142:145], v[194:197], v[98:101]
	v_mfma_f32_16x16x32_bf16 v[106:109], v[134:137], v[194:197], v[106:109]
	v_mfma_f32_16x16x32_bf16 v[106:109], v[130:133], v[190:193], v[106:109]
	v_mfma_f32_16x16x32_bf16 v[90:93], v[130:133], v[198:201], v[90:93]
	v_mfma_f32_16x16x32_bf16 v[90:93], v[134:137], v[202:205], v[90:93]
	v_mfma_f32_16x16x32_bf16 v[82:85], v[142:145], v[202:205], v[82:85]
	v_mfma_f32_16x16x32_bf16 v[82:85], v[138:141], v[198:201], v[82:85]
	v_mfma_f32_16x16x32_bf16 v[94:97], v[146:149], v[198:201], v[94:97]
	v_mfma_f32_16x16x32_bf16 v[94:97], v[150:153], v[202:205], v[94:97]
	v_mfma_f32_16x16x32_bf16 v[86:89], v[174:177], v[202:205], v[86:89]
	v_mfma_f32_16x16x32_bf16 v[86:89], v[170:173], v[198:201], v[86:89]
	v_mfma_f32_16x16x32_bf16 v[70:73], v[170:173], v[206:209], v[70:73]
	v_mfma_f32_16x16x32_bf16 v[70:73], v[174:177], v[210:213], v[70:73]
	v_mfma_f32_16x16x32_bf16 v[78:81], v[150:153], v[210:213], v[78:81]
	v_mfma_f32_16x16x32_bf16 v[78:81], v[146:149], v[206:209], v[78:81]
	v_mfma_f32_16x16x32_bf16 v[66:69], v[138:141], v[206:209], v[66:69]
	v_mfma_f32_16x16x32_bf16 v[66:69], v[142:145], v[210:213], v[66:69]
	v_mfma_f32_16x16x32_bf16 v[74:77], v[134:137], v[210:213], v[74:77]
	v_mfma_f32_16x16x32_bf16 v[74:77], v[130:133], v[206:209], v[74:77]
	s_barrier
	s_add_i32 s33, s36, s24
	s_mov_b32 m0, s33
	ds_read_b128 v[178:181], v184 offset:16384
	ds_read_b128 v[186:189], v184 offset:17408
	ds_read_b128 v[190:193], v184 offset:18432
	ds_read_b128 v[194:197], v184 offset:19456
	ds_read_b128 v[198:201], v184 offset:20480
	ds_read_b128 v[202:205], v184 offset:21504
	ds_read_b128 v[206:209], v184 offset:22528
	ds_read_b128 v[210:213], v184 offset:23552
	global_load_lds_dwordx4 v156, s[16:17]
	s_add_i32 m0, s33, 0x2000
	s_add_u32 s50, s16, 0x2b0000
	s_addc_u32 s51, s17, 0
	s_add_i32 s33, s37, s24
	global_load_lds_dwordx4 v160, s[16:17]
	s_mov_b32 m0, s33
	s_add_u32 s100, s20, 0x80
	s_addc_u32 s101, s21, 0
	global_load_lds_dwordx4 v156, s[50:51]
	s_add_i32 m0, s33, 0x2000
	s_nop 0
	global_load_lds_dwordx4 v160, s[50:51]
	s_mov_b32 m0, s25
	s_nop 0
	global_load_lds_dwordx4 v154, s[20:21]
	s_mov_b32 m0, s26
	s_nop 0
	global_load_lds_dwordx4 v158, s[20:21]
	s_waitcnt vmcnt(8)
	s_waitcnt lgkmcnt(0)
	s_barrier
	s_waitcnt lgkmcnt(0)
	v_mfma_f32_16x16x32_bf16 v[58:61], v[130:133], v[178:181], v[58:61]
	v_mfma_f32_16x16x32_bf16 v[58:61], v[134:137], v[186:189], v[58:61]
	v_mfma_f32_16x16x32_bf16 v[54:57], v[142:145], v[186:189], v[54:57]
	v_mfma_f32_16x16x32_bf16 v[54:57], v[138:141], v[178:181], v[54:57]
	v_mfma_f32_16x16x32_bf16 v[62:65], v[146:149], v[178:181], v[62:65]
	v_mfma_f32_16x16x32_bf16 v[62:65], v[150:153], v[186:189], v[62:65]
	v_mfma_f32_16x16x32_bf16 v[50:53], v[174:177], v[186:189], v[50:53]
	v_mfma_f32_16x16x32_bf16 v[50:53], v[170:173], v[178:181], v[50:53]
	v_mfma_f32_16x16x32_bf16 v[38:41], v[170:173], v[190:193], v[38:41]
	v_mfma_f32_16x16x32_bf16 v[38:41], v[174:177], v[194:197], v[38:41]
	v_mfma_f32_16x16x32_bf16 v[46:49], v[150:153], v[194:197], v[46:49]
	v_mfma_f32_16x16x32_bf16 v[46:49], v[146:149], v[190:193], v[46:49]
	v_mfma_f32_16x16x32_bf16 v[34:37], v[138:141], v[190:193], v[34:37]
	v_mfma_f32_16x16x32_bf16 v[34:37], v[142:145], v[194:197], v[34:37]
	v_mfma_f32_16x16x32_bf16 v[42:45], v[134:137], v[194:197], v[42:45]
	v_mfma_f32_16x16x32_bf16 v[42:45], v[130:133], v[190:193], v[42:45]
	v_mfma_f32_16x16x32_bf16 v[26:29], v[130:133], v[198:201], v[26:29]
	v_mfma_f32_16x16x32_bf16 v[26:29], v[134:137], v[202:205], v[26:29]
	v_mfma_f32_16x16x32_bf16 v[18:21], v[142:145], v[202:205], v[18:21]
	v_mfma_f32_16x16x32_bf16 v[18:21], v[138:141], v[198:201], v[18:21]
	v_mfma_f32_16x16x32_bf16 v[30:33], v[146:149], v[198:201], v[30:33]
	v_mfma_f32_16x16x32_bf16 v[30:33], v[150:153], v[202:205], v[30:33]
	v_mfma_f32_16x16x32_bf16 v[22:25], v[174:177], v[202:205], v[22:25]
	v_mfma_f32_16x16x32_bf16 v[22:25], v[170:173], v[198:201], v[22:25]
	v_mfma_f32_16x16x32_bf16 v[14:17], v[170:173], v[206:209], v[14:17]
	v_mfma_f32_16x16x32_bf16 v[14:17], v[174:177], v[210:213], v[14:17]
	v_mfma_f32_16x16x32_bf16 v[10:13], v[150:153], v[210:213], v[10:13]
	v_mfma_f32_16x16x32_bf16 v[10:13], v[146:149], v[206:209], v[10:13]
	v_mfma_f32_16x16x32_bf16 v[2:5], v[138:141], v[206:209], v[2:5]
	v_mfma_f32_16x16x32_bf16 v[2:5], v[142:145], v[210:213], v[2:5]
	v_mfma_f32_16x16x32_bf16 v[6:9], v[134:137], v[210:213], v[6:9]
	v_mfma_f32_16x16x32_bf16 v[6:9], v[130:133], v[206:209], v[6:9]
	s_barrier
; #define PG8_STAGE(bufoff, gbase, voff) do { _Pragma("unroll") for (int _i = 0; _i < 2; ++_i) \
;         __builtin_amdgcn_global_load_lds((const unsigned*)((const char*)(gbase) + (voff)[_i]), (PG8_LAS unsigned*)(lds + (bufoff) + ldsw + _i * 8192), 16, 0, 0); } while (0)
; #define PG8_LDA(dst, b, h) do { _Pragma("unroll") for (int m = 0; m < 4; ++m) _Pragma("unroll") for (int k = 0; k < 2; ++k) dst[m][k] = *(const PG8_LAS bf16x8*)(lds + PG8_SA(b, h) + aoff + m * 2048 + k * 1024); } while (0)
; #define PG8_LDB(dst, b, h) do { _Pragma("unroll") for (int n = 0; n < 2; ++n) _Pragma("unroll") for (int k = 0; k < 2; ++k) dst[n][k] = *(const PG8_LAS bf16x8*)(lds + PG8_SB(b, h) + boff + n * 2048 + k * 1024); } while (0)
; #define PG8_MMA(ai, bj, At, Bt) do { __builtin_amdgcn_s_setprio(1); _Pragma("unroll") for (int m = 0; m < 4; ++m) _Pragma("unroll") for (int n = 0; n < 2; ++n) _Pragma("unroll") for (int k = 0; k < 2; ++k) \
;         acc[ai][bj][m][n] = __builtin_amdgcn_mfma_f32_16x16x32_bf16(Bt[n][k], At[m][k], acc[ai][bj][m][n], 0, 0, 0); __builtin_amdgcn_s_setprio(0); } while (0)
; #define PG8_WAIT_V(n) asm volatile("s_waitcnt vmcnt(" #n ")" ::: "memory")
; #define PG8_WAIT_L(n) asm volatile("s_waitcnt lgkmcnt(" #n ")" ::: "memory")
; #define PG8_BAR __builtin_amdgcn_s_barrier()
; template <class Epi, class Sched, bool ALIGN_EPI = false, bool SP2 = false>
; __device__ __forceinline__ void gemm_phase(PG8_LAS unsigned char* lds, const Gemm g, const Sched& S, const Epi& E) {
;     ...
;         for (int t = 0; t < nt; t += 2) {
;             const bool last = (t == nt - 2);
;             const char* a1 = cA + (size_t)(t + 1) * kstep;
;             const char* a2 = last ? nA : cA + (size_t)(t + 2) * kstep; const char* b2 = last ? nB : cB + (size_t)(t + 2) * kstep;
;             const char* a3 = a2 + kstep; const char* b3 = b2 + kstep;
;     ...
;             PG8_LDB(B0, 1, 0); PG8_LDB(B1, 1, 1); PG8_SCHED; PG8_LDA(At, 1, 0); PG8_STAGE(PG8_SA(0, 1), a2 + hstep, voffA);
;             PG8_WAIT_V(8); PG8_WAIT_L(0); PG8_BAR; PG8_MMA(0, 0, At, B0); PG8_MMA(0, 1, At, B1); PG8_BAR; PG8_SCHED;
;             PG8_LDA(At, 1, 1); PG8_STAGE(PG8_SB(1, 0), b3, voffB); PG8_STAGE(PG8_SB(1, 1), b3 + hstep, voffB); PG8_STAGE(PG8_SA(1, 0), a3, voffA);
;             PG8_WAIT_V(8); PG8_WAIT_L(0); PG8_BAR; PG8_MMA(1, 0, At, B0); PG8_MMA(1, 1, At, B1); PG8_BAR; PG8_SCHED;
	s_add_i32 s33, 0, 0x18000
	s_add_i32 s42, 0, 0x1c000
	ds_read_b128 v[130:133], v241 offset:32768
	ds_read_b128 v[134:137], v241 offset:33792
	ds_read_b128 v[138:141], v241 offset:34816
	ds_read_b128 v[142:145], v241 offset:35840
	ds_read_b128 v[146:149], v241 offset:49152
	ds_read_b128 v[150:153], v241 offset:50176
	ds_read_b128 v[170:173], v241 offset:51200
	ds_read_b128 v[174:177], v241 offset:52224
	s_add_u32 s20, s20, 0x2b0000
	s_addc_u32 s21, s21, 0
	s_mov_b32 m0, s27
	ds_read_b128 v[178:181], v184 offset:32768
	ds_read_b128 v[186:189], v184 offset:33792
	ds_read_b128 v[190:193], v184 offset:34816
	ds_read_b128 v[194:197], v184 offset:35840
	ds_read_b128 v[198:201], v184 offset:36864
	ds_read_b128 v[202:205], v184 offset:37888
	ds_read_b128 v[206:209], v184 offset:38912
	ds_read_b128 v[210:213], v184 offset:39936
	global_load_lds_dwordx4 v154, s[20:21]
	s_mov_b32 m0, s28
	s_nop 0
	global_load_lds_dwordx4 v158, s[20:21]
	s_waitcnt vmcnt(8)
	s_waitcnt lgkmcnt(0)
	s_barrier
	s_waitcnt lgkmcnt(0)
	v_mfma_f32_16x16x32_bf16 v[114:117], v[130:133], v[178:181], v[114:117]
	v_mfma_f32_16x16x32_bf16 v[114:117], v[134:137], v[186:189], v[114:117]
	v_mfma_f32_16x16x32_bf16 v[118:121], v[142:145], v[186:189], v[118:121]
	v_mfma_f32_16x16x32_bf16 v[118:121], v[138:141], v[178:181], v[118:121]
	v_mfma_f32_16x16x32_bf16 v[122:125], v[146:149], v[178:181], v[122:125]
	v_mfma_f32_16x16x32_bf16 v[122:125], v[150:153], v[186:189], v[122:125]
	v_mfma_f32_16x16x32_bf16 v[126:129], v[174:177], v[186:189], v[126:129]
	v_mfma_f32_16x16x32_bf16 v[126:129], v[170:173], v[178:181], v[126:129]
	v_mfma_f32_16x16x32_bf16 v[102:105], v[170:173], v[190:193], v[102:105]
	v_mfma_f32_16x16x32_bf16 v[102:105], v[174:177], v[194:197], v[102:105]
	v_mfma_f32_16x16x32_bf16 v[110:113], v[150:153], v[194:197], v[110:113]
	v_mfma_f32_16x16x32_bf16 v[110:113], v[146:149], v[190:193], v[110:113]
	v_mfma_f32_16x16x32_bf16 v[98:101], v[138:141], v[190:193], v[98:101]
	v_mfma_f32_16x16x32_bf16 v[98:101], v[142:145], v[194:197], v[98:101]
	v_mfma_f32_16x16x32_bf16 v[106:109], v[134:137], v[194:197], v[106:109]
	v_mfma_f32_16x16x32_bf16 v[106:109], v[130:133], v[190:193], v[106:109]
	v_mfma_f32_16x16x32_bf16 v[90:93], v[130:133], v[198:201], v[90:93]
	v_mfma_f32_16x16x32_bf16 v[90:93], v[134:137], v[202:205], v[90:93]
	v_mfma_f32_16x16x32_bf16 v[82:85], v[142:145], v[202:205], v[82:85]
	v_mfma_f32_16x16x32_bf16 v[82:85], v[138:141], v[198:201], v[82:85]
	v_mfma_f32_16x16x32_bf16 v[94:97], v[146:149], v[198:201], v[94:97]
	v_mfma_f32_16x16x32_bf16 v[94:97], v[150:153], v[202:205], v[94:97]
	v_mfma_f32_16x16x32_bf16 v[86:89], v[174:177], v[202:205], v[86:89]
	v_mfma_f32_16x16x32_bf16 v[86:89], v[170:173], v[198:201], v[86:89]
	v_mfma_f32_16x16x32_bf16 v[70:73], v[170:173], v[206:209], v[70:73]
	v_mfma_f32_16x16x32_bf16 v[70:73], v[174:177], v[210:213], v[70:73]
	v_mfma_f32_16x16x32_bf16 v[78:81], v[150:153], v[210:213], v[78:81]
	v_mfma_f32_16x16x32_bf16 v[78:81], v[146:149], v[206:209], v[78:81]
	v_mfma_f32_16x16x32_bf16 v[66:69], v[138:141], v[206:209], v[66:69]
	v_mfma_f32_16x16x32_bf16 v[66:69], v[142:145], v[210:213], v[66:69]
	v_mfma_f32_16x16x32_bf16 v[74:77], v[134:137], v[210:213], v[74:77]
	v_mfma_f32_16x16x32_bf16 v[74:77], v[130:133], v[206:209], v[74:77]
	s_barrier
	s_add_i32 s20, s33, s24
	s_add_i32 m0, s20, 0xffffff80
	ds_read_b128 v[178:181], v184 offset:49152
	ds_read_b128 v[186:189], v184 offset:50176
	ds_read_b128 v[190:193], v184 offset:51200
	ds_read_b128 v[194:197], v184 offset:52224
	ds_read_b128 v[198:201], v184 offset:53248
	ds_read_b128 v[202:205], v184 offset:54272
	ds_read_b128 v[206:209], v184 offset:55296
	ds_read_b128 v[210:213], v184 offset:56320
	global_load_lds_dwordx4 v156, s[16:17] offset:128
	s_add_i32 m0, s20, 0x1f80
	s_add_i32 s20, s42, s24
	global_load_lds_dwordx4 v160, s[16:17] offset:128
	s_add_u32 s16, s16, 0x2b0080
	s_addc_u32 s17, s17, 0
	s_mov_b32 m0, s20
	s_nop 0
	global_load_lds_dwordx4 v156, s[16:17]
	s_add_i32 m0, s20, 0x2000
	s_nop 0
	global_load_lds_dwordx4 v160, s[16:17]
	s_mov_b32 m0, s30
	s_nop 0
	global_load_lds_dwordx4 v154, s[100:101]
	s_mov_b32 m0, s31
	s_nop 0
	global_load_lds_dwordx4 v158, s[100:101]
	s_waitcnt vmcnt(8)
	s_waitcnt lgkmcnt(0)
	s_barrier
	s_waitcnt lgkmcnt(0)
	v_mfma_f32_16x16x32_bf16 v[58:61], v[130:133], v[178:181], v[58:61]
	v_mfma_f32_16x16x32_bf16 v[58:61], v[134:137], v[186:189], v[58:61]
	v_mfma_f32_16x16x32_bf16 v[54:57], v[142:145], v[186:189], v[54:57]
	v_mfma_f32_16x16x32_bf16 v[54:57], v[138:141], v[178:181], v[54:57]
	v_mfma_f32_16x16x32_bf16 v[62:65], v[146:149], v[178:181], v[62:65]
	v_mfma_f32_16x16x32_bf16 v[62:65], v[150:153], v[186:189], v[62:65]
	v_mfma_f32_16x16x32_bf16 v[50:53], v[174:177], v[186:189], v[50:53]
	v_mfma_f32_16x16x32_bf16 v[50:53], v[170:173], v[178:181], v[50:53]
	v_mfma_f32_16x16x32_bf16 v[38:41], v[170:173], v[190:193], v[38:41]
	v_mfma_f32_16x16x32_bf16 v[38:41], v[174:177], v[194:197], v[38:41]
	v_mfma_f32_16x16x32_bf16 v[46:49], v[150:153], v[194:197], v[46:49]
	v_mfma_f32_16x16x32_bf16 v[46:49], v[146:149], v[190:193], v[46:49]
	v_mfma_f32_16x16x32_bf16 v[34:37], v[138:141], v[190:193], v[34:37]
	v_mfma_f32_16x16x32_bf16 v[34:37], v[142:145], v[194:197], v[34:37]
	v_mfma_f32_16x16x32_bf16 v[42:45], v[134:137], v[194:197], v[42:45]
	v_mfma_f32_16x16x32_bf16 v[42:45], v[130:133], v[190:193], v[42:45]
	v_mfma_f32_16x16x32_bf16 v[26:29], v[130:133], v[198:201], v[26:29]
	v_mfma_f32_16x16x32_bf16 v[26:29], v[134:137], v[202:205], v[26:29]
	v_mfma_f32_16x16x32_bf16 v[18:21], v[142:145], v[202:205], v[18:21]
	v_mfma_f32_16x16x32_bf16 v[18:21], v[138:141], v[198:201], v[18:21]
	v_mfma_f32_16x16x32_bf16 v[30:33], v[146:149], v[198:201], v[30:33]
	v_mfma_f32_16x16x32_bf16 v[30:33], v[150:153], v[202:205], v[30:33]
	v_mfma_f32_16x16x32_bf16 v[22:25], v[174:177], v[202:205], v[22:25]
	v_mfma_f32_16x16x32_bf16 v[22:25], v[170:173], v[198:201], v[22:25]
	v_mfma_f32_16x16x32_bf16 v[14:17], v[170:173], v[206:209], v[14:17]
	v_mfma_f32_16x16x32_bf16 v[14:17], v[174:177], v[210:213], v[14:17]
	v_mfma_f32_16x16x32_bf16 v[10:13], v[150:153], v[210:213], v[10:13]
	v_mfma_f32_16x16x32_bf16 v[10:13], v[146:149], v[206:209], v[10:13]
	v_mfma_f32_16x16x32_bf16 v[2:5], v[138:141], v[206:209], v[2:5]
	v_mfma_f32_16x16x32_bf16 v[2:5], v[142:145], v[210:213], v[2:5]
	v_mfma_f32_16x16x32_bf16 v[6:9], v[134:137], v[210:213], v[6:9]
	v_mfma_f32_16x16x32_bf16 v[6:9], v[130:133], v[206:209], v[6:9]
	s_barrier
	s_add_i32 s48, s48, 2
	s_add_u32 s18, s18, 0x100
	s_addc_u32 s19, s19, 0
	s_add_u32 s46, s46, 0x100
	s_addc_u32 s47, s47, 0
	s_cmpk_gt_u32 s48, 0xa9
	s_cbranch_scc0 .LBB0_1801
	s_and_b64 vcc, exec, s[12:13]
	s_cbranch_vccz .LBB0_1804
	s_barrier
